# HGRN prompt chain step: all 27 LDS reads issued up front with counted lgkmcnt waits, DMA issue moved under LDS latency; plus early barrier in GEMM K-loops
# speedup vs baseline: 1.0017x; 1.0017x over previous
;     __host__ __device__ bool next(int i, Unit& u) const { return (i + I0 < I1) && StaticOrder::next(i + I0, u); }
; #define PG8_STAGE(bufoff, gbase, voff) do { _Pragma("unroll") for (int _i = 0; _i < 2; ++_i) \
;         __builtin_amdgcn_global_load_lds((const unsigned*)((const char*)(gbase) + (voff)[_i]), (PG8_LAS unsigned*)(lds + (bufoff) + ldsw + _i * 8192), 16, 0, 0); } while (0)
; #define PG8_LDA(dst, b, h) do { _Pragma("unroll") for (int m = 0; m < 4; ++m) _Pragma("unroll") for (int k = 0; k < 2; ++k) dst[m][k] = *(const PG8_LAS bf16x8*)(lds + PG8_SA(b, h) + aoff + m * 2048 + k * 1024); } while (0)
; #define PG8_LDB(dst, b, h) do { _Pragma("unroll") for (int n = 0; n < 2; ++n) _Pragma("unroll") for (int k = 0; k < 2; ++k) dst[n][k] = *(const PG8_LAS bf16x8*)(lds + PG8_SB(b, h) + boff + n * 2048 + k * 1024); } while (0)
; #define PG8_WAIT_V(n) asm volatile("s_waitcnt vmcnt(" #n ")" ::: "memory")
; #define PG8_WAIT_L(n) asm volatile("s_waitcnt lgkmcnt(" #n ")" ::: "memory")
; #define PG8_BAR __builtin_amdgcn_s_barrier()
; #define PG8_SCHED __builtin_amdgcn_sched_barrier(0)
; template <class Epi, class Sched, bool ALIGN_EPI = false, bool SP2 = false>
; __device__ __forceinline__ void gemm_phase(PG8_LAS unsigned char* lds, const Gemm g, const Sched& S, const Epi& E) {
;     ...
;         const bool has_next = S.next(ui + 1, nxt);
;         const char* nA = has_next ? (const char*)g.A + (size_t)nxt.pm * tstep : cA; const char* nB = has_next ? (const char*)g.Bt + (size_t)nxt.pn * tstep : cB;
;         for (int t = 0; t < nt; t += 2) {
;             const bool last = (t == nt - 2);
;             const char* a1 = cA + (size_t)(t + 1) * kstep;
;             const char* a2 = last ? nA : cA + (size_t)(t + 2) * kstep; const char* b2 = last ? nB : cB + (size_t)(t + 2) * kstep;
;             const char* a3 = a2 + kstep; const char* b3 = b2 + kstep;
;             if (last && has_next) S.a_ready(nxt);
;             if constexpr (SP2) {
;             PG8_LDB(B0, 0, 0); PG8_LDB(B1, 0, 1); PG8_SCHED; PG8_LDA(At, 0, 0); PG8_STAGE(PG8_SA(1, 1), a1 + hstep, voffA);
;             PG8_WAIT_V(8); PG8_WAIT_L(0); PG8_BAR; PG8_MMA(0, 0, At, B0); PG8_MMA(0, 1, At, B1); PG8_BAR; PG8_SCHED;
;             PG8_LDA(At, 0, 1); PG8_STAGE(PG8_SB(0, 0), b2, voffB); PG8_STAGE(PG8_SB(0, 1), b2 + hstep, voffB); PG8_STAGE(PG8_SA(0, 0), a2, voffA);
.LBB0_48:
	ds_read_b128 v[146:149], v153
	ds_read_b128 v[156:159], v153 offset:1024
	ds_read_b128 v[160:163], v153 offset:2048
	ds_read_b128 v[164:167], v153 offset:3072
	ds_read_b128 v[168:171], v154
	ds_read_b128 v[172:175], v154 offset:1024
	ds_read_b128 v[176:179], v154 offset:2048
	ds_read_b128 v[180:183], v154 offset:3072
	s_add_u32 s22, s20, 0xfff80080
	s_addc_u32 s23, s21, -1
	s_cmp_eq_u32 s53, 28
	s_cselect_b32 s25, s13, s23
	s_cselect_b32 s24, s45, s22
	s_cselect_b32 s23, s11, s52
	s_cselect_b32 s22, s50, s51
	v_lshl_add_u64 v[216:217], s[20:21], 0, v[138:139]
	s_add_i32 m0, s19, 0xc000
	ds_read_b128 v[184:187], v155
	ds_read_b128 v[188:191], v155 offset:1024
	ds_read_b128 v[192:195], v155 offset:2048
	ds_read_b128 v[196:199], v155 offset:3072
	ds_read_b128 v[200:203], v155 offset:4096
	ds_read_b128 v[204:207], v155 offset:5120
	ds_read_b128 v[208:211], v155 offset:6144
	ds_read_b128 v[212:215], v155 offset:7168
	global_load_lds_dwordx4 v[216:217], off
	v_lshl_add_u64 v[216:217], s[20:21], 0, v[140:141]
	s_add_i32 m0, s19, 0xe000
	s_nop 0
	global_load_lds_dwordx4 v[216:217], off
	s_waitcnt vmcnt(8)
	s_waitcnt lgkmcnt(0)
	s_barrier
	s_setprio 1
	s_waitcnt lgkmcnt(0)
	v_mfma_f32_16x16x32_bf16 v[124:127], v[146:149], v[184:187], v[124:127]
	v_mfma_f32_16x16x32_bf16 v[116:119], v[160:163], v[184:187], v[116:119]
	v_mfma_f32_16x16x32_bf16 v[108:111], v[146:149], v[192:195], v[108:111]
	v_mfma_f32_16x16x32_bf16 v[100:103], v[160:163], v[192:195], v[100:103]
	v_mfma_f32_16x16x32_bf16 v[92:95], v[146:149], v[200:203], v[92:95]
	v_mfma_f32_16x16x32_bf16 v[84:87], v[160:163], v[200:203], v[84:87]
	v_mfma_f32_16x16x32_bf16 v[76:79], v[146:149], v[208:211], v[76:79]
	v_mfma_f32_16x16x32_bf16 v[68:71], v[160:163], v[208:211], v[68:71]
	v_mfma_f32_16x16x32_bf16 v[124:127], v[156:159], v[188:191], v[124:127]
	v_mfma_f32_16x16x32_bf16 v[116:119], v[164:167], v[188:191], v[116:119]
	v_mfma_f32_16x16x32_bf16 v[108:111], v[156:159], v[196:199], v[108:111]
	v_mfma_f32_16x16x32_bf16 v[100:103], v[164:167], v[196:199], v[100:103]
	v_mfma_f32_16x16x32_bf16 v[92:95], v[156:159], v[204:207], v[92:95]
	v_mfma_f32_16x16x32_bf16 v[84:87], v[164:167], v[204:207], v[84:87]
	v_mfma_f32_16x16x32_bf16 v[76:79], v[156:159], v[212:215], v[76:79]
	v_mfma_f32_16x16x32_bf16 v[68:71], v[164:167], v[212:215], v[68:71]
	s_setprio 0
	s_setprio 1
	v_mfma_f32_16x16x32_bf16 v[120:123], v[168:171], v[184:187], v[120:123]
	v_mfma_f32_16x16x32_bf16 v[112:115], v[176:179], v[184:187], v[112:115]
	v_mfma_f32_16x16x32_bf16 v[104:107], v[168:171], v[192:195], v[104:107]
	v_mfma_f32_16x16x32_bf16 v[96:99], v[176:179], v[192:195], v[96:99]
	v_mfma_f32_16x16x32_bf16 v[88:91], v[168:171], v[200:203], v[88:91]
	v_mfma_f32_16x16x32_bf16 v[80:83], v[176:179], v[200:203], v[80:83]
	v_mfma_f32_16x16x32_bf16 v[72:75], v[168:171], v[208:211], v[72:75]
	v_mfma_f32_16x16x32_bf16 v[64:67], v[176:179], v[208:211], v[64:67]
	v_mfma_f32_16x16x32_bf16 v[120:123], v[172:175], v[188:191], v[120:123]
	v_mfma_f32_16x16x32_bf16 v[112:115], v[180:183], v[188:191], v[112:115]
	v_mfma_f32_16x16x32_bf16 v[104:107], v[172:175], v[196:199], v[104:107]
	v_mfma_f32_16x16x32_bf16 v[96:99], v[180:183], v[196:199], v[96:99]
	s_setprio 2
	s_barrier
	v_mfma_f32_16x16x32_bf16 v[88:91], v[172:175], v[204:207], v[88:91]
	v_mfma_f32_16x16x32_bf16 v[80:83], v[180:183], v[204:207], v[80:83]
	v_mfma_f32_16x16x32_bf16 v[72:75], v[172:175], v[212:215], v[72:75]
	v_mfma_f32_16x16x32_bf16 v[64:67], v[180:183], v[212:215], v[64:67]
	s_setprio 0
	s_add_i32 s54, s41, s28
	v_lshl_add_u64 v[216:217], s[22:23], 0, v[134:135]
	s_mov_b32 m0, s54
	ds_read_b128 v[184:187], v155 offset:16384
	ds_read_b128 v[188:191], v155 offset:17408
	ds_read_b128 v[192:195], v155 offset:18432
	ds_read_b128 v[196:199], v155 offset:19456
	ds_read_b128 v[200:203], v155 offset:20480
	ds_read_b128 v[204:207], v155 offset:21504
	ds_read_b128 v[208:211], v155 offset:22528
	ds_read_b128 v[212:215], v155 offset:23552
	global_load_lds_dwordx4 v[216:217], off
	s_add_i32 m0, s54, 0x2000
	s_add_u32 s54, s22, 0x80000
	v_lshl_add_u64 v[218:219], s[22:23], 0, v[130:131]
	s_addc_u32 s55, s23, 0
	s_add_i32 s56, s42, s28
	global_load_lds_dwordx4 v[218:219], off
	v_lshl_add_u64 v[220:221], s[54:55], 0, v[134:135]
	s_mov_b32 m0, s56
	v_lshl_add_u64 v[222:223], s[24:25], 0, v[132:133]
	global_load_lds_dwordx4 v[220:221], off
	v_lshl_add_u64 v[220:221], s[54:55], 0, v[130:131]
	s_add_i32 m0, s56, 0x2000
	s_nop 0
	global_load_lds_dwordx4 v[220:221], off
	v_lshl_add_u64 v[220:221], s[24:25], 0, v[136:137]
	s_mov_b32 m0, s19
	s_nop 0
	global_load_lds_dwordx4 v[220:221], off
	s_mov_b32 m0, s31
	s_nop 0
	global_load_lds_dwordx4 v[222:223], off
	s_waitcnt vmcnt(8)
	s_waitcnt lgkmcnt(0)
	s_barrier
; #define PG8_STAGE(bufoff, gbase, voff) do { _Pragma("unroll") for (int _i = 0; _i < 2; ++_i) \
;         __builtin_amdgcn_global_load_lds((const unsigned*)((const char*)(gbase) + (voff)[_i]), (PG8_LAS unsigned*)(lds + (bufoff) + ldsw + _i * 8192), 16, 0, 0); } while (0)
; #define PG8_LDA(dst, b, h) do { _Pragma("unroll") for (int m = 0; m < 4; ++m) _Pragma("unroll") for (int k = 0; k < 2; ++k) dst[m][k] = *(const PG8_LAS bf16x8*)(lds + PG8_SA(b, h) + aoff + m * 2048 + k * 1024); } while (0)
; #define PG8_LDB(dst, b, h) do { _Pragma("unroll") for (int n = 0; n < 2; ++n) _Pragma("unroll") for (int k = 0; k < 2; ++k) dst[n][k] = *(const PG8_LAS bf16x8*)(lds + PG8_SB(b, h) + boff + n * 2048 + k * 1024); } while (0)
; #define PG8_MMA(ai, bj, At, Bt) do { __builtin_amdgcn_s_setprio(1); _Pragma("unroll") for (int m = 0; m < 4; ++m) _Pragma("unroll") for (int n = 0; n < 2; ++n) _Pragma("unroll") for (int k = 0; k < 2; ++k) \
;         acc[ai][bj][m][n] = __builtin_amdgcn_mfma_f32_16x16x32_bf16(Bt[n][k], At[m][k], acc[ai][bj][m][n], 0, 0, 0); __builtin_amdgcn_s_setprio(0); } while (0)
; #define PG8_WAIT_V(n) asm volatile("s_waitcnt vmcnt(" #n ")" ::: "memory")
; #define PG8_WAIT_L(n) asm volatile("s_waitcnt lgkmcnt(" #n ")" ::: "memory")
; #define PG8_BAR __builtin_amdgcn_s_barrier()
; #define PG8_SCHED __builtin_amdgcn_sched_barrier(0)
; template <class Epi, class Sched, bool ALIGN_EPI = false, bool SP2 = false>
; __device__ __forceinline__ void gemm_phase(PG8_LAS unsigned char* lds, const Gemm g, const Sched& S, const Epi& E) {
;     ...
;             PG8_WAIT_V(8); PG8_WAIT_L(0); PG8_BAR; PG8_MMA(1, 0, At, B0); PG8_MMA(1, 1, At, B1); PG8_BAR; PG8_SCHED;
;             PG8_LDB(B0, 1, 0); PG8_LDB(B1, 1, 1); PG8_SCHED; PG8_LDA(At, 1, 0); PG8_STAGE(PG8_SA(0, 1), a2 + hstep, voffA);
;             PG8_WAIT_V(8); PG8_WAIT_L(0); PG8_BAR; PG8_MMA(0, 0, At, B0); PG8_MMA(0, 1, At, B1); PG8_BAR; PG8_SCHED;
	s_setprio 1
	s_waitcnt lgkmcnt(0)
	v_mfma_f32_16x16x32_bf16 v[60:63], v[146:149], v[184:187], v[60:63]
	v_mfma_f32_16x16x32_bf16 v[52:55], v[160:163], v[184:187], v[52:55]
	v_mfma_f32_16x16x32_bf16 v[44:47], v[146:149], v[192:195], v[44:47]
	v_mfma_f32_16x16x32_bf16 v[36:39], v[160:163], v[192:195], v[36:39]
	v_mfma_f32_16x16x32_bf16 v[28:31], v[146:149], v[200:203], v[28:31]
	v_mfma_f32_16x16x32_bf16 v[20:23], v[160:163], v[200:203], v[20:23]
	v_mfma_f32_16x16x32_bf16 v[12:15], v[146:149], v[208:211], v[12:15]
	v_mfma_f32_16x16x32_bf16 v[4:7], v[160:163], v[208:211], v[4:7]
	v_mfma_f32_16x16x32_bf16 v[60:63], v[156:159], v[188:191], v[60:63]
	v_mfma_f32_16x16x32_bf16 v[52:55], v[164:167], v[188:191], v[52:55]
	v_mfma_f32_16x16x32_bf16 v[44:47], v[156:159], v[196:199], v[44:47]
	v_mfma_f32_16x16x32_bf16 v[36:39], v[164:167], v[196:199], v[36:39]
	v_mfma_f32_16x16x32_bf16 v[28:31], v[156:159], v[204:207], v[28:31]
	v_mfma_f32_16x16x32_bf16 v[20:23], v[164:167], v[204:207], v[20:23]
	v_mfma_f32_16x16x32_bf16 v[12:15], v[156:159], v[212:215], v[12:15]
	v_mfma_f32_16x16x32_bf16 v[4:7], v[164:167], v[212:215], v[4:7]
	s_setprio 0
	s_setprio 1
	v_mfma_f32_16x16x32_bf16 v[56:59], v[168:171], v[184:187], v[56:59]
	v_mfma_f32_16x16x32_bf16 v[48:51], v[176:179], v[184:187], v[48:51]
	v_mfma_f32_16x16x32_bf16 v[40:43], v[168:171], v[192:195], v[40:43]
	v_mfma_f32_16x16x32_bf16 v[32:35], v[176:179], v[192:195], v[32:35]
	v_mfma_f32_16x16x32_bf16 v[24:27], v[168:171], v[200:203], v[24:27]
	v_mfma_f32_16x16x32_bf16 v[16:19], v[176:179], v[200:203], v[16:19]
	v_mfma_f32_16x16x32_bf16 v[8:11], v[168:171], v[208:211], v[8:11]
	v_mfma_f32_16x16x32_bf16 v[0:3], v[176:179], v[208:211], v[0:3]
	v_mfma_f32_16x16x32_bf16 v[56:59], v[172:175], v[188:191], v[56:59]
	v_mfma_f32_16x16x32_bf16 v[48:51], v[180:183], v[188:191], v[48:51]
	v_mfma_f32_16x16x32_bf16 v[40:43], v[172:175], v[196:199], v[40:43]
	v_mfma_f32_16x16x32_bf16 v[32:35], v[180:183], v[196:199], v[32:35]
	s_setprio 2
	s_barrier
	v_mfma_f32_16x16x32_bf16 v[24:27], v[172:175], v[204:207], v[24:27]
	v_mfma_f32_16x16x32_bf16 v[16:19], v[180:183], v[204:207], v[16:19]
	v_mfma_f32_16x16x32_bf16 v[8:11], v[172:175], v[212:215], v[8:11]
	v_mfma_f32_16x16x32_bf16 v[0:3], v[180:183], v[212:215], v[0:3]
	s_setprio 0
	s_add_i32 s54, 0, 0x18000
	s_add_i32 s55, 0, 0x1c000
	v_add_u32_e32 v164, s54, v151
	v_add_u32_e32 v180, s55, v151
	ds_read_b128 v[146:149], v164
	ds_read_b128 v[156:159], v164 offset:1024
	ds_read_b128 v[160:163], v164 offset:2048
	ds_read_b128 v[164:167], v164 offset:3072
	ds_read_b128 v[168:171], v180
	ds_read_b128 v[172:175], v180 offset:1024
	ds_read_b128 v[176:179], v180 offset:2048
	ds_read_b128 v[180:183], v180 offset:3072
	s_add_u32 s24, s24, 0x80000
	s_addc_u32 s25, s25, 0
	s_mov_b32 m0, s34
	v_lshl_add_u64 v[224:225], s[24:25], 0, v[136:137]
	ds_read_b128 v[184:187], v155 offset:32768
	ds_read_b128 v[188:191], v155 offset:33792
	ds_read_b128 v[192:195], v155 offset:34816
	ds_read_b128 v[196:199], v155 offset:35840
	ds_read_b128 v[200:203], v155 offset:36864
	ds_read_b128 v[204:207], v155 offset:37888
	ds_read_b128 v[208:211], v155 offset:38912
	ds_read_b128 v[212:215], v155 offset:39936
	global_load_lds_dwordx4 v[224:225], off
	v_lshl_add_u64 v[224:225], s[24:25], 0, v[132:133]
	s_mov_b32 m0, s35
	s_nop 0
	global_load_lds_dwordx4 v[224:225], off
	s_waitcnt vmcnt(8)
	s_waitcnt lgkmcnt(0)
	s_barrier
	s_setprio 1
	s_waitcnt lgkmcnt(0)
	v_mfma_f32_16x16x32_bf16 v[124:127], v[146:149], v[184:187], v[124:127]
	v_mfma_f32_16x16x32_bf16 v[116:119], v[160:163], v[184:187], v[116:119]
	v_mfma_f32_16x16x32_bf16 v[108:111], v[146:149], v[192:195], v[108:111]
	v_mfma_f32_16x16x32_bf16 v[100:103], v[160:163], v[192:195], v[100:103]
	v_mfma_f32_16x16x32_bf16 v[92:95], v[146:149], v[200:203], v[92:95]
	v_mfma_f32_16x16x32_bf16 v[84:87], v[160:163], v[200:203], v[84:87]
	v_mfma_f32_16x16x32_bf16 v[76:79], v[146:149], v[208:211], v[76:79]
	v_mfma_f32_16x16x32_bf16 v[68:71], v[160:163], v[208:211], v[68:71]
	v_mfma_f32_16x16x32_bf16 v[124:127], v[156:159], v[188:191], v[124:127]
	v_mfma_f32_16x16x32_bf16 v[116:119], v[164:167], v[188:191], v[116:119]
	v_mfma_f32_16x16x32_bf16 v[108:111], v[156:159], v[196:199], v[108:111]
	v_mfma_f32_16x16x32_bf16 v[100:103], v[164:167], v[196:199], v[100:103]
	v_mfma_f32_16x16x32_bf16 v[92:95], v[156:159], v[204:207], v[92:95]
	v_mfma_f32_16x16x32_bf16 v[84:87], v[164:167], v[204:207], v[84:87]
	v_mfma_f32_16x16x32_bf16 v[76:79], v[156:159], v[212:215], v[76:79]
	v_mfma_f32_16x16x32_bf16 v[68:71], v[164:167], v[212:215], v[68:71]
	s_setprio 0
	s_setprio 1
	v_mfma_f32_16x16x32_bf16 v[120:123], v[168:171], v[184:187], v[120:123]
	v_mfma_f32_16x16x32_bf16 v[112:115], v[176:179], v[184:187], v[112:115]
	v_mfma_f32_16x16x32_bf16 v[104:107], v[168:171], v[192:195], v[104:107]
	v_mfma_f32_16x16x32_bf16 v[96:99], v[176:179], v[192:195], v[96:99]
	v_mfma_f32_16x16x32_bf16 v[88:91], v[168:171], v[200:203], v[88:91]
	v_mfma_f32_16x16x32_bf16 v[80:83], v[176:179], v[200:203], v[80:83]
	v_mfma_f32_16x16x32_bf16 v[72:75], v[168:171], v[208:211], v[72:75]
	v_mfma_f32_16x16x32_bf16 v[64:67], v[176:179], v[208:211], v[64:67]
	v_mfma_f32_16x16x32_bf16 v[120:123], v[172:175], v[188:191], v[120:123]
	v_mfma_f32_16x16x32_bf16 v[112:115], v[180:183], v[188:191], v[112:115]
	v_mfma_f32_16x16x32_bf16 v[104:107], v[172:175], v[196:199], v[104:107]
	v_mfma_f32_16x16x32_bf16 v[96:99], v[180:183], v[196:199], v[96:99]
	s_setprio 2
	s_barrier
; #define PG8_STAGE(bufoff, gbase, voff) do { _Pragma("unroll") for (int _i = 0; _i < 2; ++_i) \
;         __builtin_amdgcn_global_load_lds((const unsigned*)((const char*)(gbase) + (voff)[_i]), (PG8_LAS unsigned*)(lds + (bufoff) + ldsw + _i * 8192), 16, 0, 0); } while (0)
; #define PG8_LDA(dst, b, h) do { _Pragma("unroll") for (int m = 0; m < 4; ++m) _Pragma("unroll") for (int k = 0; k < 2; ++k) dst[m][k] = *(const PG8_LAS bf16x8*)(lds + PG8_SA(b, h) + aoff + m * 2048 + k * 1024); } while (0)
; #define PG8_MMA(ai, bj, At, Bt) do { __builtin_amdgcn_s_setprio(1); _Pragma("unroll") for (int m = 0; m < 4; ++m) _Pragma("unroll") for (int n = 0; n < 2; ++n) _Pragma("unroll") for (int k = 0; k < 2; ++k) \
;         acc[ai][bj][m][n] = __builtin_amdgcn_mfma_f32_16x16x32_bf16(Bt[n][k], At[m][k], acc[ai][bj][m][n], 0, 0, 0); __builtin_amdgcn_s_setprio(0); } while (0)
; #define PG8_WAIT_V(n) asm volatile("s_waitcnt vmcnt(" #n ")" ::: "memory")
; #define PG8_WAIT_L(n) asm volatile("s_waitcnt lgkmcnt(" #n ")" ::: "memory")
; #define PG8_BAR __builtin_amdgcn_s_barrier()
; #define PG8_SCHED __builtin_amdgcn_sched_barrier(0)
; template <class Epi, class Sched, bool ALIGN_EPI = false, bool SP2 = false>
; __device__ __forceinline__ void gemm_phase(PG8_LAS unsigned char* lds, const Gemm g, const Sched& S, const Epi& E) {
;     ...
;             PG8_WAIT_V(8); PG8_WAIT_L(0); PG8_BAR; PG8_MMA(0, 0, At, B0); PG8_MMA(0, 1, At, B1); PG8_BAR; PG8_SCHED;
;             PG8_LDA(At, 1, 1); PG8_STAGE(PG8_SB(1, 0), b3, voffB); PG8_STAGE(PG8_SB(1, 1), b3 + hstep, voffB); PG8_STAGE(PG8_SA(1, 0), a3, voffA);
;             PG8_WAIT_V(8); PG8_WAIT_L(0); PG8_BAR; PG8_MMA(1, 0, At, B0); PG8_MMA(1, 1, At, B1); PG8_BAR; PG8_SCHED;
	v_mfma_f32_16x16x32_bf16 v[88:91], v[172:175], v[204:207], v[88:91]
	v_mfma_f32_16x16x32_bf16 v[80:83], v[180:183], v[204:207], v[80:83]
	v_mfma_f32_16x16x32_bf16 v[72:75], v[172:175], v[212:215], v[72:75]
	v_mfma_f32_16x16x32_bf16 v[64:67], v[180:183], v[212:215], v[64:67]
	s_setprio 0
	s_add_i32 s24, s54, s28
	v_lshl_add_u64 v[216:217], v[216:217], 0, s[4:5]
	s_mov_b32 m0, s24
	ds_read_b128 v[184:187], v155 offset:49152
	ds_read_b128 v[188:191], v155 offset:50176
	ds_read_b128 v[192:195], v155 offset:51200
	ds_read_b128 v[196:199], v155 offset:52224
	ds_read_b128 v[200:203], v155 offset:53248
	ds_read_b128 v[204:207], v155 offset:54272
	ds_read_b128 v[208:211], v155 offset:55296
	ds_read_b128 v[212:215], v155 offset:56320
	global_load_lds_dwordx4 v[216:217], off
	s_add_i32 m0, s24, 0x2000
	s_add_u32 s22, s22, 0x80080
	v_lshl_add_u64 v[216:217], v[218:219], 0, s[4:5]
	s_addc_u32 s23, s23, 0
	s_add_i32 s24, s55, s28
	global_load_lds_dwordx4 v[216:217], off
	v_lshl_add_u64 v[216:217], s[22:23], 0, v[134:135]
	s_mov_b32 m0, s24
	s_nop 0
	global_load_lds_dwordx4 v[216:217], off
	v_lshl_add_u64 v[216:217], s[22:23], 0, v[130:131]
	s_add_i32 m0, s24, 0x2000
	s_nop 0
	global_load_lds_dwordx4 v[216:217], off
	v_lshl_add_u64 v[216:217], v[220:221], 0, s[4:5]
	s_mov_b32 m0, s37
	s_nop 0
	global_load_lds_dwordx4 v[216:217], off
	v_lshl_add_u64 v[216:217], v[222:223], 0, s[4:5]
	s_mov_b32 m0, s38
	s_nop 0
	global_load_lds_dwordx4 v[216:217], off
	s_waitcnt vmcnt(8)
	s_waitcnt lgkmcnt(0)
	s_barrier
	s_setprio 1
	s_waitcnt lgkmcnt(0)
	v_mfma_f32_16x16x32_bf16 v[60:63], v[146:149], v[184:187], v[60:63]
	v_mfma_f32_16x16x32_bf16 v[52:55], v[160:163], v[184:187], v[52:55]
	v_mfma_f32_16x16x32_bf16 v[44:47], v[146:149], v[192:195], v[44:47]
	v_mfma_f32_16x16x32_bf16 v[36:39], v[160:163], v[192:195], v[36:39]
	v_mfma_f32_16x16x32_bf16 v[28:31], v[146:149], v[200:203], v[28:31]
	v_mfma_f32_16x16x32_bf16 v[20:23], v[160:163], v[200:203], v[20:23]
	v_mfma_f32_16x16x32_bf16 v[12:15], v[146:149], v[208:211], v[12:15]
	v_mfma_f32_16x16x32_bf16 v[4:7], v[160:163], v[208:211], v[4:7]
	v_mfma_f32_16x16x32_bf16 v[60:63], v[156:159], v[188:191], v[60:63]
	v_mfma_f32_16x16x32_bf16 v[52:55], v[164:167], v[188:191], v[52:55]
	v_mfma_f32_16x16x32_bf16 v[44:47], v[156:159], v[196:199], v[44:47]
	v_mfma_f32_16x16x32_bf16 v[36:39], v[164:167], v[196:199], v[36:39]
	v_mfma_f32_16x16x32_bf16 v[28:31], v[156:159], v[204:207], v[28:31]
	v_mfma_f32_16x16x32_bf16 v[20:23], v[164:167], v[204:207], v[20:23]
	v_mfma_f32_16x16x32_bf16 v[12:15], v[156:159], v[212:215], v[12:15]
	v_mfma_f32_16x16x32_bf16 v[4:7], v[164:167], v[212:215], v[4:7]
	s_setprio 0
	s_setprio 1
	v_mfma_f32_16x16x32_bf16 v[56:59], v[168:171], v[184:187], v[56:59]
	v_mfma_f32_16x16x32_bf16 v[48:51], v[176:179], v[184:187], v[48:51]
	v_mfma_f32_16x16x32_bf16 v[40:43], v[168:171], v[192:195], v[40:43]
	v_mfma_f32_16x16x32_bf16 v[32:35], v[176:179], v[192:195], v[32:35]
	v_mfma_f32_16x16x32_bf16 v[24:27], v[168:171], v[200:203], v[24:27]
	v_mfma_f32_16x16x32_bf16 v[16:19], v[176:179], v[200:203], v[16:19]
	v_mfma_f32_16x16x32_bf16 v[8:11], v[168:171], v[208:211], v[8:11]
	v_mfma_f32_16x16x32_bf16 v[0:3], v[176:179], v[208:211], v[0:3]
	v_mfma_f32_16x16x32_bf16 v[56:59], v[172:175], v[188:191], v[56:59]
	v_mfma_f32_16x16x32_bf16 v[48:51], v[180:183], v[188:191], v[48:51]
	v_mfma_f32_16x16x32_bf16 v[40:43], v[172:175], v[196:199], v[40:43]
	v_mfma_f32_16x16x32_bf16 v[32:35], v[180:183], v[196:199], v[32:35]
	s_setprio 2
	s_barrier
	v_mfma_f32_16x16x32_bf16 v[24:27], v[172:175], v[204:207], v[24:27]
	v_mfma_f32_16x16x32_bf16 v[16:19], v[180:183], v[204:207], v[16:19]
	v_mfma_f32_16x16x32_bf16 v[8:11], v[172:175], v[212:215], v[8:11]
	v_mfma_f32_16x16x32_bf16 v[0:3], v[180:183], v[212:215], v[0:3]
	s_setprio 0
	s_add_i32 s53, s53, 2
	s_add_u32 s20, s20, 0x100
	s_addc_u32 s21, s21, 0
	s_add_u32 s51, s51, 0x100
	s_addc_u32 s52, s52, 0
	s_cmp_gt_u32 s53, 29
	s_cbranch_scc0 .LBB0_48
	s_and_b64 vcc, exec, s[8:9]
	s_cbranch_vccz .LBB0_51
	s_barrier

;     __host__ __device__ bool next(int i, Unit& u) const { return (i + I0 < I1) && StaticOrder::next(i + I0, u); }
; #define PG8_STAGE(bufoff, gbase, voff) do { _Pragma("unroll") for (int _i = 0; _i < 2; ++_i) \
;         __builtin_amdgcn_global_load_lds((const unsigned*)((const char*)(gbase) + (voff)[_i]), (PG8_LAS unsigned*)(lds + (bufoff) + ldsw + _i * 8192), 16, 0, 0); } while (0)
; #define PG8_LDA(dst, b, h) do { _Pragma("unroll") for (int m = 0; m < 4; ++m) _Pragma("unroll") for (int k = 0; k < 2; ++k) dst[m][k] = *(const PG8_LAS bf16x8*)(lds + PG8_SA(b, h) + aoff + m * 2048 + k * 1024); } while (0)
; #define PG8_LDB(dst, b, h) do { _Pragma("unroll") for (int n = 0; n < 2; ++n) _Pragma("unroll") for (int k = 0; k < 2; ++k) dst[n][k] = *(const PG8_LAS bf16x8*)(lds + PG8_SB(b, h) + boff + n * 2048 + k * 1024); } while (0)
; #define PG8_WAIT_V(n) asm volatile("s_waitcnt vmcnt(" #n ")" ::: "memory")
; #define PG8_WAIT_L(n) asm volatile("s_waitcnt lgkmcnt(" #n ")" ::: "memory")
; #define PG8_BAR __builtin_amdgcn_s_barrier()
; #define PG8_SCHED __builtin_amdgcn_sched_barrier(0)
; template <class Epi, class Sched, bool ALIGN_EPI = false, bool SP2 = false>
; __device__ __forceinline__ void gemm_phase(PG8_LAS unsigned char* lds, const Gemm g, const Sched& S, const Epi& E) {
;     ...
;         const bool has_next = S.next(ui + 1, nxt);
;         const char* nA = has_next ? (const char*)g.A + (size_t)nxt.pm * tstep : cA; const char* nB = has_next ? (const char*)g.Bt + (size_t)nxt.pn * tstep : cB;
;         for (int t = 0; t < nt; t += 2) {
;             const bool last = (t == nt - 2);
;             const char* a1 = cA + (size_t)(t + 1) * kstep;
;             const char* a2 = last ? nA : cA + (size_t)(t + 2) * kstep; const char* b2 = last ? nB : cB + (size_t)(t + 2) * kstep;
;             const char* a3 = a2 + kstep; const char* b3 = b2 + kstep;
;             if (last && has_next) S.a_ready(nxt);
;             if constexpr (SP2) {
;             PG8_LDB(B0, 0, 0); PG8_LDB(B1, 0, 1); PG8_SCHED; PG8_LDA(At, 0, 0); PG8_STAGE(PG8_SA(1, 1), a1 + hstep, voffA);
;             PG8_WAIT_V(8); PG8_WAIT_L(0); PG8_BAR; PG8_MMA(0, 0, At, B0); PG8_MMA(0, 1, At, B1); PG8_BAR; PG8_SCHED;
;             PG8_LDA(At, 0, 1); PG8_STAGE(PG8_SB(0, 0), b2, voffB); PG8_STAGE(PG8_SB(0, 1), b2 + hstep, voffB); PG8_STAGE(PG8_SA(0, 0), a2, voffA);
.LBB0_140:
	ds_read_b128 v[158:161], v155
	ds_read_b128 v[162:165], v155 offset:1024
	ds_read_b128 v[166:169], v155 offset:2048
	ds_read_b128 v[170:173], v155 offset:3072
	ds_read_b128 v[174:177], v156
	ds_read_b128 v[178:181], v156 offset:1024
	ds_read_b128 v[182:185], v156 offset:2048
	ds_read_b128 v[186:189], v156 offset:3072
	s_add_u32 s24, s22, 0xffea0080
	s_addc_u32 s25, s23, -1
	s_cmpk_eq_i32 s58, 0x54
	s_cselect_b32 s27, s19, s25
	s_cselect_b32 s26, s18, s24
	s_cselect_b32 s25, s21, s57
	s_cselect_b32 s24, s20, s56
	v_lshl_add_u64 v[222:223], s[22:23], 0, v[138:139]
	s_add_i32 m0, s31, 0xc000
	ds_read_b128 v[190:193], v157
	ds_read_b128 v[194:197], v157 offset:1024
	ds_read_b128 v[198:201], v157 offset:2048
	ds_read_b128 v[202:205], v157 offset:3072
	ds_read_b128 v[206:209], v157 offset:4096
	ds_read_b128 v[210:213], v157 offset:5120
	ds_read_b128 v[214:217], v157 offset:6144
	ds_read_b128 v[218:221], v157 offset:7168
	global_load_lds_dwordx4 v[222:223], off
	v_lshl_add_u64 v[222:223], s[22:23], 0, v[140:141]
	s_add_i32 m0, s31, 0xe000
	s_nop 0
	global_load_lds_dwordx4 v[222:223], off
	s_waitcnt vmcnt(8)
	s_waitcnt lgkmcnt(0)
	s_barrier
	s_setprio 1
	s_waitcnt lgkmcnt(0)
	v_mfma_f32_16x16x32_bf16 v[124:127], v[158:161], v[190:193], v[124:127]
	v_mfma_f32_16x16x32_bf16 v[120:123], v[166:169], v[190:193], v[120:123]
	v_mfma_f32_16x16x32_bf16 v[116:119], v[158:161], v[198:201], v[116:119]
	v_mfma_f32_16x16x32_bf16 v[112:115], v[166:169], v[198:201], v[112:115]
	v_mfma_f32_16x16x32_bf16 v[100:103], v[158:161], v[206:209], v[100:103]
	v_mfma_f32_16x16x32_bf16 v[96:99], v[166:169], v[206:209], v[96:99]
	v_mfma_f32_16x16x32_bf16 v[84:87], v[158:161], v[214:217], v[84:87]
	v_mfma_f32_16x16x32_bf16 v[80:83], v[166:169], v[214:217], v[80:83]
	v_mfma_f32_16x16x32_bf16 v[124:127], v[162:165], v[194:197], v[124:127]
	v_mfma_f32_16x16x32_bf16 v[120:123], v[170:173], v[194:197], v[120:123]
	v_mfma_f32_16x16x32_bf16 v[116:119], v[162:165], v[202:205], v[116:119]
	v_mfma_f32_16x16x32_bf16 v[112:115], v[170:173], v[202:205], v[112:115]
	v_mfma_f32_16x16x32_bf16 v[100:103], v[162:165], v[210:213], v[100:103]
	v_mfma_f32_16x16x32_bf16 v[96:99], v[170:173], v[210:213], v[96:99]
	v_mfma_f32_16x16x32_bf16 v[84:87], v[162:165], v[218:221], v[84:87]
	v_mfma_f32_16x16x32_bf16 v[80:83], v[170:173], v[218:221], v[80:83]
	s_setprio 0
	s_setprio 1
	v_mfma_f32_16x16x32_bf16 v[108:111], v[174:177], v[190:193], v[108:111]
	v_mfma_f32_16x16x32_bf16 v[104:107], v[182:185], v[190:193], v[104:107]
	v_mfma_f32_16x16x32_bf16 v[92:95], v[174:177], v[198:201], v[92:95]
	v_mfma_f32_16x16x32_bf16 v[88:91], v[182:185], v[198:201], v[88:91]
	v_mfma_f32_16x16x32_bf16 v[76:79], v[174:177], v[206:209], v[76:79]
	v_mfma_f32_16x16x32_bf16 v[72:75], v[182:185], v[206:209], v[72:75]
	v_mfma_f32_16x16x32_bf16 v[68:71], v[174:177], v[214:217], v[68:71]
	v_mfma_f32_16x16x32_bf16 v[64:67], v[182:185], v[214:217], v[64:67]
	v_mfma_f32_16x16x32_bf16 v[108:111], v[178:181], v[194:197], v[108:111]
	v_mfma_f32_16x16x32_bf16 v[104:107], v[186:189], v[194:197], v[104:107]
	v_mfma_f32_16x16x32_bf16 v[92:95], v[178:181], v[202:205], v[92:95]
	v_mfma_f32_16x16x32_bf16 v[88:91], v[186:189], v[202:205], v[88:91]
	s_setprio 2
	s_barrier
	v_mfma_f32_16x16x32_bf16 v[76:79], v[178:181], v[210:213], v[76:79]
	v_mfma_f32_16x16x32_bf16 v[72:75], v[186:189], v[210:213], v[72:75]
	v_mfma_f32_16x16x32_bf16 v[68:71], v[178:181], v[218:221], v[68:71]
	v_mfma_f32_16x16x32_bf16 v[64:67], v[186:189], v[218:221], v[64:67]
	s_setprio 0
	s_add_i32 s59, s42, s28
	v_lshl_add_u64 v[222:223], s[24:25], 0, v[132:133]
	s_mov_b32 m0, s59
	ds_read_b128 v[190:193], v157 offset:16384
	ds_read_b128 v[194:197], v157 offset:17408
	ds_read_b128 v[198:201], v157 offset:18432
	ds_read_b128 v[202:205], v157 offset:19456
	ds_read_b128 v[206:209], v157 offset:20480
	ds_read_b128 v[210:213], v157 offset:21504
	ds_read_b128 v[214:217], v157 offset:22528
	ds_read_b128 v[218:221], v157 offset:23552
	global_load_lds_dwordx4 v[222:223], off
	s_add_i32 m0, s59, 0x2000
	s_add_u32 s60, s24, 0x160000
	v_lshl_add_u64 v[224:225], s[24:25], 0, v[136:137]
	s_addc_u32 s61, s25, 0
	s_add_i32 s59, s43, s28
	global_load_lds_dwordx4 v[224:225], off
	v_lshl_add_u64 v[226:227], s[60:61], 0, v[132:133]
	s_mov_b32 m0, s59
	v_lshl_add_u64 v[228:229], s[26:27], 0, v[134:135]
	global_load_lds_dwordx4 v[226:227], off
	v_lshl_add_u64 v[226:227], s[60:61], 0, v[136:137]
	s_add_i32 m0, s59, 0x2000
	s_nop 0
	global_load_lds_dwordx4 v[226:227], off
	v_lshl_add_u64 v[226:227], s[26:27], 0, v[130:131]
	s_mov_b32 m0, s31
	s_nop 0
	global_load_lds_dwordx4 v[226:227], off
	s_mov_b32 m0, s34
	s_nop 0
	global_load_lds_dwordx4 v[228:229], off
	s_waitcnt vmcnt(8)
	s_waitcnt lgkmcnt(0)
	s_barrier
; #define PG8_STAGE(bufoff, gbase, voff) do { _Pragma("unroll") for (int _i = 0; _i < 2; ++_i) \
;         __builtin_amdgcn_global_load_lds((const unsigned*)((const char*)(gbase) + (voff)[_i]), (PG8_LAS unsigned*)(lds + (bufoff) + ldsw + _i * 8192), 16, 0, 0); } while (0)
; #define PG8_LDA(dst, b, h) do { _Pragma("unroll") for (int m = 0; m < 4; ++m) _Pragma("unroll") for (int k = 0; k < 2; ++k) dst[m][k] = *(const PG8_LAS bf16x8*)(lds + PG8_SA(b, h) + aoff + m * 2048 + k * 1024); } while (0)
; #define PG8_LDB(dst, b, h) do { _Pragma("unroll") for (int n = 0; n < 2; ++n) _Pragma("unroll") for (int k = 0; k < 2; ++k) dst[n][k] = *(const PG8_LAS bf16x8*)(lds + PG8_SB(b, h) + boff + n * 2048 + k * 1024); } while (0)
; #define PG8_MMA(ai, bj, At, Bt) do { __builtin_amdgcn_s_setprio(1); _Pragma("unroll") for (int m = 0; m < 4; ++m) _Pragma("unroll") for (int n = 0; n < 2; ++n) _Pragma("unroll") for (int k = 0; k < 2; ++k) \
;         acc[ai][bj][m][n] = __builtin_amdgcn_mfma_f32_16x16x32_bf16(Bt[n][k], At[m][k], acc[ai][bj][m][n], 0, 0, 0); __builtin_amdgcn_s_setprio(0); } while (0)
; #define PG8_WAIT_V(n) asm volatile("s_waitcnt vmcnt(" #n ")" ::: "memory")
; #define PG8_WAIT_L(n) asm volatile("s_waitcnt lgkmcnt(" #n ")" ::: "memory")
; #define PG8_BAR __builtin_amdgcn_s_barrier()
; #define PG8_SCHED __builtin_amdgcn_sched_barrier(0)
; template <class Epi, class Sched, bool ALIGN_EPI = false, bool SP2 = false>
; __device__ __forceinline__ void gemm_phase(PG8_LAS unsigned char* lds, const Gemm g, const Sched& S, const Epi& E) {
;     ...
;             PG8_WAIT_V(8); PG8_WAIT_L(0); PG8_BAR; PG8_MMA(1, 0, At, B0); PG8_MMA(1, 1, At, B1); PG8_BAR; PG8_SCHED;
;             PG8_LDB(B0, 1, 0); PG8_LDB(B1, 1, 1); PG8_SCHED; PG8_LDA(At, 1, 0); PG8_STAGE(PG8_SA(0, 1), a2 + hstep, voffA);
;             PG8_WAIT_V(8); PG8_WAIT_L(0); PG8_BAR; PG8_MMA(0, 0, At, B0); PG8_MMA(0, 1, At, B1); PG8_BAR; PG8_SCHED;
	s_setprio 1
	s_waitcnt lgkmcnt(0)
	v_mfma_f32_16x16x32_bf16 v[60:63], v[158:161], v[190:193], v[60:63]
	v_mfma_f32_16x16x32_bf16 v[56:59], v[166:169], v[190:193], v[56:59]
	v_mfma_f32_16x16x32_bf16 v[52:55], v[158:161], v[198:201], v[52:55]
	v_mfma_f32_16x16x32_bf16 v[48:51], v[166:169], v[198:201], v[48:51]
	v_mfma_f32_16x16x32_bf16 v[36:39], v[158:161], v[206:209], v[36:39]
	v_mfma_f32_16x16x32_bf16 v[32:35], v[166:169], v[206:209], v[32:35]
	v_mfma_f32_16x16x32_bf16 v[20:23], v[158:161], v[214:217], v[20:23]
	v_mfma_f32_16x16x32_bf16 v[16:19], v[166:169], v[214:217], v[16:19]
	v_mfma_f32_16x16x32_bf16 v[60:63], v[162:165], v[194:197], v[60:63]
	v_mfma_f32_16x16x32_bf16 v[56:59], v[170:173], v[194:197], v[56:59]
	v_mfma_f32_16x16x32_bf16 v[52:55], v[162:165], v[202:205], v[52:55]
	v_mfma_f32_16x16x32_bf16 v[48:51], v[170:173], v[202:205], v[48:51]
	v_mfma_f32_16x16x32_bf16 v[36:39], v[162:165], v[210:213], v[36:39]
	v_mfma_f32_16x16x32_bf16 v[32:35], v[170:173], v[210:213], v[32:35]
	v_mfma_f32_16x16x32_bf16 v[20:23], v[162:165], v[218:221], v[20:23]
	v_mfma_f32_16x16x32_bf16 v[16:19], v[170:173], v[218:221], v[16:19]
	s_setprio 0
	s_setprio 1
	v_mfma_f32_16x16x32_bf16 v[44:47], v[174:177], v[190:193], v[44:47]
	v_mfma_f32_16x16x32_bf16 v[40:43], v[182:185], v[190:193], v[40:43]
	v_mfma_f32_16x16x32_bf16 v[28:31], v[174:177], v[198:201], v[28:31]
	v_mfma_f32_16x16x32_bf16 v[24:27], v[182:185], v[198:201], v[24:27]
	v_mfma_f32_16x16x32_bf16 v[12:15], v[174:177], v[206:209], v[12:15]
	v_mfma_f32_16x16x32_bf16 v[8:11], v[182:185], v[206:209], v[8:11]
	v_mfma_f32_16x16x32_bf16 v[4:7], v[174:177], v[214:217], v[4:7]
	v_mfma_f32_16x16x32_bf16 v[0:3], v[182:185], v[214:217], v[0:3]
	v_mfma_f32_16x16x32_bf16 v[44:47], v[178:181], v[194:197], v[44:47]
	v_mfma_f32_16x16x32_bf16 v[40:43], v[186:189], v[194:197], v[40:43]
	v_mfma_f32_16x16x32_bf16 v[28:31], v[178:181], v[202:205], v[28:31]
	v_mfma_f32_16x16x32_bf16 v[24:27], v[186:189], v[202:205], v[24:27]
	s_setprio 2
	s_barrier
	v_mfma_f32_16x16x32_bf16 v[12:15], v[178:181], v[210:213], v[12:15]
	v_mfma_f32_16x16x32_bf16 v[8:11], v[186:189], v[210:213], v[8:11]
	v_mfma_f32_16x16x32_bf16 v[4:7], v[178:181], v[218:221], v[4:7]
	v_mfma_f32_16x16x32_bf16 v[0:3], v[186:189], v[218:221], v[0:3]
	s_setprio 0
	s_add_i32 s59, 0, 0x18000
	s_add_i32 s60, 0, 0x1c000
	v_add_u32_e32 v170, s59, v153
	v_add_u32_e32 v186, s60, v153
	ds_read_b128 v[158:161], v170
	ds_read_b128 v[162:165], v170 offset:1024
	ds_read_b128 v[166:169], v170 offset:2048
	ds_read_b128 v[170:173], v170 offset:3072
	ds_read_b128 v[174:177], v186
	ds_read_b128 v[178:181], v186 offset:1024
	ds_read_b128 v[182:185], v186 offset:2048
	ds_read_b128 v[186:189], v186 offset:3072
	s_add_u32 s26, s26, 0x160000
	s_addc_u32 s27, s27, 0
	s_mov_b32 m0, s35
	v_lshl_add_u64 v[230:231], s[26:27], 0, v[130:131]
	ds_read_b128 v[190:193], v157 offset:32768
	ds_read_b128 v[194:197], v157 offset:33792
	ds_read_b128 v[198:201], v157 offset:34816
	ds_read_b128 v[202:205], v157 offset:35840
	ds_read_b128 v[206:209], v157 offset:36864
	ds_read_b128 v[210:213], v157 offset:37888
	ds_read_b128 v[214:217], v157 offset:38912
	ds_read_b128 v[218:221], v157 offset:39936
	global_load_lds_dwordx4 v[230:231], off
	v_lshl_add_u64 v[230:231], s[26:27], 0, v[134:135]
	s_mov_b32 m0, s36
	s_nop 0
	global_load_lds_dwordx4 v[230:231], off
	s_waitcnt vmcnt(8)
	s_waitcnt lgkmcnt(0)
	s_barrier
	s_setprio 1
	s_waitcnt lgkmcnt(0)
	v_mfma_f32_16x16x32_bf16 v[124:127], v[158:161], v[190:193], v[124:127]
	v_mfma_f32_16x16x32_bf16 v[120:123], v[166:169], v[190:193], v[120:123]
	v_mfma_f32_16x16x32_bf16 v[116:119], v[158:161], v[198:201], v[116:119]
	v_mfma_f32_16x16x32_bf16 v[112:115], v[166:169], v[198:201], v[112:115]
	v_mfma_f32_16x16x32_bf16 v[100:103], v[158:161], v[206:209], v[100:103]
	v_mfma_f32_16x16x32_bf16 v[96:99], v[166:169], v[206:209], v[96:99]
	v_mfma_f32_16x16x32_bf16 v[84:87], v[158:161], v[214:217], v[84:87]
	v_mfma_f32_16x16x32_bf16 v[80:83], v[166:169], v[214:217], v[80:83]
	v_mfma_f32_16x16x32_bf16 v[124:127], v[162:165], v[194:197], v[124:127]
	v_mfma_f32_16x16x32_bf16 v[120:123], v[170:173], v[194:197], v[120:123]
	v_mfma_f32_16x16x32_bf16 v[116:119], v[162:165], v[202:205], v[116:119]
	v_mfma_f32_16x16x32_bf16 v[112:115], v[170:173], v[202:205], v[112:115]
	v_mfma_f32_16x16x32_bf16 v[100:103], v[162:165], v[210:213], v[100:103]
	v_mfma_f32_16x16x32_bf16 v[96:99], v[170:173], v[210:213], v[96:99]
	v_mfma_f32_16x16x32_bf16 v[84:87], v[162:165], v[218:221], v[84:87]
	v_mfma_f32_16x16x32_bf16 v[80:83], v[170:173], v[218:221], v[80:83]
	s_setprio 0
	s_setprio 1
	v_mfma_f32_16x16x32_bf16 v[108:111], v[174:177], v[190:193], v[108:111]
	v_mfma_f32_16x16x32_bf16 v[104:107], v[182:185], v[190:193], v[104:107]
	v_mfma_f32_16x16x32_bf16 v[92:95], v[174:177], v[198:201], v[92:95]
	v_mfma_f32_16x16x32_bf16 v[88:91], v[182:185], v[198:201], v[88:91]
	v_mfma_f32_16x16x32_bf16 v[76:79], v[174:177], v[206:209], v[76:79]
	v_mfma_f32_16x16x32_bf16 v[72:75], v[182:185], v[206:209], v[72:75]
	v_mfma_f32_16x16x32_bf16 v[68:71], v[174:177], v[214:217], v[68:71]
	v_mfma_f32_16x16x32_bf16 v[64:67], v[182:185], v[214:217], v[64:67]
	v_mfma_f32_16x16x32_bf16 v[108:111], v[178:181], v[194:197], v[108:111]
	v_mfma_f32_16x16x32_bf16 v[104:107], v[186:189], v[194:197], v[104:107]
	v_mfma_f32_16x16x32_bf16 v[92:95], v[178:181], v[202:205], v[92:95]
	v_mfma_f32_16x16x32_bf16 v[88:91], v[186:189], v[202:205], v[88:91]
	s_setprio 2
	s_barrier
; #define PG8_STAGE(bufoff, gbase, voff) do { _Pragma("unroll") for (int _i = 0; _i < 2; ++_i) \
;         __builtin_amdgcn_global_load_lds((const unsigned*)((const char*)(gbase) + (voff)[_i]), (PG8_LAS unsigned*)(lds + (bufoff) + ldsw + _i * 8192), 16, 0, 0); } while (0)
; #define PG8_LDA(dst, b, h) do { _Pragma("unroll") for (int m = 0; m < 4; ++m) _Pragma("unroll") for (int k = 0; k < 2; ++k) dst[m][k] = *(const PG8_LAS bf16x8*)(lds + PG8_SA(b, h) + aoff + m * 2048 + k * 1024); } while (0)
; #define PG8_MMA(ai, bj, At, Bt) do { __builtin_amdgcn_s_setprio(1); _Pragma("unroll") for (int m = 0; m < 4; ++m) _Pragma("unroll") for (int n = 0; n < 2; ++n) _Pragma("unroll") for (int k = 0; k < 2; ++k) \
;         acc[ai][bj][m][n] = __builtin_amdgcn_mfma_f32_16x16x32_bf16(Bt[n][k], At[m][k], acc[ai][bj][m][n], 0, 0, 0); __builtin_amdgcn_s_setprio(0); } while (0)
; #define PG8_WAIT_V(n) asm volatile("s_waitcnt vmcnt(" #n ")" ::: "memory")
; #define PG8_WAIT_L(n) asm volatile("s_waitcnt lgkmcnt(" #n ")" ::: "memory")
; #define PG8_BAR __builtin_amdgcn_s_barrier()
; #define PG8_SCHED __builtin_amdgcn_sched_barrier(0)
; template <class Epi, class Sched, bool ALIGN_EPI = false, bool SP2 = false>
; __device__ __forceinline__ void gemm_phase(PG8_LAS unsigned char* lds, const Gemm g, const Sched& S, const Epi& E) {
;     ...
;             PG8_WAIT_V(8); PG8_WAIT_L(0); PG8_BAR; PG8_MMA(0, 0, At, B0); PG8_MMA(0, 1, At, B1); PG8_BAR; PG8_SCHED;
;             PG8_LDA(At, 1, 1); PG8_STAGE(PG8_SB(1, 0), b3, voffB); PG8_STAGE(PG8_SB(1, 1), b3 + hstep, voffB); PG8_STAGE(PG8_SA(1, 0), a3, voffA);
;             PG8_WAIT_V(8); PG8_WAIT_L(0); PG8_BAR; PG8_MMA(1, 0, At, B0); PG8_MMA(1, 1, At, B1); PG8_BAR; PG8_SCHED;
	v_mfma_f32_16x16x32_bf16 v[76:79], v[178:181], v[210:213], v[76:79]
	v_mfma_f32_16x16x32_bf16 v[72:75], v[186:189], v[210:213], v[72:75]
	v_mfma_f32_16x16x32_bf16 v[68:71], v[178:181], v[218:221], v[68:71]
	v_mfma_f32_16x16x32_bf16 v[64:67], v[186:189], v[218:221], v[64:67]
	s_setprio 0
	s_add_i32 s26, s59, s28
	v_lshl_add_u64 v[222:223], v[222:223], 0, s[4:5]
	s_mov_b32 m0, s26
	ds_read_b128 v[190:193], v157 offset:49152
	ds_read_b128 v[194:197], v157 offset:50176
	ds_read_b128 v[198:201], v157 offset:51200
	ds_read_b128 v[202:205], v157 offset:52224
	ds_read_b128 v[206:209], v157 offset:53248
	ds_read_b128 v[210:213], v157 offset:54272
	ds_read_b128 v[214:217], v157 offset:55296
	ds_read_b128 v[218:221], v157 offset:56320
	global_load_lds_dwordx4 v[222:223], off
	s_add_i32 m0, s26, 0x2000
	s_add_u32 s24, s24, 0x160080
	v_lshl_add_u64 v[222:223], v[224:225], 0, s[4:5]
	s_addc_u32 s25, s25, 0
	s_add_i32 s26, s60, s28
	global_load_lds_dwordx4 v[222:223], off
	v_lshl_add_u64 v[222:223], s[24:25], 0, v[132:133]
	s_mov_b32 m0, s26
	s_nop 0
	global_load_lds_dwordx4 v[222:223], off
	v_lshl_add_u64 v[222:223], s[24:25], 0, v[136:137]
	s_add_i32 m0, s26, 0x2000
	s_nop 0
	global_load_lds_dwordx4 v[222:223], off
	v_lshl_add_u64 v[222:223], v[226:227], 0, s[4:5]
	s_mov_b32 m0, s38
	s_nop 0
	global_load_lds_dwordx4 v[222:223], off
	v_lshl_add_u64 v[222:223], v[228:229], 0, s[4:5]
	s_mov_b32 m0, s39
	s_nop 0
	global_load_lds_dwordx4 v[222:223], off
	s_waitcnt vmcnt(8)
	s_waitcnt lgkmcnt(0)
	s_barrier
	s_setprio 1
	s_waitcnt lgkmcnt(0)
	v_mfma_f32_16x16x32_bf16 v[60:63], v[158:161], v[190:193], v[60:63]
	v_mfma_f32_16x16x32_bf16 v[56:59], v[166:169], v[190:193], v[56:59]
	v_mfma_f32_16x16x32_bf16 v[52:55], v[158:161], v[198:201], v[52:55]
	v_mfma_f32_16x16x32_bf16 v[48:51], v[166:169], v[198:201], v[48:51]
	v_mfma_f32_16x16x32_bf16 v[36:39], v[158:161], v[206:209], v[36:39]
	v_mfma_f32_16x16x32_bf16 v[32:35], v[166:169], v[206:209], v[32:35]
	v_mfma_f32_16x16x32_bf16 v[20:23], v[158:161], v[214:217], v[20:23]
	v_mfma_f32_16x16x32_bf16 v[16:19], v[166:169], v[214:217], v[16:19]
	v_mfma_f32_16x16x32_bf16 v[60:63], v[162:165], v[194:197], v[60:63]
	v_mfma_f32_16x16x32_bf16 v[56:59], v[170:173], v[194:197], v[56:59]
	v_mfma_f32_16x16x32_bf16 v[52:55], v[162:165], v[202:205], v[52:55]
	v_mfma_f32_16x16x32_bf16 v[48:51], v[170:173], v[202:205], v[48:51]
	v_mfma_f32_16x16x32_bf16 v[36:39], v[162:165], v[210:213], v[36:39]
	v_mfma_f32_16x16x32_bf16 v[32:35], v[170:173], v[210:213], v[32:35]
	v_mfma_f32_16x16x32_bf16 v[20:23], v[162:165], v[218:221], v[20:23]
	v_mfma_f32_16x16x32_bf16 v[16:19], v[170:173], v[218:221], v[16:19]
	s_setprio 0
	s_setprio 1
	v_mfma_f32_16x16x32_bf16 v[44:47], v[174:177], v[190:193], v[44:47]
	v_mfma_f32_16x16x32_bf16 v[40:43], v[182:185], v[190:193], v[40:43]
	v_mfma_f32_16x16x32_bf16 v[28:31], v[174:177], v[198:201], v[28:31]
	v_mfma_f32_16x16x32_bf16 v[24:27], v[182:185], v[198:201], v[24:27]
	v_mfma_f32_16x16x32_bf16 v[12:15], v[174:177], v[206:209], v[12:15]
	v_mfma_f32_16x16x32_bf16 v[8:11], v[182:185], v[206:209], v[8:11]
	v_mfma_f32_16x16x32_bf16 v[4:7], v[174:177], v[214:217], v[4:7]
	v_mfma_f32_16x16x32_bf16 v[0:3], v[182:185], v[214:217], v[0:3]
	v_mfma_f32_16x16x32_bf16 v[44:47], v[178:181], v[194:197], v[44:47]
	v_mfma_f32_16x16x32_bf16 v[40:43], v[186:189], v[194:197], v[40:43]
	v_mfma_f32_16x16x32_bf16 v[28:31], v[178:181], v[202:205], v[28:31]
	v_mfma_f32_16x16x32_bf16 v[24:27], v[186:189], v[202:205], v[24:27]
	s_setprio 2
	s_barrier
	v_mfma_f32_16x16x32_bf16 v[12:15], v[178:181], v[210:213], v[12:15]
	v_mfma_f32_16x16x32_bf16 v[8:11], v[186:189], v[210:213], v[8:11]
	v_mfma_f32_16x16x32_bf16 v[4:7], v[178:181], v[218:221], v[4:7]
	v_mfma_f32_16x16x32_bf16 v[0:3], v[186:189], v[218:221], v[0:3]
	s_setprio 0
	s_add_i32 s58, s58, 2
	s_add_u32 s22, s22, 0x100
	s_addc_u32 s23, s23, 0
	s_add_u32 s56, s56, 0x100
	s_addc_u32 s57, s57, 0
	s_cmpk_gt_u32 s58, 0x55
	s_cbranch_scc0 .LBB0_140
	s_and_b64 vcc, exec, s[8:9]
	s_cbranch_vccz .LBB0_143
	s_barrier

;     __host__ __device__ bool next(int i, Unit& u) const { return (i + I0 < I1) && StaticOrder::next(i + I0, u); }
; #define PG8_STAGE(bufoff, gbase, voff) do { _Pragma("unroll") for (int _i = 0; _i < 2; ++_i) \
;         __builtin_amdgcn_global_load_lds((const unsigned*)((const char*)(gbase) + (voff)[_i]), (PG8_LAS unsigned*)(lds + (bufoff) + ldsw + _i * 8192), 16, 0, 0); } while (0)
; #define PG8_LDA(dst, b, h) do { _Pragma("unroll") for (int m = 0; m < 4; ++m) _Pragma("unroll") for (int k = 0; k < 2; ++k) dst[m][k] = *(const PG8_LAS bf16x8*)(lds + PG8_SA(b, h) + aoff + m * 2048 + k * 1024); } while (0)
; #define PG8_LDB(dst, b, h) do { _Pragma("unroll") for (int n = 0; n < 2; ++n) _Pragma("unroll") for (int k = 0; k < 2; ++k) dst[n][k] = *(const PG8_LAS bf16x8*)(lds + PG8_SB(b, h) + boff + n * 2048 + k * 1024); } while (0)
; #define PG8_WAIT_V(n) asm volatile("s_waitcnt vmcnt(" #n ")" ::: "memory")
; #define PG8_WAIT_L(n) asm volatile("s_waitcnt lgkmcnt(" #n ")" ::: "memory")
; #define PG8_BAR __builtin_amdgcn_s_barrier()
; #define PG8_SCHED __builtin_amdgcn_sched_barrier(0)
; template <class Epi, class Sched, bool ALIGN_EPI = false, bool SP2 = false>
; __device__ __forceinline__ void gemm_phase(PG8_LAS unsigned char* lds, const Gemm g, const Sched& S, const Epi& E) {
;     ...
;         const bool has_next = S.next(ui + 1, nxt);
;         const char* nA = has_next ? (const char*)g.A + (size_t)nxt.pm * tstep : cA; const char* nB = has_next ? (const char*)g.Bt + (size_t)nxt.pn * tstep : cB;
;         for (int t = 0; t < nt; t += 2) {
;             const bool last = (t == nt - 2);
;             const char* a1 = cA + (size_t)(t + 1) * kstep;
;             const char* a2 = last ? nA : cA + (size_t)(t + 2) * kstep; const char* b2 = last ? nB : cB + (size_t)(t + 2) * kstep;
;             const char* a3 = a2 + kstep; const char* b3 = b2 + kstep;
;             if (last && has_next) S.a_ready(nxt);
;             if constexpr (SP2) {
;             PG8_LDB(B0, 0, 0); PG8_LDB(B1, 0, 1); PG8_SCHED; PG8_LDA(At, 0, 0); PG8_STAGE(PG8_SA(1, 1), a1 + hstep, voffA);
;             PG8_WAIT_V(8); PG8_WAIT_L(0); PG8_BAR; PG8_MMA(0, 0, At, B0); PG8_MMA(0, 1, At, B1); PG8_BAR; PG8_SCHED;
;             PG8_LDA(At, 0, 1); PG8_STAGE(PG8_SB(0, 0), b2, voffB); PG8_STAGE(PG8_SB(0, 1), b2 + hstep, voffB); PG8_STAGE(PG8_SA(0, 0), a2, voffA);
.LBB0_165:
	ds_read_b128 v[150:153], v139
	ds_read_b128 v[154:157], v139 offset:1024
	ds_read_b128 v[158:161], v139 offset:2048
	ds_read_b128 v[162:165], v139 offset:3072
	ds_read_b128 v[166:169], v145
	ds_read_b128 v[170:173], v145 offset:1024
	ds_read_b128 v[174:177], v145 offset:2048
	ds_read_b128 v[178:181], v145 offset:3072
	s_add_u32 s12, s8, s10
	s_addc_u32 s13, s9, s11
	s_add_u32 s12, s12, 0x13500100
	s_addc_u32 s13, s13, 0
	s_add_u32 s39, s24, s10
	s_addc_u32 s40, s25, s11
	s_cmpk_eq_i32 s10, 0x1500
	s_cselect_b32 s15, s5, s13
	s_cselect_b32 s14, s4, s12
	s_cselect_b32 s13, s3, s40
	s_cselect_b32 s12, s2, s39
	s_mov_b32 m0, s27
	v_lshl_add_u64 v[214:215], v[140:141], 0, s[10:11]
	ds_read_b128 v[182:185], v146
	ds_read_b128 v[186:189], v146 offset:1024
	ds_read_b128 v[190:193], v146 offset:2048
	ds_read_b128 v[194:197], v146 offset:3072
	ds_read_b128 v[198:201], v146 offset:4096
	ds_read_b128 v[202:205], v146 offset:5120
	ds_read_b128 v[206:209], v146 offset:6144
	ds_read_b128 v[210:213], v146 offset:7168
	global_load_lds_dwordx4 v[214:215], off
	v_lshl_add_u64 v[214:215], v[142:143], 0, s[10:11]
	s_mov_b32 m0, s28
	s_nop 0
	global_load_lds_dwordx4 v[214:215], off
	s_waitcnt vmcnt(8)
	s_waitcnt lgkmcnt(0)
	s_barrier
	s_setprio 1
	s_waitcnt lgkmcnt(0)
	v_mfma_f32_16x16x32_bf16 v[124:127], v[150:153], v[182:185], v[124:127]
	v_mfma_f32_16x16x32_bf16 v[120:123], v[158:161], v[182:185], v[120:123]
	v_mfma_f32_16x16x32_bf16 v[116:119], v[150:153], v[190:193], v[116:119]
	v_mfma_f32_16x16x32_bf16 v[112:115], v[158:161], v[190:193], v[112:115]
	v_mfma_f32_16x16x32_bf16 v[108:111], v[150:153], v[198:201], v[108:111]
	v_mfma_f32_16x16x32_bf16 v[104:107], v[158:161], v[198:201], v[104:107]
	v_mfma_f32_16x16x32_bf16 v[96:99], v[150:153], v[206:209], v[96:99]
	v_mfma_f32_16x16x32_bf16 v[88:91], v[158:161], v[206:209], v[88:91]
	v_mfma_f32_16x16x32_bf16 v[124:127], v[154:157], v[186:189], v[124:127]
	v_mfma_f32_16x16x32_bf16 v[120:123], v[162:165], v[186:189], v[120:123]
	v_mfma_f32_16x16x32_bf16 v[116:119], v[154:157], v[194:197], v[116:119]
	v_mfma_f32_16x16x32_bf16 v[112:115], v[162:165], v[194:197], v[112:115]
	v_mfma_f32_16x16x32_bf16 v[108:111], v[154:157], v[202:205], v[108:111]
	v_mfma_f32_16x16x32_bf16 v[104:107], v[162:165], v[202:205], v[104:107]
	v_mfma_f32_16x16x32_bf16 v[96:99], v[154:157], v[210:213], v[96:99]
	v_mfma_f32_16x16x32_bf16 v[88:91], v[162:165], v[210:213], v[88:91]
	s_setprio 0
	s_setprio 1
	v_mfma_f32_16x16x32_bf16 v[100:103], v[166:169], v[182:185], v[100:103]
	v_mfma_f32_16x16x32_bf16 v[92:95], v[174:177], v[182:185], v[92:95]
	v_mfma_f32_16x16x32_bf16 v[84:87], v[166:169], v[190:193], v[84:87]
	v_mfma_f32_16x16x32_bf16 v[80:83], v[174:177], v[190:193], v[80:83]
	v_mfma_f32_16x16x32_bf16 v[76:79], v[166:169], v[198:201], v[76:79]
	v_mfma_f32_16x16x32_bf16 v[72:75], v[174:177], v[198:201], v[72:75]
	v_mfma_f32_16x16x32_bf16 v[68:71], v[166:169], v[206:209], v[68:71]
	v_mfma_f32_16x16x32_bf16 v[64:67], v[174:177], v[206:209], v[64:67]
	v_mfma_f32_16x16x32_bf16 v[100:103], v[170:173], v[186:189], v[100:103]
	v_mfma_f32_16x16x32_bf16 v[92:95], v[178:181], v[186:189], v[92:95]
	v_mfma_f32_16x16x32_bf16 v[84:87], v[170:173], v[194:197], v[84:87]
	v_mfma_f32_16x16x32_bf16 v[80:83], v[178:181], v[194:197], v[80:83]
	s_setprio 2
	s_barrier
	v_mfma_f32_16x16x32_bf16 v[76:79], v[170:173], v[202:205], v[76:79]
	v_mfma_f32_16x16x32_bf16 v[72:75], v[178:181], v[202:205], v[72:75]
	v_mfma_f32_16x16x32_bf16 v[68:71], v[170:173], v[210:213], v[68:71]
	v_mfma_f32_16x16x32_bf16 v[64:67], v[178:181], v[210:213], v[64:67]
	s_setprio 0
	s_mov_b32 m0, s29
	v_lshl_add_u64 v[214:215], s[12:13], 0, v[132:133]
	s_add_u32 s40, s12, 0x160000
	ds_read_b128 v[182:185], v146 offset:16384
	ds_read_b128 v[186:189], v146 offset:17408
	ds_read_b128 v[190:193], v146 offset:18432
	ds_read_b128 v[194:197], v146 offset:19456
	ds_read_b128 v[198:201], v146 offset:20480
	ds_read_b128 v[202:205], v146 offset:21504
	ds_read_b128 v[206:209], v146 offset:22528
	ds_read_b128 v[210:213], v146 offset:23552
	global_load_lds_dwordx4 v[214:215], off
	v_lshl_add_u64 v[216:217], s[12:13], 0, v[136:137]
	s_mov_b32 m0, s30
	s_addc_u32 s41, s13, 0
	global_load_lds_dwordx4 v[216:217], off
	v_lshl_add_u64 v[218:219], s[40:41], 0, v[132:133]
	s_mov_b32 m0, s31
	v_lshl_add_u64 v[220:221], s[14:15], 0, v[134:135]
	global_load_lds_dwordx4 v[218:219], off
	v_lshl_add_u64 v[218:219], s[40:41], 0, v[136:137]
	s_mov_b32 m0, s34
	s_nop 0
	global_load_lds_dwordx4 v[218:219], off
	v_lshl_add_u64 v[218:219], s[14:15], 0, v[130:131]
	s_mov_b32 m0, s17
	s_nop 0
	global_load_lds_dwordx4 v[218:219], off
	s_mov_b32 m0, s18
	s_nop 0
	global_load_lds_dwordx4 v[220:221], off
	s_waitcnt vmcnt(8)
	s_waitcnt lgkmcnt(0)
	s_barrier
; #define PG8_STAGE(bufoff, gbase, voff) do { _Pragma("unroll") for (int _i = 0; _i < 2; ++_i) \
;         __builtin_amdgcn_global_load_lds((const unsigned*)((const char*)(gbase) + (voff)[_i]), (PG8_LAS unsigned*)(lds + (bufoff) + ldsw + _i * 8192), 16, 0, 0); } while (0)
; #define PG8_LDA(dst, b, h) do { _Pragma("unroll") for (int m = 0; m < 4; ++m) _Pragma("unroll") for (int k = 0; k < 2; ++k) dst[m][k] = *(const PG8_LAS bf16x8*)(lds + PG8_SA(b, h) + aoff + m * 2048 + k * 1024); } while (0)
; #define PG8_LDB(dst, b, h) do { _Pragma("unroll") for (int n = 0; n < 2; ++n) _Pragma("unroll") for (int k = 0; k < 2; ++k) dst[n][k] = *(const PG8_LAS bf16x8*)(lds + PG8_SB(b, h) + boff + n * 2048 + k * 1024); } while (0)
; #define PG8_MMA(ai, bj, At, Bt) do { __builtin_amdgcn_s_setprio(1); _Pragma("unroll") for (int m = 0; m < 4; ++m) _Pragma("unroll") for (int n = 0; n < 2; ++n) _Pragma("unroll") for (int k = 0; k < 2; ++k) \
;         acc[ai][bj][m][n] = __builtin_amdgcn_mfma_f32_16x16x32_bf16(Bt[n][k], At[m][k], acc[ai][bj][m][n], 0, 0, 0); __builtin_amdgcn_s_setprio(0); } while (0)
; #define PG8_WAIT_V(n) asm volatile("s_waitcnt vmcnt(" #n ")" ::: "memory")
; #define PG8_WAIT_L(n) asm volatile("s_waitcnt lgkmcnt(" #n ")" ::: "memory")
; #define PG8_BAR __builtin_amdgcn_s_barrier()
; #define PG8_SCHED __builtin_amdgcn_sched_barrier(0)
; template <class Epi, class Sched, bool ALIGN_EPI = false, bool SP2 = false>
; __device__ __forceinline__ void gemm_phase(PG8_LAS unsigned char* lds, const Gemm g, const Sched& S, const Epi& E) {
;     ...
;             PG8_WAIT_V(8); PG8_WAIT_L(0); PG8_BAR; PG8_MMA(1, 0, At, B0); PG8_MMA(1, 1, At, B1); PG8_BAR; PG8_SCHED;
;             PG8_LDB(B0, 1, 0); PG8_LDB(B1, 1, 1); PG8_SCHED; PG8_LDA(At, 1, 0); PG8_STAGE(PG8_SA(0, 1), a2 + hstep, voffA);
;             PG8_WAIT_V(8); PG8_WAIT_L(0); PG8_BAR; PG8_MMA(0, 0, At, B0); PG8_MMA(0, 1, At, B1); PG8_BAR; PG8_SCHED;
	s_setprio 1
	s_waitcnt lgkmcnt(0)
	v_mfma_f32_16x16x32_bf16 v[60:63], v[150:153], v[182:185], v[60:63]
	v_mfma_f32_16x16x32_bf16 v[56:59], v[158:161], v[182:185], v[56:59]
	v_mfma_f32_16x16x32_bf16 v[52:55], v[150:153], v[190:193], v[52:55]
	v_mfma_f32_16x16x32_bf16 v[48:51], v[158:161], v[190:193], v[48:51]
	v_mfma_f32_16x16x32_bf16 v[44:47], v[150:153], v[198:201], v[44:47]
	v_mfma_f32_16x16x32_bf16 v[40:43], v[158:161], v[198:201], v[40:43]
	v_mfma_f32_16x16x32_bf16 v[32:35], v[150:153], v[206:209], v[32:35]
	v_mfma_f32_16x16x32_bf16 v[24:27], v[158:161], v[206:209], v[24:27]
	v_mfma_f32_16x16x32_bf16 v[60:63], v[154:157], v[186:189], v[60:63]
	v_mfma_f32_16x16x32_bf16 v[56:59], v[162:165], v[186:189], v[56:59]
	v_mfma_f32_16x16x32_bf16 v[52:55], v[154:157], v[194:197], v[52:55]
	v_mfma_f32_16x16x32_bf16 v[48:51], v[162:165], v[194:197], v[48:51]
	v_mfma_f32_16x16x32_bf16 v[44:47], v[154:157], v[202:205], v[44:47]
	v_mfma_f32_16x16x32_bf16 v[40:43], v[162:165], v[202:205], v[40:43]
	v_mfma_f32_16x16x32_bf16 v[32:35], v[154:157], v[210:213], v[32:35]
	v_mfma_f32_16x16x32_bf16 v[24:27], v[162:165], v[210:213], v[24:27]
	s_setprio 0
	s_setprio 1
	v_mfma_f32_16x16x32_bf16 v[36:39], v[166:169], v[182:185], v[36:39]
	v_mfma_f32_16x16x32_bf16 v[28:31], v[174:177], v[182:185], v[28:31]
	v_mfma_f32_16x16x32_bf16 v[20:23], v[166:169], v[190:193], v[20:23]
	v_mfma_f32_16x16x32_bf16 v[16:19], v[174:177], v[190:193], v[16:19]
	v_mfma_f32_16x16x32_bf16 v[12:15], v[166:169], v[198:201], v[12:15]
	v_mfma_f32_16x16x32_bf16 v[8:11], v[174:177], v[198:201], v[8:11]
	v_mfma_f32_16x16x32_bf16 v[4:7], v[166:169], v[206:209], v[4:7]
	v_mfma_f32_16x16x32_bf16 v[0:3], v[174:177], v[206:209], v[0:3]
	v_mfma_f32_16x16x32_bf16 v[36:39], v[170:173], v[186:189], v[36:39]
	v_mfma_f32_16x16x32_bf16 v[28:31], v[178:181], v[186:189], v[28:31]
	v_mfma_f32_16x16x32_bf16 v[20:23], v[170:173], v[194:197], v[20:23]
	v_mfma_f32_16x16x32_bf16 v[16:19], v[178:181], v[194:197], v[16:19]
	s_setprio 2
	s_barrier
	v_mfma_f32_16x16x32_bf16 v[12:15], v[170:173], v[202:205], v[12:15]
	v_mfma_f32_16x16x32_bf16 v[8:11], v[178:181], v[202:205], v[8:11]
	v_mfma_f32_16x16x32_bf16 v[4:7], v[170:173], v[210:213], v[4:7]
	v_mfma_f32_16x16x32_bf16 v[0:3], v[178:181], v[210:213], v[0:3]
	s_setprio 0
	ds_read_b128 v[150:153], v147
	ds_read_b128 v[154:157], v147 offset:1024
	ds_read_b128 v[158:161], v147 offset:2048
	ds_read_b128 v[162:165], v147 offset:3072
	ds_read_b128 v[166:169], v148
	ds_read_b128 v[170:173], v148 offset:1024
	ds_read_b128 v[174:177], v148 offset:2048
	ds_read_b128 v[178:181], v148 offset:3072
	s_add_u32 s14, s14, 0x160000
	s_addc_u32 s15, s15, 0
	s_mov_b32 m0, s19
	v_lshl_add_u64 v[222:223], s[14:15], 0, v[130:131]
	ds_read_b128 v[182:185], v146 offset:32768
	ds_read_b128 v[186:189], v146 offset:33792
	ds_read_b128 v[190:193], v146 offset:34816
	ds_read_b128 v[194:197], v146 offset:35840
	ds_read_b128 v[198:201], v146 offset:36864
	ds_read_b128 v[202:205], v146 offset:37888
	ds_read_b128 v[206:209], v146 offset:38912
	ds_read_b128 v[210:213], v146 offset:39936
	global_load_lds_dwordx4 v[222:223], off
	v_lshl_add_u64 v[222:223], s[14:15], 0, v[134:135]
	s_mov_b32 m0, s20
	s_nop 0
	global_load_lds_dwordx4 v[222:223], off
	s_waitcnt vmcnt(8)
	s_waitcnt lgkmcnt(0)
	s_barrier
	s_setprio 1
	s_waitcnt lgkmcnt(0)
	v_mfma_f32_16x16x32_bf16 v[124:127], v[150:153], v[182:185], v[124:127]
	v_mfma_f32_16x16x32_bf16 v[120:123], v[158:161], v[182:185], v[120:123]
	v_mfma_f32_16x16x32_bf16 v[116:119], v[150:153], v[190:193], v[116:119]
	v_mfma_f32_16x16x32_bf16 v[112:115], v[158:161], v[190:193], v[112:115]
	v_mfma_f32_16x16x32_bf16 v[108:111], v[150:153], v[198:201], v[108:111]
	v_mfma_f32_16x16x32_bf16 v[104:107], v[158:161], v[198:201], v[104:107]
	v_mfma_f32_16x16x32_bf16 v[96:99], v[150:153], v[206:209], v[96:99]
	v_mfma_f32_16x16x32_bf16 v[88:91], v[158:161], v[206:209], v[88:91]
	v_mfma_f32_16x16x32_bf16 v[124:127], v[154:157], v[186:189], v[124:127]
	v_mfma_f32_16x16x32_bf16 v[120:123], v[162:165], v[186:189], v[120:123]
	v_mfma_f32_16x16x32_bf16 v[116:119], v[154:157], v[194:197], v[116:119]
	v_mfma_f32_16x16x32_bf16 v[112:115], v[162:165], v[194:197], v[112:115]
	v_mfma_f32_16x16x32_bf16 v[108:111], v[154:157], v[202:205], v[108:111]
	v_mfma_f32_16x16x32_bf16 v[104:107], v[162:165], v[202:205], v[104:107]
	v_mfma_f32_16x16x32_bf16 v[96:99], v[154:157], v[210:213], v[96:99]
	v_mfma_f32_16x16x32_bf16 v[88:91], v[162:165], v[210:213], v[88:91]
	s_setprio 0
	s_setprio 1
	v_mfma_f32_16x16x32_bf16 v[100:103], v[166:169], v[182:185], v[100:103]
	v_mfma_f32_16x16x32_bf16 v[92:95], v[174:177], v[182:185], v[92:95]
	v_mfma_f32_16x16x32_bf16 v[84:87], v[166:169], v[190:193], v[84:87]
	v_mfma_f32_16x16x32_bf16 v[80:83], v[174:177], v[190:193], v[80:83]
	v_mfma_f32_16x16x32_bf16 v[76:79], v[166:169], v[198:201], v[76:79]
	v_mfma_f32_16x16x32_bf16 v[72:75], v[174:177], v[198:201], v[72:75]
	v_mfma_f32_16x16x32_bf16 v[68:71], v[166:169], v[206:209], v[68:71]
	v_mfma_f32_16x16x32_bf16 v[64:67], v[174:177], v[206:209], v[64:67]
	v_mfma_f32_16x16x32_bf16 v[100:103], v[170:173], v[186:189], v[100:103]
	v_mfma_f32_16x16x32_bf16 v[92:95], v[178:181], v[186:189], v[92:95]
	v_mfma_f32_16x16x32_bf16 v[84:87], v[170:173], v[194:197], v[84:87]
	v_mfma_f32_16x16x32_bf16 v[80:83], v[178:181], v[194:197], v[80:83]
	s_setprio 2
	s_barrier
; #define PG8_STAGE(bufoff, gbase, voff) do { _Pragma("unroll") for (int _i = 0; _i < 2; ++_i) \
;         __builtin_amdgcn_global_load_lds((const unsigned*)((const char*)(gbase) + (voff)[_i]), (PG8_LAS unsigned*)(lds + (bufoff) + ldsw + _i * 8192), 16, 0, 0); } while (0)
; #define PG8_LDA(dst, b, h) do { _Pragma("unroll") for (int m = 0; m < 4; ++m) _Pragma("unroll") for (int k = 0; k < 2; ++k) dst[m][k] = *(const PG8_LAS bf16x8*)(lds + PG8_SA(b, h) + aoff + m * 2048 + k * 1024); } while (0)
; #define PG8_MMA(ai, bj, At, Bt) do { __builtin_amdgcn_s_setprio(1); _Pragma("unroll") for (int m = 0; m < 4; ++m) _Pragma("unroll") for (int n = 0; n < 2; ++n) _Pragma("unroll") for (int k = 0; k < 2; ++k) \
;         acc[ai][bj][m][n] = __builtin_amdgcn_mfma_f32_16x16x32_bf16(Bt[n][k], At[m][k], acc[ai][bj][m][n], 0, 0, 0); __builtin_amdgcn_s_setprio(0); } while (0)
; #define PG8_WAIT_V(n) asm volatile("s_waitcnt vmcnt(" #n ")" ::: "memory")
; #define PG8_WAIT_L(n) asm volatile("s_waitcnt lgkmcnt(" #n ")" ::: "memory")
; #define PG8_BAR __builtin_amdgcn_s_barrier()
; #define PG8_SCHED __builtin_amdgcn_sched_barrier(0)
; template <class Epi, class Sched, bool ALIGN_EPI = false, bool SP2 = false>
; __device__ __forceinline__ void gemm_phase(PG8_LAS unsigned char* lds, const Gemm g, const Sched& S, const Epi& E) {
;     ...
;             PG8_WAIT_V(8); PG8_WAIT_L(0); PG8_BAR; PG8_MMA(0, 0, At, B0); PG8_MMA(0, 1, At, B1); PG8_BAR; PG8_SCHED;
;             PG8_LDA(At, 1, 1); PG8_STAGE(PG8_SB(1, 0), b3, voffB); PG8_STAGE(PG8_SB(1, 1), b3 + hstep, voffB); PG8_STAGE(PG8_SA(1, 0), a3, voffA);
;             PG8_WAIT_V(8); PG8_WAIT_L(0); PG8_BAR; PG8_MMA(1, 0, At, B0); PG8_MMA(1, 1, At, B1); PG8_BAR; PG8_SCHED;
	v_mfma_f32_16x16x32_bf16 v[76:79], v[170:173], v[202:205], v[76:79]
	v_mfma_f32_16x16x32_bf16 v[72:75], v[178:181], v[202:205], v[72:75]
	v_mfma_f32_16x16x32_bf16 v[68:71], v[170:173], v[210:213], v[68:71]
	v_mfma_f32_16x16x32_bf16 v[64:67], v[178:181], v[210:213], v[64:67]
	s_setprio 0
	s_mov_b32 m0, s35
	v_lshl_add_u64 v[214:215], v[214:215], 0, s[6:7]
	s_add_u32 s12, s12, 0x160080
	ds_read_b128 v[182:185], v146 offset:49152
	ds_read_b128 v[186:189], v146 offset:50176
	ds_read_b128 v[190:193], v146 offset:51200
	ds_read_b128 v[194:197], v146 offset:52224
	ds_read_b128 v[198:201], v146 offset:53248
	ds_read_b128 v[202:205], v146 offset:54272
	ds_read_b128 v[206:209], v146 offset:55296
	ds_read_b128 v[210:213], v146 offset:56320
	global_load_lds_dwordx4 v[214:215], off
	v_lshl_add_u64 v[214:215], v[216:217], 0, s[6:7]
	s_mov_b32 m0, s36
	s_addc_u32 s13, s13, 0
	global_load_lds_dwordx4 v[214:215], off
	v_lshl_add_u64 v[214:215], s[12:13], 0, v[132:133]
	s_mov_b32 m0, s37
	s_nop 0
	global_load_lds_dwordx4 v[214:215], off
	v_lshl_add_u64 v[214:215], s[12:13], 0, v[136:137]
	s_mov_b32 m0, s38
	s_nop 0
	global_load_lds_dwordx4 v[214:215], off
	v_lshl_add_u64 v[214:215], v[218:219], 0, s[6:7]
	s_mov_b32 m0, s22
	s_nop 0
	global_load_lds_dwordx4 v[214:215], off
	v_lshl_add_u64 v[214:215], v[220:221], 0, s[6:7]
	s_mov_b32 m0, s23
	s_nop 0
	global_load_lds_dwordx4 v[214:215], off
	s_waitcnt vmcnt(8)
	s_waitcnt lgkmcnt(0)
	s_barrier
	s_setprio 1
	s_waitcnt lgkmcnt(0)
	v_mfma_f32_16x16x32_bf16 v[60:63], v[150:153], v[182:185], v[60:63]
	v_mfma_f32_16x16x32_bf16 v[56:59], v[158:161], v[182:185], v[56:59]
	v_mfma_f32_16x16x32_bf16 v[52:55], v[150:153], v[190:193], v[52:55]
	v_mfma_f32_16x16x32_bf16 v[48:51], v[158:161], v[190:193], v[48:51]
	v_mfma_f32_16x16x32_bf16 v[44:47], v[150:153], v[198:201], v[44:47]
	v_mfma_f32_16x16x32_bf16 v[40:43], v[158:161], v[198:201], v[40:43]
	v_mfma_f32_16x16x32_bf16 v[32:35], v[150:153], v[206:209], v[32:35]
	v_mfma_f32_16x16x32_bf16 v[24:27], v[158:161], v[206:209], v[24:27]
	v_mfma_f32_16x16x32_bf16 v[60:63], v[154:157], v[186:189], v[60:63]
	v_mfma_f32_16x16x32_bf16 v[56:59], v[162:165], v[186:189], v[56:59]
	v_mfma_f32_16x16x32_bf16 v[52:55], v[154:157], v[194:197], v[52:55]
	v_mfma_f32_16x16x32_bf16 v[48:51], v[162:165], v[194:197], v[48:51]
	v_mfma_f32_16x16x32_bf16 v[44:47], v[154:157], v[202:205], v[44:47]
	v_mfma_f32_16x16x32_bf16 v[40:43], v[162:165], v[202:205], v[40:43]
	v_mfma_f32_16x16x32_bf16 v[32:35], v[154:157], v[210:213], v[32:35]
	v_mfma_f32_16x16x32_bf16 v[24:27], v[162:165], v[210:213], v[24:27]
	s_setprio 0
	s_setprio 1
	v_mfma_f32_16x16x32_bf16 v[36:39], v[166:169], v[182:185], v[36:39]
	v_mfma_f32_16x16x32_bf16 v[28:31], v[174:177], v[182:185], v[28:31]
	v_mfma_f32_16x16x32_bf16 v[20:23], v[166:169], v[190:193], v[20:23]
	v_mfma_f32_16x16x32_bf16 v[16:19], v[174:177], v[190:193], v[16:19]
	v_mfma_f32_16x16x32_bf16 v[12:15], v[166:169], v[198:201], v[12:15]
	v_mfma_f32_16x16x32_bf16 v[8:11], v[174:177], v[198:201], v[8:11]
	v_mfma_f32_16x16x32_bf16 v[4:7], v[166:169], v[206:209], v[4:7]
	v_mfma_f32_16x16x32_bf16 v[0:3], v[174:177], v[206:209], v[0:3]
	v_mfma_f32_16x16x32_bf16 v[36:39], v[170:173], v[186:189], v[36:39]
	v_mfma_f32_16x16x32_bf16 v[28:31], v[178:181], v[186:189], v[28:31]
	v_mfma_f32_16x16x32_bf16 v[20:23], v[170:173], v[194:197], v[20:23]
	v_mfma_f32_16x16x32_bf16 v[16:19], v[178:181], v[194:197], v[16:19]
	s_setprio 2
	s_barrier
	v_mfma_f32_16x16x32_bf16 v[12:15], v[170:173], v[202:205], v[12:15]
	v_mfma_f32_16x16x32_bf16 v[8:11], v[178:181], v[202:205], v[8:11]
	v_mfma_f32_16x16x32_bf16 v[4:7], v[170:173], v[210:213], v[4:7]
	v_mfma_f32_16x16x32_bf16 v[0:3], v[178:181], v[210:213], v[0:3]
	s_setprio 0
	s_add_i32 s26, s26, 2
	s_add_u32 s10, s10, 0x100
	s_addc_u32 s11, s11, 0
	s_cmp_gt_u32 s26, 41
	s_cbranch_scc0 .LBB0_165
	s_cmpk_lt_u32 s16, 0x100
	s_cbranch_scc0 .LBB0_168
	s_barrier

;     __host__ __device__ bool next(int i, Unit& u) const { return (i + I0 < I1) && StaticOrder::next(i + I0, u); }
; #define PG8_STAGE(bufoff, gbase, voff) do { _Pragma("unroll") for (int _i = 0; _i < 2; ++_i) \
;         __builtin_amdgcn_global_load_lds((const unsigned*)((const char*)(gbase) + (voff)[_i]), (PG8_LAS unsigned*)(lds + (bufoff) + ldsw + _i * 8192), 16, 0, 0); } while (0)
; #define PG8_LDA(dst, b, h) do { _Pragma("unroll") for (int m = 0; m < 4; ++m) _Pragma("unroll") for (int k = 0; k < 2; ++k) dst[m][k] = *(const PG8_LAS bf16x8*)(lds + PG8_SA(b, h) + aoff + m * 2048 + k * 1024); } while (0)
; #define PG8_LDB(dst, b, h) do { _Pragma("unroll") for (int n = 0; n < 2; ++n) _Pragma("unroll") for (int k = 0; k < 2; ++k) dst[n][k] = *(const PG8_LAS bf16x8*)(lds + PG8_SB(b, h) + boff + n * 2048 + k * 1024); } while (0)
; #define PG8_WAIT_V(n) asm volatile("s_waitcnt vmcnt(" #n ")" ::: "memory")
; #define PG8_WAIT_L(n) asm volatile("s_waitcnt lgkmcnt(" #n ")" ::: "memory")
; #define PG8_BAR __builtin_amdgcn_s_barrier()
; #define PG8_SCHED __builtin_amdgcn_sched_barrier(0)
; template <class Epi, class Sched, bool ALIGN_EPI = false, bool SP2 = false>
; __device__ __forceinline__ void gemm_phase(PG8_LAS unsigned char* lds, const Gemm g, const Sched& S, const Epi& E) {
;     ...
;         const bool has_next = S.next(ui + 1, nxt);
;         const char* nA = has_next ? (const char*)g.A + (size_t)nxt.pm * tstep : cA; const char* nB = has_next ? (const char*)g.Bt + (size_t)nxt.pn * tstep : cB;
;         for (int t = 0; t < nt; t += 2) {
;             const bool last = (t == nt - 2);
;             const char* a1 = cA + (size_t)(t + 1) * kstep;
;             const char* a2 = last ? nA : cA + (size_t)(t + 2) * kstep; const char* b2 = last ? nB : cB + (size_t)(t + 2) * kstep;
;             const char* a3 = a2 + kstep; const char* b3 = b2 + kstep;
;             if (last && has_next) S.a_ready(nxt);
;             if constexpr (SP2) {
;             PG8_LDB(B0, 0, 0); PG8_LDB(B1, 0, 1); PG8_SCHED; PG8_LDA(At, 0, 0); PG8_STAGE(PG8_SA(1, 1), a1 + hstep, voffA);
;             PG8_WAIT_V(8); PG8_WAIT_L(0); PG8_BAR; PG8_MMA(0, 0, At, B0); PG8_MMA(0, 1, At, B1); PG8_BAR; PG8_SCHED;
;             PG8_LDA(At, 0, 1); PG8_STAGE(PG8_SB(0, 0), b2, voffB); PG8_STAGE(PG8_SB(0, 1), b2 + hstep, voffB); PG8_STAGE(PG8_SA(0, 0), a2, voffA);
.LBB0_356:
	ds_read_b128 v[152:155], v149
	ds_read_b128 v[156:159], v149 offset:1024
	ds_read_b128 v[160:163], v149 offset:2048
	ds_read_b128 v[164:167], v149 offset:3072
	ds_read_b128 v[168:171], v150
	ds_read_b128 v[172:175], v150 offset:1024
	ds_read_b128 v[176:179], v150 offset:2048
	ds_read_b128 v[180:183], v150 offset:3072
	s_add_u32 s22, s20, 0xfff80080
	s_addc_u32 s23, s21, -1
	s_cmp_eq_u32 s49, 28
	s_cselect_b32 s25, s15, s23
	s_cselect_b32 s24, s43, s22
	s_cselect_b32 s23, s13, s48
	s_cselect_b32 s22, s44, s45
	v_lshl_add_u64 v[216:217], s[20:21], 0, v[138:139]
	s_add_i32 m0, s11, 0xc000
	ds_read_b128 v[184:187], v151
	ds_read_b128 v[188:191], v151 offset:1024
	ds_read_b128 v[192:195], v151 offset:2048
	ds_read_b128 v[196:199], v151 offset:3072
	ds_read_b128 v[200:203], v151 offset:4096
	ds_read_b128 v[204:207], v151 offset:5120
	ds_read_b128 v[208:211], v151 offset:6144
	ds_read_b128 v[212:215], v151 offset:7168
	global_load_lds_dwordx4 v[216:217], off
	v_lshl_add_u64 v[216:217], s[20:21], 0, v[140:141]
	s_add_i32 m0, s11, 0xe000
	s_nop 0
	global_load_lds_dwordx4 v[216:217], off
	s_waitcnt vmcnt(8)
	s_waitcnt lgkmcnt(0)
	s_barrier
	s_setprio 1
	s_waitcnt lgkmcnt(0)
	v_mfma_f32_16x16x32_bf16 v[124:127], v[152:155], v[184:187], v[124:127]
	v_mfma_f32_16x16x32_bf16 v[120:123], v[160:163], v[184:187], v[120:123]
	v_mfma_f32_16x16x32_bf16 v[116:119], v[152:155], v[192:195], v[116:119]
	v_mfma_f32_16x16x32_bf16 v[112:115], v[160:163], v[192:195], v[112:115]
	v_mfma_f32_16x16x32_bf16 v[100:103], v[152:155], v[200:203], v[100:103]
	v_mfma_f32_16x16x32_bf16 v[96:99], v[160:163], v[200:203], v[96:99]
	v_mfma_f32_16x16x32_bf16 v[84:87], v[152:155], v[208:211], v[84:87]
	v_mfma_f32_16x16x32_bf16 v[80:83], v[160:163], v[208:211], v[80:83]
	v_mfma_f32_16x16x32_bf16 v[124:127], v[156:159], v[188:191], v[124:127]
	v_mfma_f32_16x16x32_bf16 v[120:123], v[164:167], v[188:191], v[120:123]
	v_mfma_f32_16x16x32_bf16 v[116:119], v[156:159], v[196:199], v[116:119]
	v_mfma_f32_16x16x32_bf16 v[112:115], v[164:167], v[196:199], v[112:115]
	v_mfma_f32_16x16x32_bf16 v[100:103], v[156:159], v[204:207], v[100:103]
	v_mfma_f32_16x16x32_bf16 v[96:99], v[164:167], v[204:207], v[96:99]
	v_mfma_f32_16x16x32_bf16 v[84:87], v[156:159], v[212:215], v[84:87]
	v_mfma_f32_16x16x32_bf16 v[80:83], v[164:167], v[212:215], v[80:83]
	s_setprio 0
	s_setprio 1
	v_mfma_f32_16x16x32_bf16 v[108:111], v[168:171], v[184:187], v[108:111]
	v_mfma_f32_16x16x32_bf16 v[104:107], v[176:179], v[184:187], v[104:107]
	v_mfma_f32_16x16x32_bf16 v[92:95], v[168:171], v[192:195], v[92:95]
	v_mfma_f32_16x16x32_bf16 v[88:91], v[176:179], v[192:195], v[88:91]
	v_mfma_f32_16x16x32_bf16 v[76:79], v[168:171], v[200:203], v[76:79]
	v_mfma_f32_16x16x32_bf16 v[72:75], v[176:179], v[200:203], v[72:75]
	v_mfma_f32_16x16x32_bf16 v[68:71], v[168:171], v[208:211], v[68:71]
	v_mfma_f32_16x16x32_bf16 v[64:67], v[176:179], v[208:211], v[64:67]
	v_mfma_f32_16x16x32_bf16 v[108:111], v[172:175], v[188:191], v[108:111]
	v_mfma_f32_16x16x32_bf16 v[104:107], v[180:183], v[188:191], v[104:107]
	v_mfma_f32_16x16x32_bf16 v[92:95], v[172:175], v[196:199], v[92:95]
	v_mfma_f32_16x16x32_bf16 v[88:91], v[180:183], v[196:199], v[88:91]
	s_setprio 2
	s_barrier
	v_mfma_f32_16x16x32_bf16 v[76:79], v[172:175], v[204:207], v[76:79]
	v_mfma_f32_16x16x32_bf16 v[72:75], v[180:183], v[204:207], v[72:75]
	v_mfma_f32_16x16x32_bf16 v[68:71], v[172:175], v[212:215], v[68:71]
	v_mfma_f32_16x16x32_bf16 v[64:67], v[180:183], v[212:215], v[64:67]
	s_setprio 0
	s_add_i32 s50, s39, s26
	v_lshl_add_u64 v[216:217], s[22:23], 0, v[134:135]
	s_mov_b32 m0, s50
	ds_read_b128 v[184:187], v151 offset:16384
	ds_read_b128 v[188:191], v151 offset:17408
	ds_read_b128 v[192:195], v151 offset:18432
	ds_read_b128 v[196:199], v151 offset:19456
	ds_read_b128 v[200:203], v151 offset:20480
	ds_read_b128 v[204:207], v151 offset:21504
	ds_read_b128 v[208:211], v151 offset:22528
	ds_read_b128 v[212:215], v151 offset:23552
	global_load_lds_dwordx4 v[216:217], off
	s_add_i32 m0, s50, 0x2000
	s_add_u32 s50, s22, 0x80000
	v_lshl_add_u64 v[218:219], s[22:23], 0, v[130:131]
	s_addc_u32 s51, s23, 0
	s_add_i32 s52, s40, s26
	global_load_lds_dwordx4 v[218:219], off
	v_lshl_add_u64 v[220:221], s[50:51], 0, v[134:135]
	s_mov_b32 m0, s52
	v_lshl_add_u64 v[222:223], s[24:25], 0, v[132:133]
	global_load_lds_dwordx4 v[220:221], off
	v_lshl_add_u64 v[220:221], s[50:51], 0, v[130:131]
	s_add_i32 m0, s52, 0x2000
	s_nop 0
	global_load_lds_dwordx4 v[220:221], off
	v_lshl_add_u64 v[220:221], s[24:25], 0, v[136:137]
	s_mov_b32 m0, s11
	s_nop 0
	global_load_lds_dwordx4 v[220:221], off
	s_mov_b32 m0, s29
	s_nop 0
	global_load_lds_dwordx4 v[222:223], off
	s_waitcnt vmcnt(8)
	s_waitcnt lgkmcnt(0)
	s_barrier
; #define PG8_STAGE(bufoff, gbase, voff) do { _Pragma("unroll") for (int _i = 0; _i < 2; ++_i) \
;         __builtin_amdgcn_global_load_lds((const unsigned*)((const char*)(gbase) + (voff)[_i]), (PG8_LAS unsigned*)(lds + (bufoff) + ldsw + _i * 8192), 16, 0, 0); } while (0)
; #define PG8_LDA(dst, b, h) do { _Pragma("unroll") for (int m = 0; m < 4; ++m) _Pragma("unroll") for (int k = 0; k < 2; ++k) dst[m][k] = *(const PG8_LAS bf16x8*)(lds + PG8_SA(b, h) + aoff + m * 2048 + k * 1024); } while (0)
; #define PG8_LDB(dst, b, h) do { _Pragma("unroll") for (int n = 0; n < 2; ++n) _Pragma("unroll") for (int k = 0; k < 2; ++k) dst[n][k] = *(const PG8_LAS bf16x8*)(lds + PG8_SB(b, h) + boff + n * 2048 + k * 1024); } while (0)
; #define PG8_MMA(ai, bj, At, Bt) do { __builtin_amdgcn_s_setprio(1); _Pragma("unroll") for (int m = 0; m < 4; ++m) _Pragma("unroll") for (int n = 0; n < 2; ++n) _Pragma("unroll") for (int k = 0; k < 2; ++k) \
;         acc[ai][bj][m][n] = __builtin_amdgcn_mfma_f32_16x16x32_bf16(Bt[n][k], At[m][k], acc[ai][bj][m][n], 0, 0, 0); __builtin_amdgcn_s_setprio(0); } while (0)
; #define PG8_WAIT_V(n) asm volatile("s_waitcnt vmcnt(" #n ")" ::: "memory")
; #define PG8_WAIT_L(n) asm volatile("s_waitcnt lgkmcnt(" #n ")" ::: "memory")
; #define PG8_BAR __builtin_amdgcn_s_barrier()
; #define PG8_SCHED __builtin_amdgcn_sched_barrier(0)
; template <class Epi, class Sched, bool ALIGN_EPI = false, bool SP2 = false>
; __device__ __forceinline__ void gemm_phase(PG8_LAS unsigned char* lds, const Gemm g, const Sched& S, const Epi& E) {
;     ...
;             PG8_WAIT_V(8); PG8_WAIT_L(0); PG8_BAR; PG8_MMA(1, 0, At, B0); PG8_MMA(1, 1, At, B1); PG8_BAR; PG8_SCHED;
;             PG8_LDB(B0, 1, 0); PG8_LDB(B1, 1, 1); PG8_SCHED; PG8_LDA(At, 1, 0); PG8_STAGE(PG8_SA(0, 1), a2 + hstep, voffA);
;             PG8_WAIT_V(8); PG8_WAIT_L(0); PG8_BAR; PG8_MMA(0, 0, At, B0); PG8_MMA(0, 1, At, B1); PG8_BAR; PG8_SCHED;
	s_setprio 1
	s_waitcnt lgkmcnt(0)
	v_mfma_f32_16x16x32_bf16 v[60:63], v[152:155], v[184:187], v[60:63]
	v_mfma_f32_16x16x32_bf16 v[56:59], v[160:163], v[184:187], v[56:59]
	v_mfma_f32_16x16x32_bf16 v[52:55], v[152:155], v[192:195], v[52:55]
	v_mfma_f32_16x16x32_bf16 v[48:51], v[160:163], v[192:195], v[48:51]
	v_mfma_f32_16x16x32_bf16 v[36:39], v[152:155], v[200:203], v[36:39]
	v_mfma_f32_16x16x32_bf16 v[32:35], v[160:163], v[200:203], v[32:35]
	v_mfma_f32_16x16x32_bf16 v[20:23], v[152:155], v[208:211], v[20:23]
	v_mfma_f32_16x16x32_bf16 v[16:19], v[160:163], v[208:211], v[16:19]
	v_mfma_f32_16x16x32_bf16 v[60:63], v[156:159], v[188:191], v[60:63]
	v_mfma_f32_16x16x32_bf16 v[56:59], v[164:167], v[188:191], v[56:59]
	v_mfma_f32_16x16x32_bf16 v[52:55], v[156:159], v[196:199], v[52:55]
	v_mfma_f32_16x16x32_bf16 v[48:51], v[164:167], v[196:199], v[48:51]
	v_mfma_f32_16x16x32_bf16 v[36:39], v[156:159], v[204:207], v[36:39]
	v_mfma_f32_16x16x32_bf16 v[32:35], v[164:167], v[204:207], v[32:35]
	v_mfma_f32_16x16x32_bf16 v[20:23], v[156:159], v[212:215], v[20:23]
	v_mfma_f32_16x16x32_bf16 v[16:19], v[164:167], v[212:215], v[16:19]
	s_setprio 0
	s_setprio 1
	v_mfma_f32_16x16x32_bf16 v[44:47], v[168:171], v[184:187], v[44:47]
	v_mfma_f32_16x16x32_bf16 v[40:43], v[176:179], v[184:187], v[40:43]
	v_mfma_f32_16x16x32_bf16 v[28:31], v[168:171], v[192:195], v[28:31]
	v_mfma_f32_16x16x32_bf16 v[24:27], v[176:179], v[192:195], v[24:27]
	v_mfma_f32_16x16x32_bf16 v[12:15], v[168:171], v[200:203], v[12:15]
	v_mfma_f32_16x16x32_bf16 v[8:11], v[176:179], v[200:203], v[8:11]
	v_mfma_f32_16x16x32_bf16 v[4:7], v[168:171], v[208:211], v[4:7]
	v_mfma_f32_16x16x32_bf16 v[0:3], v[176:179], v[208:211], v[0:3]
	v_mfma_f32_16x16x32_bf16 v[44:47], v[172:175], v[188:191], v[44:47]
	v_mfma_f32_16x16x32_bf16 v[40:43], v[180:183], v[188:191], v[40:43]
	v_mfma_f32_16x16x32_bf16 v[28:31], v[172:175], v[196:199], v[28:31]
	v_mfma_f32_16x16x32_bf16 v[24:27], v[180:183], v[196:199], v[24:27]
	s_setprio 2
	s_barrier
	v_mfma_f32_16x16x32_bf16 v[12:15], v[172:175], v[204:207], v[12:15]
	v_mfma_f32_16x16x32_bf16 v[8:11], v[180:183], v[204:207], v[8:11]
	v_mfma_f32_16x16x32_bf16 v[4:7], v[172:175], v[212:215], v[4:7]
	v_mfma_f32_16x16x32_bf16 v[0:3], v[180:183], v[212:215], v[0:3]
	s_setprio 0
	s_add_i32 s50, 0, 0x18000
	s_add_i32 s51, 0, 0x1c000
	v_add_u32_e32 v164, s50, v147
	v_add_u32_e32 v180, s51, v147
	ds_read_b128 v[152:155], v164
	ds_read_b128 v[156:159], v164 offset:1024
	ds_read_b128 v[160:163], v164 offset:2048
	ds_read_b128 v[164:167], v164 offset:3072
	ds_read_b128 v[168:171], v180
	ds_read_b128 v[172:175], v180 offset:1024
	ds_read_b128 v[176:179], v180 offset:2048
	ds_read_b128 v[180:183], v180 offset:3072
	s_add_u32 s24, s24, 0x80000
	s_addc_u32 s25, s25, 0
	s_mov_b32 m0, s30
	v_lshl_add_u64 v[224:225], s[24:25], 0, v[136:137]
	ds_read_b128 v[184:187], v151 offset:32768
	ds_read_b128 v[188:191], v151 offset:33792
	ds_read_b128 v[192:195], v151 offset:34816
	ds_read_b128 v[196:199], v151 offset:35840
	ds_read_b128 v[200:203], v151 offset:36864
	ds_read_b128 v[204:207], v151 offset:37888
	ds_read_b128 v[208:211], v151 offset:38912
	ds_read_b128 v[212:215], v151 offset:39936
	global_load_lds_dwordx4 v[224:225], off
	v_lshl_add_u64 v[224:225], s[24:25], 0, v[132:133]
	s_mov_b32 m0, s31
	s_nop 0
	global_load_lds_dwordx4 v[224:225], off
	s_waitcnt vmcnt(8)
	s_waitcnt lgkmcnt(0)
	s_barrier
	s_setprio 1
	s_waitcnt lgkmcnt(0)
	v_mfma_f32_16x16x32_bf16 v[124:127], v[152:155], v[184:187], v[124:127]
	v_mfma_f32_16x16x32_bf16 v[120:123], v[160:163], v[184:187], v[120:123]
	v_mfma_f32_16x16x32_bf16 v[116:119], v[152:155], v[192:195], v[116:119]
	v_mfma_f32_16x16x32_bf16 v[112:115], v[160:163], v[192:195], v[112:115]
	v_mfma_f32_16x16x32_bf16 v[100:103], v[152:155], v[200:203], v[100:103]
	v_mfma_f32_16x16x32_bf16 v[96:99], v[160:163], v[200:203], v[96:99]
	v_mfma_f32_16x16x32_bf16 v[84:87], v[152:155], v[208:211], v[84:87]
	v_mfma_f32_16x16x32_bf16 v[80:83], v[160:163], v[208:211], v[80:83]
	v_mfma_f32_16x16x32_bf16 v[124:127], v[156:159], v[188:191], v[124:127]
	v_mfma_f32_16x16x32_bf16 v[120:123], v[164:167], v[188:191], v[120:123]
	v_mfma_f32_16x16x32_bf16 v[116:119], v[156:159], v[196:199], v[116:119]
	v_mfma_f32_16x16x32_bf16 v[112:115], v[164:167], v[196:199], v[112:115]
	v_mfma_f32_16x16x32_bf16 v[100:103], v[156:159], v[204:207], v[100:103]
	v_mfma_f32_16x16x32_bf16 v[96:99], v[164:167], v[204:207], v[96:99]
	v_mfma_f32_16x16x32_bf16 v[84:87], v[156:159], v[212:215], v[84:87]
	v_mfma_f32_16x16x32_bf16 v[80:83], v[164:167], v[212:215], v[80:83]
	s_setprio 0
	s_setprio 1
	v_mfma_f32_16x16x32_bf16 v[108:111], v[168:171], v[184:187], v[108:111]
	v_mfma_f32_16x16x32_bf16 v[104:107], v[176:179], v[184:187], v[104:107]
	v_mfma_f32_16x16x32_bf16 v[92:95], v[168:171], v[192:195], v[92:95]
	v_mfma_f32_16x16x32_bf16 v[88:91], v[176:179], v[192:195], v[88:91]
	v_mfma_f32_16x16x32_bf16 v[76:79], v[168:171], v[200:203], v[76:79]
	v_mfma_f32_16x16x32_bf16 v[72:75], v[176:179], v[200:203], v[72:75]
	v_mfma_f32_16x16x32_bf16 v[68:71], v[168:171], v[208:211], v[68:71]
	v_mfma_f32_16x16x32_bf16 v[64:67], v[176:179], v[208:211], v[64:67]
	v_mfma_f32_16x16x32_bf16 v[108:111], v[172:175], v[188:191], v[108:111]
	v_mfma_f32_16x16x32_bf16 v[104:107], v[180:183], v[188:191], v[104:107]
	v_mfma_f32_16x16x32_bf16 v[92:95], v[172:175], v[196:199], v[92:95]
	v_mfma_f32_16x16x32_bf16 v[88:91], v[180:183], v[196:199], v[88:91]
	s_setprio 2
	s_barrier
; #define PG8_STAGE(bufoff, gbase, voff) do { _Pragma("unroll") for (int _i = 0; _i < 2; ++_i) \
;         __builtin_amdgcn_global_load_lds((const unsigned*)((const char*)(gbase) + (voff)[_i]), (PG8_LAS unsigned*)(lds + (bufoff) + ldsw + _i * 8192), 16, 0, 0); } while (0)
; #define PG8_LDA(dst, b, h) do { _Pragma("unroll") for (int m = 0; m < 4; ++m) _Pragma("unroll") for (int k = 0; k < 2; ++k) dst[m][k] = *(const PG8_LAS bf16x8*)(lds + PG8_SA(b, h) + aoff + m * 2048 + k * 1024); } while (0)
; #define PG8_MMA(ai, bj, At, Bt) do { __builtin_amdgcn_s_setprio(1); _Pragma("unroll") for (int m = 0; m < 4; ++m) _Pragma("unroll") for (int n = 0; n < 2; ++n) _Pragma("unroll") for (int k = 0; k < 2; ++k) \
;         acc[ai][bj][m][n] = __builtin_amdgcn_mfma_f32_16x16x32_bf16(Bt[n][k], At[m][k], acc[ai][bj][m][n], 0, 0, 0); __builtin_amdgcn_s_setprio(0); } while (0)
; #define PG8_WAIT_V(n) asm volatile("s_waitcnt vmcnt(" #n ")" ::: "memory")
; #define PG8_WAIT_L(n) asm volatile("s_waitcnt lgkmcnt(" #n ")" ::: "memory")
; #define PG8_BAR __builtin_amdgcn_s_barrier()
; #define PG8_SCHED __builtin_amdgcn_sched_barrier(0)
; template <class Epi, class Sched, bool ALIGN_EPI = false, bool SP2 = false>
; __device__ __forceinline__ void gemm_phase(PG8_LAS unsigned char* lds, const Gemm g, const Sched& S, const Epi& E) {
;     ...
;             PG8_WAIT_V(8); PG8_WAIT_L(0); PG8_BAR; PG8_MMA(0, 0, At, B0); PG8_MMA(0, 1, At, B1); PG8_BAR; PG8_SCHED;
;             PG8_LDA(At, 1, 1); PG8_STAGE(PG8_SB(1, 0), b3, voffB); PG8_STAGE(PG8_SB(1, 1), b3 + hstep, voffB); PG8_STAGE(PG8_SA(1, 0), a3, voffA);
;             PG8_WAIT_V(8); PG8_WAIT_L(0); PG8_BAR; PG8_MMA(1, 0, At, B0); PG8_MMA(1, 1, At, B1); PG8_BAR; PG8_SCHED;
	v_mfma_f32_16x16x32_bf16 v[76:79], v[172:175], v[204:207], v[76:79]
	v_mfma_f32_16x16x32_bf16 v[72:75], v[180:183], v[204:207], v[72:75]
	v_mfma_f32_16x16x32_bf16 v[68:71], v[172:175], v[212:215], v[68:71]
	v_mfma_f32_16x16x32_bf16 v[64:67], v[180:183], v[212:215], v[64:67]
	s_setprio 0
	s_add_i32 s24, s50, s26
	v_lshl_add_u64 v[216:217], v[216:217], 0, s[4:5]
	s_mov_b32 m0, s24
	ds_read_b128 v[184:187], v151 offset:49152
	ds_read_b128 v[188:191], v151 offset:50176
	ds_read_b128 v[192:195], v151 offset:51200
	ds_read_b128 v[196:199], v151 offset:52224
	ds_read_b128 v[200:203], v151 offset:53248
	ds_read_b128 v[204:207], v151 offset:54272
	ds_read_b128 v[208:211], v151 offset:55296
	ds_read_b128 v[212:215], v151 offset:56320
	global_load_lds_dwordx4 v[216:217], off
	s_add_i32 m0, s24, 0x2000
	s_add_u32 s22, s22, 0x80080
	v_lshl_add_u64 v[216:217], v[218:219], 0, s[4:5]
	s_addc_u32 s23, s23, 0
	s_add_i32 s24, s51, s26
	global_load_lds_dwordx4 v[216:217], off
	v_lshl_add_u64 v[216:217], s[22:23], 0, v[134:135]
	s_mov_b32 m0, s24
	s_nop 0
	global_load_lds_dwordx4 v[216:217], off
	v_lshl_add_u64 v[216:217], s[22:23], 0, v[130:131]
	s_add_i32 m0, s24, 0x2000
	s_nop 0
	global_load_lds_dwordx4 v[216:217], off
	v_lshl_add_u64 v[216:217], v[220:221], 0, s[4:5]
	s_mov_b32 m0, s35
	s_nop 0
	global_load_lds_dwordx4 v[216:217], off
	v_lshl_add_u64 v[216:217], v[222:223], 0, s[4:5]
	s_mov_b32 m0, s36
	s_nop 0
	global_load_lds_dwordx4 v[216:217], off
	s_waitcnt vmcnt(8)
	s_waitcnt lgkmcnt(0)
	s_barrier
	s_setprio 1
	s_waitcnt lgkmcnt(0)
	v_mfma_f32_16x16x32_bf16 v[60:63], v[152:155], v[184:187], v[60:63]
	v_mfma_f32_16x16x32_bf16 v[56:59], v[160:163], v[184:187], v[56:59]
	v_mfma_f32_16x16x32_bf16 v[52:55], v[152:155], v[192:195], v[52:55]
	v_mfma_f32_16x16x32_bf16 v[48:51], v[160:163], v[192:195], v[48:51]
	v_mfma_f32_16x16x32_bf16 v[36:39], v[152:155], v[200:203], v[36:39]
	v_mfma_f32_16x16x32_bf16 v[32:35], v[160:163], v[200:203], v[32:35]
	v_mfma_f32_16x16x32_bf16 v[20:23], v[152:155], v[208:211], v[20:23]
	v_mfma_f32_16x16x32_bf16 v[16:19], v[160:163], v[208:211], v[16:19]
	v_mfma_f32_16x16x32_bf16 v[60:63], v[156:159], v[188:191], v[60:63]
	v_mfma_f32_16x16x32_bf16 v[56:59], v[164:167], v[188:191], v[56:59]
	v_mfma_f32_16x16x32_bf16 v[52:55], v[156:159], v[196:199], v[52:55]
	v_mfma_f32_16x16x32_bf16 v[48:51], v[164:167], v[196:199], v[48:51]
	v_mfma_f32_16x16x32_bf16 v[36:39], v[156:159], v[204:207], v[36:39]
	v_mfma_f32_16x16x32_bf16 v[32:35], v[164:167], v[204:207], v[32:35]
	v_mfma_f32_16x16x32_bf16 v[20:23], v[156:159], v[212:215], v[20:23]
	v_mfma_f32_16x16x32_bf16 v[16:19], v[164:167], v[212:215], v[16:19]
	s_setprio 0
	s_setprio 1
	v_mfma_f32_16x16x32_bf16 v[44:47], v[168:171], v[184:187], v[44:47]
	v_mfma_f32_16x16x32_bf16 v[40:43], v[176:179], v[184:187], v[40:43]
	v_mfma_f32_16x16x32_bf16 v[28:31], v[168:171], v[192:195], v[28:31]
	v_mfma_f32_16x16x32_bf16 v[24:27], v[176:179], v[192:195], v[24:27]
	v_mfma_f32_16x16x32_bf16 v[12:15], v[168:171], v[200:203], v[12:15]
	v_mfma_f32_16x16x32_bf16 v[8:11], v[176:179], v[200:203], v[8:11]
	v_mfma_f32_16x16x32_bf16 v[4:7], v[168:171], v[208:211], v[4:7]
	v_mfma_f32_16x16x32_bf16 v[0:3], v[176:179], v[208:211], v[0:3]
	v_mfma_f32_16x16x32_bf16 v[44:47], v[172:175], v[188:191], v[44:47]
	v_mfma_f32_16x16x32_bf16 v[40:43], v[180:183], v[188:191], v[40:43]
	v_mfma_f32_16x16x32_bf16 v[28:31], v[172:175], v[196:199], v[28:31]
	v_mfma_f32_16x16x32_bf16 v[24:27], v[180:183], v[196:199], v[24:27]
	s_setprio 2
	s_barrier
	v_mfma_f32_16x16x32_bf16 v[12:15], v[172:175], v[204:207], v[12:15]
	v_mfma_f32_16x16x32_bf16 v[8:11], v[180:183], v[204:207], v[8:11]
	v_mfma_f32_16x16x32_bf16 v[4:7], v[172:175], v[212:215], v[4:7]
	v_mfma_f32_16x16x32_bf16 v[0:3], v[180:183], v[212:215], v[0:3]
	s_setprio 0
	s_add_i32 s49, s49, 2
	s_add_u32 s20, s20, 0x100
	s_addc_u32 s21, s21, 0
	s_add_u32 s45, s45, 0x100
	s_addc_u32 s48, s48, 0
	s_cmp_gt_u32 s49, 29
	s_cbranch_scc0 .LBB0_356
	s_and_b64 vcc, exec, s[8:9]
	s_cbranch_vccz .LBB0_359
	s_barrier

; #define LAS __attribute__((address_space(3)))
; __device__ __forceinline__ void ch_issue(const unsigned char* Rl, LAS unsigned char* dst, int wave) {
;     __builtin_amdgcn_global_load_lds((const unsigned*)(Rl + wave * 1024), (LAS unsigned*)(dst + wave * 1024), 16, 0, 0);
;     __builtin_amdgcn_global_load_lds((const unsigned*)(Rl + (wave + 8) * 1024), (LAS unsigned*)(dst + (wave + 8) * 1024), 16, 0, 0);
;     __builtin_amdgcn_global_load_lds((const unsigned*)(Rl + (wave + 16) * 1024), (LAS unsigned*)(dst + (wave + 16) * 1024), 16, 0, 0);
;     if (wave < 3) __builtin_amdgcn_global_load_lds((const unsigned*)(Rl + (wave + 24) * 1024), (LAS unsigned*)(dst + (wave + 24) * 1024), 16, 0, 0);
; }
; __device__ __forceinline__ void hgrn_chain(const unsigned char* REC, const float* s0, float* sout, bf16_t* MIX,
;                                            int cidx0, int nchunks, int h, int vhalf, LAS unsigned char* lds, int wave, int lane) {
;     ...
;     for (int c = 0; c < nchunks; ++c) {
;         ch_issue(Ri, lds + islot * CH_SLOT, wave); Ri = Ri < Rlast ? Ri + 8 * REC_STRIDE : Rlast;
;         islot = islot == CH_NS - 1 ? 0 : islot + 1;
;         const LAS unsigned char* R = lds + slot * CH_SLOT;
;         slot = slot == CH_NS - 1 ? 0 : slot + 1;
;         if (comp) {
.LBB0_605:
	s_and_b64 vcc, exec, s[88:89]
	s_cbranch_vccnz .Lch_comp_new
	s_mul_i32 s8, s15, 0x6c00
	s_add_i32 s8, s33, s8
	v_lshl_add_u64 v[32:33], v[44:45], 0, s[96:97]
	s_mov_b32 m0, s8
	s_and_b64 vcc, exec, s[6:7]
	global_load_lds_dwordx4 v[32:33], off
	v_lshl_add_u64 v[32:33], v[44:45], 0, s[0:1]
	s_add_i32 m0, s8, 0x2000
	s_nop 0
	global_load_lds_dwordx4 v[32:33], off
	v_lshl_add_u64 v[32:33], v[44:45], 0, s[4:5]
	s_add_i32 m0, s8, 0x4000
	s_nop 0
	global_load_lds_dwordx4 v[32:33], off
	s_cbranch_vccz .LBB0_609
	v_cndmask_b32_e64 v32, 0, 1, s[88:89]
	v_cmp_ne_u32_e64 s[8:9], 1, v32

; #define LAS __attribute__((address_space(3)))
; __device__ __forceinline__ void hgrn_chain(const unsigned char* REC, const float* s0, float* sout, bf16_t* MIX,
;                                            int cidx0, int nchunks, int h, int vhalf, LAS unsigned char* lds, int wave, int lane) {
;     ...
;         if (comp) {
;             bf16x8 QDf[2][4], KEf[8], ITf, Af[2]; f32x4 DEC[8];
; #pragma unroll
;             for (int kb = 0; kb < 8; ++kb) { DEC[kb] = *(const LAS f32x4*)(R + R_DEC + (16 * kb + 4 * g) * 4); KEf[kb] = *(const LAS bf16x8*)(R + R_KE + ((16 * kb + c16) * 32 + 8 * g) * 2); }
;             ITf = *(const LAS bf16x8*)(R + R_IT + ((v0 + c16) * 32 + 8 * g) * 2);
; #pragma unroll
;             for (int tb = 0; tb < 2; ++tb) {
;                 Af[tb] = *(const LAS bf16x8*)(R + R_A + ((16 * tb + c16) * 32 + 8 * g) * 2);
; #pragma unroll
;                 for (int kk = 0; kk < 4; ++kk) QDf[tb][kk] = *(const LAS bf16x8*)(R + R_QD + ((tb * 4 + kk) * 64 + lane) * 16);
;             }
;             bf16x8 Sb[4];
; #pragma unroll
;             for (int kk = 0; kk < 4; ++kk) {
;                 u32x4 sb; sb.x = cvt_pk_bf16(S[2 * kk][0], S[2 * kk][1]); sb.y = cvt_pk_bf16(S[2 * kk][2], S[2 * kk][3]);
;                 sb.z = cvt_pk_bf16(S[2 * kk + 1][0], S[2 * kk + 1][1]); sb.w = cvt_pk_bf16(S[2 * kk + 1][2], S[2 * kk + 1][3]);
;                 Sb[kk] = __builtin_bit_cast(bf16x8, sb);
;             }
; #pragma unroll
;             for (int kb = 0; kb < 8; ++kb) S[kb] = __builtin_amdgcn_mfma_f32_16x16x32_bf16(KEf[kb], ITf, S[kb] * DEC[kb], 0, 0, 0);
;             f32x4 o0 = {0.f, 0.f, 0.f, 0.f}, o1 = o0;
;             o0 = __builtin_amdgcn_mfma_f32_16x16x32_bf16(ITf, Af[0], o0, 0, 0, 0);
;             o1 = __builtin_amdgcn_mfma_f32_16x16x32_bf16(ITf, Af[1], o1, 0, 0, 0);
; #pragma unroll
;             for (int kk = 0; kk < 4; ++kk) { o0 = __builtin_amdgcn_mfma_f32_16x16x32_bf16(Sb[kk], QDf[0][kk], o0, 0, 0, 0); o1 = __builtin_amdgcn_mfma_f32_16x16x32_bf16(Sb[kk], QDf[1][kk], o1, 0, 0, 0); }
;             u32x2 w; w.x = cvt_pk_bf16(o0[0], o0[1]); w.y = cvt_pk_bf16(o0[2], o0[3]);
;             *(u32x2*)(mo + (size_t)c * 32 * D) = w;
;             w.x = cvt_pk_bf16(o1[0], o1[1]); w.y = cvt_pk_bf16(o1[2], o1[3]);
;             *(u32x2*)(mo + (size_t)c * 32 * D + (size_t)16 * D) = w;
.LBB0_609:
	v_lshl_add_u64 v[32:33], v[44:45], 0, s[90:91]
	s_add_i32 m0, s8, 0x6000
	s_nop 0
	global_load_lds_dwordx4 v[32:33], off
	v_cndmask_b32_e64 v32, 0, 1, s[88:89]
	v_cmp_ne_u32_e64 s[8:9], 1, v32
	s_branch .LBB0_607
.Lch_comp_new:
	s_mul_i32 s12, s16, 0x6c00
	v_add_u32_e32 v36, s12, v61
	v_add_u32_e32 v39, s12, v120
	v_add_u32_e32 v37, v36, v63
	v_add_u32_e32 v38, v36, v62
	ds_read_b128 v[32:35], v38 offset:16384
	ds_read_b128 v[164:167], v36 offset:26624
	ds_read_b128 v[196:199], v37 offset:8192
	ds_read_b128 v[168:171], v36 offset:26688
	ds_read_b128 v[200:203], v37 offset:9216
	ds_read_b128 v[172:175], v36 offset:26752
	ds_read_b128 v[204:207], v37 offset:10240
	ds_read_b128 v[176:179], v36 offset:26816
	ds_read_b128 v[208:211], v37 offset:11264
	ds_read_b128 v[180:183], v36 offset:26880
	ds_read_b128 v[212:215], v37 offset:12288
	ds_read_b128 v[184:187], v36 offset:26944
	ds_read_b128 v[216:219], v37 offset:13312
	ds_read_b128 v[188:191], v36 offset:27008
	ds_read_b128 v[220:223], v37 offset:14336
	s_mul_i32 s8, s15, 0x6c00
	s_add_i32 s8, s33, s8
	v_lshl_add_u64 v[40:41], v[44:45], 0, s[96:97]
	s_mov_b32 m0, s8
	s_and_b64 vcc, exec, s[6:7]
	global_load_lds_dwordx4 v[40:41], off
	v_lshl_add_u64 v[40:41], v[44:45], 0, s[0:1]
	s_add_i32 m0, s8, 0x2000
	s_nop 0
	global_load_lds_dwordx4 v[40:41], off
	v_lshl_add_u64 v[40:41], v[44:45], 0, s[4:5]
	s_add_i32 m0, s8, 0x4000
	s_nop 0
	global_load_lds_dwordx4 v[40:41], off
	s_cbranch_vccnz .Lch_no4
	v_lshl_add_u64 v[40:41], v[44:45], 0, s[90:91]
	s_add_i32 m0, s8, 0x6000
	s_nop 0
	global_load_lds_dwordx4 v[40:41], off
.Lch_no4:
	s_mov_b64 s[8:9], 0
	v_cvt_pk_bf16_f32 v110, v28, v29
	v_cvt_pk_bf16_f32 v111, v30, v31
	v_cvt_pk_bf16_f32 v112, v24, v25
	v_cvt_pk_bf16_f32 v113, v26, v27
	v_cvt_pk_bf16_f32 v114, v20, v21
	v_cvt_pk_bf16_f32 v115, v22, v23
	v_cvt_pk_bf16_f32 v116, v16, v17
	v_cvt_pk_bf16_f32 v117, v18, v19
	v_cvt_pk_bf16_f32 v130, v12, v13
	v_cvt_pk_bf16_f32 v131, v14, v15
	v_cvt_pk_bf16_f32 v132, v8, v9
	v_cvt_pk_bf16_f32 v133, v10, v11
	v_cvt_pk_bf16_f32 v134, v4, v5
	v_cvt_pk_bf16_f32 v135, v6, v7
	v_cvt_pk_bf16_f32 v136, v0, v1
	v_cvt_pk_bf16_f32 v137, v2, v3
	s_waitcnt lgkmcnt(12)
	v_pk_mul_f32 v[28:29], v[28:29], v[164:165]
	v_pk_mul_f32 v[30:31], v[30:31], v[166:167]
	ds_read_b128 v[192:195], v36 offset:27072
	ds_read_b128 v[224:227], v37 offset:15360
	v_mfma_f32_16x16x32_bf16 v[28:31], v[196:199], v[32:35], v[28:31]
	s_waitcnt lgkmcnt(12)
	v_pk_mul_f32 v[24:25], v[24:25], v[168:169]
	v_pk_mul_f32 v[26:27], v[26:27], v[170:171]
	ds_read_b128 v[228:231], v37 offset:24576
	ds_read_b128 v[232:235], v37 offset:25600
	v_mfma_f32_16x16x32_bf16 v[24:27], v[200:203], v[32:35], v[24:27]
	s_waitcnt lgkmcnt(12)
	v_pk_mul_f32 v[20:21], v[20:21], v[172:173]
	v_pk_mul_f32 v[22:23], v[22:23], v[174:175]
	ds_read_b128 v[78:81], v39
	ds_read_b128 v[82:85], v39 offset:4096
	v_mfma_f32_16x16x32_bf16 v[20:23], v[204:207], v[32:35], v[20:23]
	s_waitcnt lgkmcnt(12)
	v_pk_mul_f32 v[16:17], v[16:17], v[176:177]
	v_pk_mul_f32 v[18:19], v[18:19], v[178:179]
	ds_read_b128 v[86:89], v39 offset:1024
	ds_read_b128 v[90:93], v39 offset:5120
	v_mfma_f32_16x16x32_bf16 v[16:19], v[208:211], v[32:35], v[16:19]
	s_waitcnt lgkmcnt(12)
	v_pk_mul_f32 v[12:13], v[12:13], v[180:181]
	v_pk_mul_f32 v[14:15], v[14:15], v[182:183]
	ds_read_b128 v[94:97], v39 offset:2048
	ds_read_b128 v[98:101], v39 offset:6144
	v_mfma_f32_16x16x32_bf16 v[12:15], v[212:215], v[32:35], v[12:15]
	s_waitcnt lgkmcnt(12)
	v_pk_mul_f32 v[8:9], v[8:9], v[184:185]
	v_pk_mul_f32 v[10:11], v[10:11], v[186:187]
	ds_read_b128 v[102:105], v39 offset:3072
	ds_read_b128 v[106:109], v39 offset:7168
	v_mfma_f32_16x16x32_bf16 v[8:11], v[216:219], v[32:35], v[8:11]
	s_waitcnt lgkmcnt(12)
	v_pk_mul_f32 v[4:5], v[4:5], v[188:189]
	v_pk_mul_f32 v[6:7], v[6:7], v[190:191]
	s_nop 1
	v_mfma_f32_16x16x32_bf16 v[4:7], v[220:223], v[32:35], v[4:7]
	s_waitcnt lgkmcnt(10)
	v_pk_mul_f32 v[0:1], v[0:1], v[192:193]
	v_pk_mul_f32 v[2:3], v[2:3], v[194:195]
	s_nop 1
	v_mfma_f32_16x16x32_bf16 v[0:3], v[224:227], v[32:35], v[0:3]
	s_waitcnt lgkmcnt(8)
	v_mfma_f32_16x16x32_bf16 v[138:141], v[32:35], v[228:231], 0
	v_mfma_f32_16x16x32_bf16 v[146:149], v[32:35], v[232:235], 0
	s_waitcnt lgkmcnt(7)
	v_mfma_f32_16x16x32_bf16 v[138:141], v[110:113], v[78:81], v[138:141]
	s_waitcnt lgkmcnt(6)
	v_mfma_f32_16x16x32_bf16 v[146:149], v[110:113], v[82:85], v[146:149]
	s_waitcnt lgkmcnt(5)
	v_mfma_f32_16x16x32_bf16 v[138:141], v[114:117], v[86:89], v[138:141]
	s_waitcnt lgkmcnt(4)
	v_mfma_f32_16x16x32_bf16 v[146:149], v[114:117], v[90:93], v[146:149]
	s_waitcnt lgkmcnt(3)
	v_mfma_f32_16x16x32_bf16 v[138:141], v[130:133], v[94:97], v[138:141]
	s_waitcnt lgkmcnt(2)
	v_mfma_f32_16x16x32_bf16 v[146:149], v[130:133], v[98:101], v[146:149]
	s_waitcnt lgkmcnt(1)
	v_mfma_f32_16x16x32_bf16 v[138:141], v[134:137], v[102:105], v[138:141]
	s_waitcnt lgkmcnt(0)
	v_mfma_f32_16x16x32_bf16 v[146:149], v[134:137], v[106:109], v[146:149]
	s_mov_b32 s12, 0xffff0000
	s_nop 6
	v_cvt_pk_bf16_f32 v36, v138, v139
	v_cvt_pk_bf16_f32 v37, v140, v141
	v_add_co_u32_e32 v38, vcc, s12, v48
	v_cvt_pk_bf16_f32 v40, v146, v147
	s_nop 0
	v_addc_co_u32_e32 v39, vcc, -1, v49, vcc
	v_cvt_pk_bf16_f32 v41, v148, v149
	global_store_dwordx2 v[38:39], v[36:37], off
	global_store_dwordx2 v[48:49], v[40:41], off
	s_cmp_lt_i32 s11, 1
	s_mov_b64 s[12:13], -1
	s_cbranch_scc1 .LBB0_608

;     __host__ __device__ bool next(int i, Unit& u) const { return (i + I0 < I1) && StaticOrder::next(i + I0, u); }
; #define PG8_STAGE(bufoff, gbase, voff) do { _Pragma("unroll") for (int _i = 0; _i < 2; ++_i) \
;         __builtin_amdgcn_global_load_lds((const unsigned*)((const char*)(gbase) + (voff)[_i]), (PG8_LAS unsigned*)(lds + (bufoff) + ldsw + _i * 8192), 16, 0, 0); } while (0)
; #define PG8_LDA(dst, b, h) do { _Pragma("unroll") for (int m = 0; m < 4; ++m) _Pragma("unroll") for (int k = 0; k < 2; ++k) dst[m][k] = *(const PG8_LAS bf16x8*)(lds + PG8_SA(b, h) + aoff + m * 2048 + k * 1024); } while (0)
; #define PG8_LDB(dst, b, h) do { _Pragma("unroll") for (int n = 0; n < 2; ++n) _Pragma("unroll") for (int k = 0; k < 2; ++k) dst[n][k] = *(const PG8_LAS bf16x8*)(lds + PG8_SB(b, h) + boff + n * 2048 + k * 1024); } while (0)
; #define PG8_WAIT_V(n) asm volatile("s_waitcnt vmcnt(" #n ")" ::: "memory")
; #define PG8_WAIT_L(n) asm volatile("s_waitcnt lgkmcnt(" #n ")" ::: "memory")
; #define PG8_BAR __builtin_amdgcn_s_barrier()
; #define PG8_SCHED __builtin_amdgcn_sched_barrier(0)
; template <class Epi, class Sched, bool ALIGN_EPI = false, bool SP2 = false>
; __device__ __forceinline__ void gemm_phase(PG8_LAS unsigned char* lds, const Gemm g, const Sched& S, const Epi& E) {
;     ...
;         const bool has_next = S.next(ui + 1, nxt);
;         const char* nA = has_next ? (const char*)g.A + (size_t)nxt.pm * tstep : cA; const char* nB = has_next ? (const char*)g.Bt + (size_t)nxt.pn * tstep : cB;
;         for (int t = 0; t < nt; t += 2) {
;             const bool last = (t == nt - 2);
;             const char* a1 = cA + (size_t)(t + 1) * kstep;
;             const char* a2 = last ? nA : cA + (size_t)(t + 2) * kstep; const char* b2 = last ? nB : cB + (size_t)(t + 2) * kstep;
;             const char* a3 = a2 + kstep; const char* b3 = b2 + kstep;
;             if (last && has_next) S.a_ready(nxt);
;             if constexpr (SP2) {
;             PG8_LDB(B0, 0, 0); PG8_LDB(B1, 0, 1); PG8_SCHED; PG8_LDA(At, 0, 0); PG8_STAGE(PG8_SA(1, 1), a1 + hstep, voffA);
;             PG8_WAIT_V(8); PG8_WAIT_L(0); PG8_BAR; PG8_MMA(0, 0, At, B0); PG8_MMA(0, 1, At, B1); PG8_BAR; PG8_SCHED;
;             PG8_LDA(At, 0, 1); PG8_STAGE(PG8_SB(0, 0), b2, voffB); PG8_STAGE(PG8_SB(0, 1), b2 + hstep, voffB); PG8_STAGE(PG8_SA(0, 0), a2, voffA);
.LBB0_818:
	ds_read_b128 v[162:165], v158
	ds_read_b128 v[166:169], v158 offset:1024
	ds_read_b128 v[170:173], v158 offset:2048
	ds_read_b128 v[174:177], v158 offset:3072
	ds_read_b128 v[178:181], v159
	ds_read_b128 v[182:185], v159 offset:1024
	ds_read_b128 v[186:189], v159 offset:2048
	ds_read_b128 v[190:193], v159 offset:3072
	s_add_u32 s34, s30, 0xfff80080
	s_addc_u32 s35, s31, -1
	s_cmp_eq_u32 s59, 28
	s_cselect_b32 s37, s23, s35
	s_cselect_b32 s36, s55, s34
	s_cselect_b32 s35, s21, s58
	s_cselect_b32 s34, s56, s57
	v_lshl_add_u64 v[226:227], s[30:31], 0, v[138:139]
	s_add_i32 m0, s25, 0xc000
	ds_read_b128 v[194:197], v160
	ds_read_b128 v[198:201], v160 offset:1024
	ds_read_b128 v[202:205], v160 offset:2048
	ds_read_b128 v[206:209], v160 offset:3072
	ds_read_b128 v[210:213], v160 offset:4096
	ds_read_b128 v[214:217], v160 offset:5120
	ds_read_b128 v[218:221], v160 offset:6144
	ds_read_b128 v[222:225], v160 offset:7168
	global_load_lds_dwordx4 v[226:227], off
	v_lshl_add_u64 v[226:227], s[30:31], 0, v[140:141]
	s_add_i32 m0, s25, 0xe000
	s_nop 0
	global_load_lds_dwordx4 v[226:227], off
	s_waitcnt vmcnt(8)
	s_waitcnt lgkmcnt(0)
	s_barrier
	s_setprio 1
	s_waitcnt lgkmcnt(0)
	v_mfma_f32_16x16x32_bf16 v[124:127], v[162:165], v[194:197], v[124:127]
	v_mfma_f32_16x16x32_bf16 v[120:123], v[170:173], v[194:197], v[120:123]
	v_mfma_f32_16x16x32_bf16 v[116:119], v[162:165], v[202:205], v[116:119]
	v_mfma_f32_16x16x32_bf16 v[112:115], v[170:173], v[202:205], v[112:115]
	v_mfma_f32_16x16x32_bf16 v[100:103], v[162:165], v[210:213], v[100:103]
	v_mfma_f32_16x16x32_bf16 v[96:99], v[170:173], v[210:213], v[96:99]
	v_mfma_f32_16x16x32_bf16 v[84:87], v[162:165], v[218:221], v[84:87]
	v_mfma_f32_16x16x32_bf16 v[80:83], v[170:173], v[218:221], v[80:83]
	v_mfma_f32_16x16x32_bf16 v[124:127], v[166:169], v[198:201], v[124:127]
	v_mfma_f32_16x16x32_bf16 v[120:123], v[174:177], v[198:201], v[120:123]
	v_mfma_f32_16x16x32_bf16 v[116:119], v[166:169], v[206:209], v[116:119]
	v_mfma_f32_16x16x32_bf16 v[112:115], v[174:177], v[206:209], v[112:115]
	v_mfma_f32_16x16x32_bf16 v[100:103], v[166:169], v[214:217], v[100:103]
	v_mfma_f32_16x16x32_bf16 v[96:99], v[174:177], v[214:217], v[96:99]
	v_mfma_f32_16x16x32_bf16 v[84:87], v[166:169], v[222:225], v[84:87]
	v_mfma_f32_16x16x32_bf16 v[80:83], v[174:177], v[222:225], v[80:83]
	s_setprio 0
	s_setprio 1
	v_mfma_f32_16x16x32_bf16 v[108:111], v[178:181], v[194:197], v[108:111]
	v_mfma_f32_16x16x32_bf16 v[104:107], v[186:189], v[194:197], v[104:107]
	v_mfma_f32_16x16x32_bf16 v[92:95], v[178:181], v[202:205], v[92:95]
	v_mfma_f32_16x16x32_bf16 v[88:91], v[186:189], v[202:205], v[88:91]
	v_mfma_f32_16x16x32_bf16 v[76:79], v[178:181], v[210:213], v[76:79]
	v_mfma_f32_16x16x32_bf16 v[72:75], v[186:189], v[210:213], v[72:75]
	v_mfma_f32_16x16x32_bf16 v[68:71], v[178:181], v[218:221], v[68:71]
	v_mfma_f32_16x16x32_bf16 v[64:67], v[186:189], v[218:221], v[64:67]
	v_mfma_f32_16x16x32_bf16 v[108:111], v[182:185], v[198:201], v[108:111]
	v_mfma_f32_16x16x32_bf16 v[104:107], v[190:193], v[198:201], v[104:107]
	v_mfma_f32_16x16x32_bf16 v[92:95], v[182:185], v[206:209], v[92:95]
	v_mfma_f32_16x16x32_bf16 v[88:91], v[190:193], v[206:209], v[88:91]
	s_setprio 2
	s_barrier
	v_mfma_f32_16x16x32_bf16 v[76:79], v[182:185], v[214:217], v[76:79]
	v_mfma_f32_16x16x32_bf16 v[72:75], v[190:193], v[214:217], v[72:75]
	v_mfma_f32_16x16x32_bf16 v[68:71], v[182:185], v[222:225], v[68:71]
	v_mfma_f32_16x16x32_bf16 v[64:67], v[190:193], v[222:225], v[64:67]
	s_setprio 0
	s_add_i32 s60, s48, s33
	v_lshl_add_u64 v[226:227], s[34:35], 0, v[134:135]
	s_mov_b32 m0, s60
	ds_read_b128 v[194:197], v160 offset:16384
	ds_read_b128 v[198:201], v160 offset:17408
	ds_read_b128 v[202:205], v160 offset:18432
	ds_read_b128 v[206:209], v160 offset:19456
	ds_read_b128 v[210:213], v160 offset:20480
	ds_read_b128 v[214:217], v160 offset:21504
	ds_read_b128 v[218:221], v160 offset:22528
	ds_read_b128 v[222:225], v160 offset:23552
	global_load_lds_dwordx4 v[226:227], off
	s_add_i32 m0, s60, 0x2000
	s_add_u32 s60, s34, 0x80000
	v_lshl_add_u64 v[228:229], s[34:35], 0, v[130:131]
	s_addc_u32 s61, s35, 0
	s_add_i32 s62, s49, s33
	global_load_lds_dwordx4 v[228:229], off
	v_lshl_add_u64 v[230:231], s[60:61], 0, v[134:135]
	s_mov_b32 m0, s62
	v_lshl_add_u64 v[232:233], s[36:37], 0, v[132:133]
	global_load_lds_dwordx4 v[230:231], off
	v_lshl_add_u64 v[230:231], s[60:61], 0, v[130:131]
	s_add_i32 m0, s62, 0x2000
	s_nop 0
	global_load_lds_dwordx4 v[230:231], off
	v_lshl_add_u64 v[230:231], s[36:37], 0, v[136:137]
	s_mov_b32 m0, s25
	s_nop 0
	global_load_lds_dwordx4 v[230:231], off
	s_mov_b32 m0, s40
	s_nop 0
	global_load_lds_dwordx4 v[232:233], off
	s_waitcnt vmcnt(8)
	s_waitcnt lgkmcnt(0)
	s_barrier
; #define PG8_STAGE(bufoff, gbase, voff) do { _Pragma("unroll") for (int _i = 0; _i < 2; ++_i) \
;         __builtin_amdgcn_global_load_lds((const unsigned*)((const char*)(gbase) + (voff)[_i]), (PG8_LAS unsigned*)(lds + (bufoff) + ldsw + _i * 8192), 16, 0, 0); } while (0)
; #define PG8_LDA(dst, b, h) do { _Pragma("unroll") for (int m = 0; m < 4; ++m) _Pragma("unroll") for (int k = 0; k < 2; ++k) dst[m][k] = *(const PG8_LAS bf16x8*)(lds + PG8_SA(b, h) + aoff + m * 2048 + k * 1024); } while (0)
; #define PG8_LDB(dst, b, h) do { _Pragma("unroll") for (int n = 0; n < 2; ++n) _Pragma("unroll") for (int k = 0; k < 2; ++k) dst[n][k] = *(const PG8_LAS bf16x8*)(lds + PG8_SB(b, h) + boff + n * 2048 + k * 1024); } while (0)
; #define PG8_MMA(ai, bj, At, Bt) do { __builtin_amdgcn_s_setprio(1); _Pragma("unroll") for (int m = 0; m < 4; ++m) _Pragma("unroll") for (int n = 0; n < 2; ++n) _Pragma("unroll") for (int k = 0; k < 2; ++k) \
;         acc[ai][bj][m][n] = __builtin_amdgcn_mfma_f32_16x16x32_bf16(Bt[n][k], At[m][k], acc[ai][bj][m][n], 0, 0, 0); __builtin_amdgcn_s_setprio(0); } while (0)
; #define PG8_WAIT_V(n) asm volatile("s_waitcnt vmcnt(" #n ")" ::: "memory")
; #define PG8_WAIT_L(n) asm volatile("s_waitcnt lgkmcnt(" #n ")" ::: "memory")
; #define PG8_BAR __builtin_amdgcn_s_barrier()
; #define PG8_SCHED __builtin_amdgcn_sched_barrier(0)
; template <class Epi, class Sched, bool ALIGN_EPI = false, bool SP2 = false>
; __device__ __forceinline__ void gemm_phase(PG8_LAS unsigned char* lds, const Gemm g, const Sched& S, const Epi& E) {
;     ...
;             PG8_WAIT_V(8); PG8_WAIT_L(0); PG8_BAR; PG8_MMA(1, 0, At, B0); PG8_MMA(1, 1, At, B1); PG8_BAR; PG8_SCHED;
;             PG8_LDB(B0, 1, 0); PG8_LDB(B1, 1, 1); PG8_SCHED; PG8_LDA(At, 1, 0); PG8_STAGE(PG8_SA(0, 1), a2 + hstep, voffA);
;             PG8_WAIT_V(8); PG8_WAIT_L(0); PG8_BAR; PG8_MMA(0, 0, At, B0); PG8_MMA(0, 1, At, B1); PG8_BAR; PG8_SCHED;
	s_setprio 1
	s_waitcnt lgkmcnt(0)
	v_mfma_f32_16x16x32_bf16 v[60:63], v[162:165], v[194:197], v[60:63]
	v_mfma_f32_16x16x32_bf16 v[56:59], v[170:173], v[194:197], v[56:59]
	v_mfma_f32_16x16x32_bf16 v[52:55], v[162:165], v[202:205], v[52:55]
	v_mfma_f32_16x16x32_bf16 v[48:51], v[170:173], v[202:205], v[48:51]
	v_mfma_f32_16x16x32_bf16 v[36:39], v[162:165], v[210:213], v[36:39]
	v_mfma_f32_16x16x32_bf16 v[32:35], v[170:173], v[210:213], v[32:35]
	v_mfma_f32_16x16x32_bf16 v[20:23], v[162:165], v[218:221], v[20:23]
	v_mfma_f32_16x16x32_bf16 v[16:19], v[170:173], v[218:221], v[16:19]
	v_mfma_f32_16x16x32_bf16 v[60:63], v[166:169], v[198:201], v[60:63]
	v_mfma_f32_16x16x32_bf16 v[56:59], v[174:177], v[198:201], v[56:59]
	v_mfma_f32_16x16x32_bf16 v[52:55], v[166:169], v[206:209], v[52:55]
	v_mfma_f32_16x16x32_bf16 v[48:51], v[174:177], v[206:209], v[48:51]
	v_mfma_f32_16x16x32_bf16 v[36:39], v[166:169], v[214:217], v[36:39]
	v_mfma_f32_16x16x32_bf16 v[32:35], v[174:177], v[214:217], v[32:35]
	v_mfma_f32_16x16x32_bf16 v[20:23], v[166:169], v[222:225], v[20:23]
	v_mfma_f32_16x16x32_bf16 v[16:19], v[174:177], v[222:225], v[16:19]
	s_setprio 0
	s_setprio 1
	v_mfma_f32_16x16x32_bf16 v[44:47], v[178:181], v[194:197], v[44:47]
	v_mfma_f32_16x16x32_bf16 v[40:43], v[186:189], v[194:197], v[40:43]
	v_mfma_f32_16x16x32_bf16 v[28:31], v[178:181], v[202:205], v[28:31]
	v_mfma_f32_16x16x32_bf16 v[24:27], v[186:189], v[202:205], v[24:27]
	v_mfma_f32_16x16x32_bf16 v[12:15], v[178:181], v[210:213], v[12:15]
	v_mfma_f32_16x16x32_bf16 v[8:11], v[186:189], v[210:213], v[8:11]
	v_mfma_f32_16x16x32_bf16 v[4:7], v[178:181], v[218:221], v[4:7]
	v_mfma_f32_16x16x32_bf16 v[0:3], v[186:189], v[218:221], v[0:3]
	v_mfma_f32_16x16x32_bf16 v[44:47], v[182:185], v[198:201], v[44:47]
	v_mfma_f32_16x16x32_bf16 v[40:43], v[190:193], v[198:201], v[40:43]
	v_mfma_f32_16x16x32_bf16 v[28:31], v[182:185], v[206:209], v[28:31]
	v_mfma_f32_16x16x32_bf16 v[24:27], v[190:193], v[206:209], v[24:27]
	s_setprio 2
	s_barrier
	v_mfma_f32_16x16x32_bf16 v[12:15], v[182:185], v[214:217], v[12:15]
	v_mfma_f32_16x16x32_bf16 v[8:11], v[190:193], v[214:217], v[8:11]
	v_mfma_f32_16x16x32_bf16 v[4:7], v[182:185], v[222:225], v[4:7]
	v_mfma_f32_16x16x32_bf16 v[0:3], v[190:193], v[222:225], v[0:3]
	s_setprio 0
	s_add_i32 s60, 0, 0x18000
	v_add_u32_e32 v161, s60, v156
	s_add_i32 s61, 0, 0x1c000
	ds_read_b128 v[162:165], v161
	ds_read_b128 v[166:169], v161 offset:1024
	ds_read_b128 v[170:173], v161 offset:2048
	ds_read_b128 v[174:177], v161 offset:3072
	v_add_u32_e32 v161, s61, v156
	ds_read_b128 v[178:181], v161
	ds_read_b128 v[182:185], v161 offset:1024
	ds_read_b128 v[186:189], v161 offset:2048
	ds_read_b128 v[190:193], v161 offset:3072
	s_add_u32 s36, s36, 0x80000
	s_addc_u32 s37, s37, 0
	s_mov_b32 m0, s41
	v_lshl_add_u64 v[234:235], s[36:37], 0, v[136:137]
	ds_read_b128 v[194:197], v160 offset:32768
	ds_read_b128 v[198:201], v160 offset:33792
	ds_read_b128 v[202:205], v160 offset:34816
	ds_read_b128 v[206:209], v160 offset:35840
	ds_read_b128 v[210:213], v160 offset:36864
	ds_read_b128 v[214:217], v160 offset:37888
	ds_read_b128 v[218:221], v160 offset:38912
	ds_read_b128 v[222:225], v160 offset:39936
	global_load_lds_dwordx4 v[234:235], off
	v_lshl_add_u64 v[234:235], s[36:37], 0, v[132:133]
	s_mov_b32 m0, s42
	s_nop 0
	global_load_lds_dwordx4 v[234:235], off
	s_waitcnt vmcnt(8)
	s_waitcnt lgkmcnt(0)
	s_barrier
	s_setprio 1
	s_waitcnt lgkmcnt(0)
	v_mfma_f32_16x16x32_bf16 v[124:127], v[162:165], v[194:197], v[124:127]
	v_mfma_f32_16x16x32_bf16 v[120:123], v[170:173], v[194:197], v[120:123]
	v_mfma_f32_16x16x32_bf16 v[116:119], v[162:165], v[202:205], v[116:119]
	v_mfma_f32_16x16x32_bf16 v[112:115], v[170:173], v[202:205], v[112:115]
	v_mfma_f32_16x16x32_bf16 v[100:103], v[162:165], v[210:213], v[100:103]
	v_mfma_f32_16x16x32_bf16 v[96:99], v[170:173], v[210:213], v[96:99]
	v_mfma_f32_16x16x32_bf16 v[84:87], v[162:165], v[218:221], v[84:87]
	v_mfma_f32_16x16x32_bf16 v[80:83], v[170:173], v[218:221], v[80:83]
	v_mfma_f32_16x16x32_bf16 v[124:127], v[166:169], v[198:201], v[124:127]
	v_mfma_f32_16x16x32_bf16 v[120:123], v[174:177], v[198:201], v[120:123]
	v_mfma_f32_16x16x32_bf16 v[116:119], v[166:169], v[206:209], v[116:119]
	v_mfma_f32_16x16x32_bf16 v[112:115], v[174:177], v[206:209], v[112:115]
	v_mfma_f32_16x16x32_bf16 v[100:103], v[166:169], v[214:217], v[100:103]
	v_mfma_f32_16x16x32_bf16 v[96:99], v[174:177], v[214:217], v[96:99]
	v_mfma_f32_16x16x32_bf16 v[84:87], v[166:169], v[222:225], v[84:87]
	v_mfma_f32_16x16x32_bf16 v[80:83], v[174:177], v[222:225], v[80:83]
	s_setprio 0
	s_setprio 1
	v_mfma_f32_16x16x32_bf16 v[108:111], v[178:181], v[194:197], v[108:111]
	v_mfma_f32_16x16x32_bf16 v[104:107], v[186:189], v[194:197], v[104:107]
	v_mfma_f32_16x16x32_bf16 v[92:95], v[178:181], v[202:205], v[92:95]
	v_mfma_f32_16x16x32_bf16 v[88:91], v[186:189], v[202:205], v[88:91]
	v_mfma_f32_16x16x32_bf16 v[76:79], v[178:181], v[210:213], v[76:79]
	v_mfma_f32_16x16x32_bf16 v[72:75], v[186:189], v[210:213], v[72:75]
	v_mfma_f32_16x16x32_bf16 v[68:71], v[178:181], v[218:221], v[68:71]
	v_mfma_f32_16x16x32_bf16 v[64:67], v[186:189], v[218:221], v[64:67]
	v_mfma_f32_16x16x32_bf16 v[108:111], v[182:185], v[198:201], v[108:111]
	v_mfma_f32_16x16x32_bf16 v[104:107], v[190:193], v[198:201], v[104:107]
	v_mfma_f32_16x16x32_bf16 v[92:95], v[182:185], v[206:209], v[92:95]
	v_mfma_f32_16x16x32_bf16 v[88:91], v[190:193], v[206:209], v[88:91]
	s_setprio 2
	s_barrier
; #define PG8_STAGE(bufoff, gbase, voff) do { _Pragma("unroll") for (int _i = 0; _i < 2; ++_i) \
;         __builtin_amdgcn_global_load_lds((const unsigned*)((const char*)(gbase) + (voff)[_i]), (PG8_LAS unsigned*)(lds + (bufoff) + ldsw + _i * 8192), 16, 0, 0); } while (0)
; #define PG8_LDA(dst, b, h) do { _Pragma("unroll") for (int m = 0; m < 4; ++m) _Pragma("unroll") for (int k = 0; k < 2; ++k) dst[m][k] = *(const PG8_LAS bf16x8*)(lds + PG8_SA(b, h) + aoff + m * 2048 + k * 1024); } while (0)
; #define PG8_MMA(ai, bj, At, Bt) do { __builtin_amdgcn_s_setprio(1); _Pragma("unroll") for (int m = 0; m < 4; ++m) _Pragma("unroll") for (int n = 0; n < 2; ++n) _Pragma("unroll") for (int k = 0; k < 2; ++k) \
;         acc[ai][bj][m][n] = __builtin_amdgcn_mfma_f32_16x16x32_bf16(Bt[n][k], At[m][k], acc[ai][bj][m][n], 0, 0, 0); __builtin_amdgcn_s_setprio(0); } while (0)
; #define PG8_WAIT_V(n) asm volatile("s_waitcnt vmcnt(" #n ")" ::: "memory")
; #define PG8_WAIT_L(n) asm volatile("s_waitcnt lgkmcnt(" #n ")" ::: "memory")
; #define PG8_BAR __builtin_amdgcn_s_barrier()
; #define PG8_SCHED __builtin_amdgcn_sched_barrier(0)
; template <class Epi, class Sched, bool ALIGN_EPI = false, bool SP2 = false>
; __device__ __forceinline__ void gemm_phase(PG8_LAS unsigned char* lds, const Gemm g, const Sched& S, const Epi& E) {
;     ...
;             PG8_WAIT_V(8); PG8_WAIT_L(0); PG8_BAR; PG8_MMA(0, 0, At, B0); PG8_MMA(0, 1, At, B1); PG8_BAR; PG8_SCHED;
;             PG8_LDA(At, 1, 1); PG8_STAGE(PG8_SB(1, 0), b3, voffB); PG8_STAGE(PG8_SB(1, 1), b3 + hstep, voffB); PG8_STAGE(PG8_SA(1, 0), a3, voffA);
;             PG8_WAIT_V(8); PG8_WAIT_L(0); PG8_BAR; PG8_MMA(1, 0, At, B0); PG8_MMA(1, 1, At, B1); PG8_BAR; PG8_SCHED;
	v_mfma_f32_16x16x32_bf16 v[76:79], v[182:185], v[214:217], v[76:79]
	v_mfma_f32_16x16x32_bf16 v[72:75], v[190:193], v[214:217], v[72:75]
	v_mfma_f32_16x16x32_bf16 v[68:71], v[182:185], v[222:225], v[68:71]
	v_mfma_f32_16x16x32_bf16 v[64:67], v[190:193], v[222:225], v[64:67]
	s_setprio 0
	s_add_i32 s36, s60, s33
	v_lshl_add_u64 v[226:227], v[226:227], 0, s[10:11]
	s_mov_b32 m0, s36
	ds_read_b128 v[194:197], v160 offset:49152
	ds_read_b128 v[198:201], v160 offset:50176
	ds_read_b128 v[202:205], v160 offset:51200
	ds_read_b128 v[206:209], v160 offset:52224
	ds_read_b128 v[210:213], v160 offset:53248
	ds_read_b128 v[214:217], v160 offset:54272
	ds_read_b128 v[218:221], v160 offset:55296
	ds_read_b128 v[222:225], v160 offset:56320
	global_load_lds_dwordx4 v[226:227], off
	s_add_i32 m0, s36, 0x2000
	s_add_u32 s34, s34, 0x80080
	v_lshl_add_u64 v[226:227], v[228:229], 0, s[10:11]
	s_addc_u32 s35, s35, 0
	s_add_i32 s36, s61, s33
	global_load_lds_dwordx4 v[226:227], off
	v_lshl_add_u64 v[226:227], s[34:35], 0, v[134:135]
	s_mov_b32 m0, s36
	s_nop 0
	global_load_lds_dwordx4 v[226:227], off
	v_lshl_add_u64 v[226:227], s[34:35], 0, v[130:131]
	s_add_i32 m0, s36, 0x2000
	s_nop 0
	global_load_lds_dwordx4 v[226:227], off
	v_lshl_add_u64 v[226:227], v[230:231], 0, s[10:11]
	s_mov_b32 m0, s44
	s_nop 0
	global_load_lds_dwordx4 v[226:227], off
	v_lshl_add_u64 v[226:227], v[232:233], 0, s[10:11]
	s_mov_b32 m0, s45
	s_nop 0
	global_load_lds_dwordx4 v[226:227], off
	s_waitcnt vmcnt(8)
	s_waitcnt lgkmcnt(0)
	s_barrier
	s_setprio 1
	s_waitcnt lgkmcnt(0)
	v_mfma_f32_16x16x32_bf16 v[60:63], v[162:165], v[194:197], v[60:63]
	v_mfma_f32_16x16x32_bf16 v[56:59], v[170:173], v[194:197], v[56:59]
	v_mfma_f32_16x16x32_bf16 v[52:55], v[162:165], v[202:205], v[52:55]
	v_mfma_f32_16x16x32_bf16 v[48:51], v[170:173], v[202:205], v[48:51]
	v_mfma_f32_16x16x32_bf16 v[36:39], v[162:165], v[210:213], v[36:39]
	v_mfma_f32_16x16x32_bf16 v[32:35], v[170:173], v[210:213], v[32:35]
	v_mfma_f32_16x16x32_bf16 v[20:23], v[162:165], v[218:221], v[20:23]
	v_mfma_f32_16x16x32_bf16 v[16:19], v[170:173], v[218:221], v[16:19]
	v_mfma_f32_16x16x32_bf16 v[60:63], v[166:169], v[198:201], v[60:63]
	v_mfma_f32_16x16x32_bf16 v[56:59], v[174:177], v[198:201], v[56:59]
	v_mfma_f32_16x16x32_bf16 v[52:55], v[166:169], v[206:209], v[52:55]
	v_mfma_f32_16x16x32_bf16 v[48:51], v[174:177], v[206:209], v[48:51]
	v_mfma_f32_16x16x32_bf16 v[36:39], v[166:169], v[214:217], v[36:39]
	v_mfma_f32_16x16x32_bf16 v[32:35], v[174:177], v[214:217], v[32:35]
	v_mfma_f32_16x16x32_bf16 v[20:23], v[166:169], v[222:225], v[20:23]
	v_mfma_f32_16x16x32_bf16 v[16:19], v[174:177], v[222:225], v[16:19]
	s_setprio 0
	s_setprio 1
	v_mfma_f32_16x16x32_bf16 v[44:47], v[178:181], v[194:197], v[44:47]
	v_mfma_f32_16x16x32_bf16 v[40:43], v[186:189], v[194:197], v[40:43]
	v_mfma_f32_16x16x32_bf16 v[28:31], v[178:181], v[202:205], v[28:31]
	v_mfma_f32_16x16x32_bf16 v[24:27], v[186:189], v[202:205], v[24:27]
	v_mfma_f32_16x16x32_bf16 v[12:15], v[178:181], v[210:213], v[12:15]
	v_mfma_f32_16x16x32_bf16 v[8:11], v[186:189], v[210:213], v[8:11]
	v_mfma_f32_16x16x32_bf16 v[4:7], v[178:181], v[218:221], v[4:7]
	v_mfma_f32_16x16x32_bf16 v[0:3], v[186:189], v[218:221], v[0:3]
	v_mfma_f32_16x16x32_bf16 v[44:47], v[182:185], v[198:201], v[44:47]
	v_mfma_f32_16x16x32_bf16 v[40:43], v[190:193], v[198:201], v[40:43]
	v_mfma_f32_16x16x32_bf16 v[28:31], v[182:185], v[206:209], v[28:31]
	v_mfma_f32_16x16x32_bf16 v[24:27], v[190:193], v[206:209], v[24:27]
	s_setprio 2
	s_barrier
	v_mfma_f32_16x16x32_bf16 v[12:15], v[182:185], v[214:217], v[12:15]
	v_mfma_f32_16x16x32_bf16 v[8:11], v[190:193], v[214:217], v[8:11]
	v_mfma_f32_16x16x32_bf16 v[4:7], v[182:185], v[222:225], v[4:7]
	v_mfma_f32_16x16x32_bf16 v[0:3], v[190:193], v[222:225], v[0:3]
	s_setprio 0
	s_add_i32 s59, s59, 2
	s_add_u32 s30, s30, 0x100
	s_addc_u32 s31, s31, 0
	s_add_u32 s57, s57, 0x100
	s_addc_u32 s58, s58, 0
	s_cmp_gt_u32 s59, 29
	s_cbranch_scc0 .LBB0_818
	s_and_b64 vcc, exec, s[12:13]
	s_cbranch_vccz .LBB0_821
	s_barrier

;     __host__ __device__ bool next(int i, Unit& u) const { return (i + I0 < I1) && StaticOrder::next(i + I0, u); }
; #define PG8_STAGE(bufoff, gbase, voff) do { _Pragma("unroll") for (int _i = 0; _i < 2; ++_i) \
;         __builtin_amdgcn_global_load_lds((const unsigned*)((const char*)(gbase) + (voff)[_i]), (PG8_LAS unsigned*)(lds + (bufoff) + ldsw + _i * 8192), 16, 0, 0); } while (0)
; #define PG8_LDA(dst, b, h) do { _Pragma("unroll") for (int m = 0; m < 4; ++m) _Pragma("unroll") for (int k = 0; k < 2; ++k) dst[m][k] = *(const PG8_LAS bf16x8*)(lds + PG8_SA(b, h) + aoff + m * 2048 + k * 1024); } while (0)
; #define PG8_LDB(dst, b, h) do { _Pragma("unroll") for (int n = 0; n < 2; ++n) _Pragma("unroll") for (int k = 0; k < 2; ++k) dst[n][k] = *(const PG8_LAS bf16x8*)(lds + PG8_SB(b, h) + boff + n * 2048 + k * 1024); } while (0)
; #define PG8_WAIT_V(n) asm volatile("s_waitcnt vmcnt(" #n ")" ::: "memory")
; #define PG8_WAIT_L(n) asm volatile("s_waitcnt lgkmcnt(" #n ")" ::: "memory")
; #define PG8_BAR __builtin_amdgcn_s_barrier()
; #define PG8_SCHED __builtin_amdgcn_sched_barrier(0)
; template <class Epi, class Sched, bool ALIGN_EPI = false, bool SP2 = false>
; __device__ __forceinline__ void gemm_phase(PG8_LAS unsigned char* lds, const Gemm g, const Sched& S, const Epi& E) {
;     ...
;         const bool has_next = S.next(ui + 1, nxt);
;         const char* nA = has_next ? (const char*)g.A + (size_t)nxt.pm * tstep : cA; const char* nB = has_next ? (const char*)g.Bt + (size_t)nxt.pn * tstep : cB;
;         for (int t = 0; t < nt; t += 2) {
;             const bool last = (t == nt - 2);
;             const char* a1 = cA + (size_t)(t + 1) * kstep;
;             const char* a2 = last ? nA : cA + (size_t)(t + 2) * kstep; const char* b2 = last ? nB : cB + (size_t)(t + 2) * kstep;
;             const char* a3 = a2 + kstep; const char* b3 = b2 + kstep;
;             if (last && has_next) S.a_ready(nxt);
;             if constexpr (SP2) {
;             PG8_LDB(B0, 0, 0); PG8_LDB(B1, 0, 1); PG8_SCHED; PG8_LDA(At, 0, 0); PG8_STAGE(PG8_SA(1, 1), a1 + hstep, voffA);
;             PG8_WAIT_V(8); PG8_WAIT_L(0); PG8_BAR; PG8_MMA(0, 0, At, B0); PG8_MMA(0, 1, At, B1); PG8_BAR; PG8_SCHED;
;             PG8_LDA(At, 0, 1); PG8_STAGE(PG8_SB(0, 0), b2, voffB); PG8_STAGE(PG8_SB(0, 1), b2 + hstep, voffB); PG8_STAGE(PG8_SA(0, 0), a2, voffA);
.LBB0_835:
	s_add_u32 s31, s24, s30
	s_addc_u32 s38, s25, 0
	s_add_u32 s36, s31, 0x100
	s_addc_u32 s37, s38, 0
	s_and_b64 s[34:35], s[28:29], exec
	s_cselect_b32 s35, s15, s37
	s_cselect_b32 s34, s58, s36
	s_add_u32 s30, s18, s30
	s_addc_u32 s36, s19, 0
	s_add_u32 s30, s30, 0x100
	s_addc_u32 s36, s36, 0
	s_and_b64 s[28:29], s[28:29], exec
	s_cselect_b32 s37, s13, s36
	s_cselect_b32 s36, s59, s30
	s_add_u32 s40, s31, 0x10080
	ds_read_b128 v[148:151], v145
	ds_read_b128 v[152:155], v145 offset:1024
	ds_read_b128 v[156:159], v145 offset:2048
	ds_read_b128 v[160:163], v145 offset:3072
	ds_read_b128 v[164:167], v146
	ds_read_b128 v[168:171], v146 offset:1024
	ds_read_b128 v[172:175], v146 offset:2048
	ds_read_b128 v[176:179], v146 offset:3072
	s_addc_u32 s41, s38, 0
	s_add_i32 s69, s55, s42
	s_add_i32 m0, s17, 0xc000
	s_add_i32 s70, s17, 0xe000
	s_add_i32 s66, s69, 0x2000
	s_add_u32 s38, s36, 0x10000
	s_addc_u32 s39, s37, 0
	s_add_i32 s68, s56, s42
	s_add_i32 s67, s68, 0x2000
	s_add_i32 s65, 0, 0x18000
	s_add_i32 s64, 0, 0x1c000
	s_add_u32 s30, s34, 0x10000
	s_addc_u32 s31, s35, 0
	s_add_i32 s63, s65, s42
	s_add_i32 s61, s63, 0x2000
	s_add_u32 s28, s36, 0x10080
	s_addc_u32 s29, s37, 0
	s_add_i32 s62, s64, s42
	s_add_i32 s60, s62, 0x2000
	v_lshl_add_u64 v[212:213], s[40:41], 0, v[136:137]
	ds_read_b128 v[180:183], v147
	ds_read_b128 v[184:187], v147 offset:1024
	ds_read_b128 v[188:191], v147 offset:2048
	ds_read_b128 v[192:195], v147 offset:3072
	ds_read_b128 v[196:199], v147 offset:4096
	ds_read_b128 v[200:203], v147 offset:5120
	ds_read_b128 v[204:207], v147 offset:6144
	ds_read_b128 v[208:211], v147 offset:7168
	global_load_lds_dwordx4 v[212:213], off
	v_lshl_add_u64 v[212:213], s[40:41], 0, v[132:133]
	s_mov_b32 m0, s70
	s_nop 0
	global_load_lds_dwordx4 v[212:213], off
	s_waitcnt vmcnt(8)
	s_waitcnt lgkmcnt(0)
	s_barrier
	s_setprio 1
	s_waitcnt lgkmcnt(0)
	v_mfma_f32_16x16x32_bf16 v[124:127], v[148:151], v[180:183], v[124:127]
	v_mfma_f32_16x16x32_bf16 v[120:123], v[156:159], v[180:183], v[120:123]
	v_mfma_f32_16x16x32_bf16 v[116:119], v[148:151], v[188:191], v[116:119]
	v_mfma_f32_16x16x32_bf16 v[112:115], v[156:159], v[188:191], v[112:115]
	v_mfma_f32_16x16x32_bf16 v[100:103], v[148:151], v[196:199], v[100:103]
	v_mfma_f32_16x16x32_bf16 v[96:99], v[156:159], v[196:199], v[96:99]
	v_mfma_f32_16x16x32_bf16 v[84:87], v[148:151], v[204:207], v[84:87]
	v_mfma_f32_16x16x32_bf16 v[80:83], v[156:159], v[204:207], v[80:83]
	v_mfma_f32_16x16x32_bf16 v[124:127], v[152:155], v[184:187], v[124:127]
	v_mfma_f32_16x16x32_bf16 v[120:123], v[160:163], v[184:187], v[120:123]
	v_mfma_f32_16x16x32_bf16 v[116:119], v[152:155], v[192:195], v[116:119]
	v_mfma_f32_16x16x32_bf16 v[112:115], v[160:163], v[192:195], v[112:115]
	v_mfma_f32_16x16x32_bf16 v[100:103], v[152:155], v[200:203], v[100:103]
	v_mfma_f32_16x16x32_bf16 v[96:99], v[160:163], v[200:203], v[96:99]
	v_mfma_f32_16x16x32_bf16 v[84:87], v[152:155], v[208:211], v[84:87]
	v_mfma_f32_16x16x32_bf16 v[80:83], v[160:163], v[208:211], v[80:83]
	s_setprio 0
	s_setprio 1
	v_mfma_f32_16x16x32_bf16 v[108:111], v[164:167], v[180:183], v[108:111]
	v_mfma_f32_16x16x32_bf16 v[104:107], v[172:175], v[180:183], v[104:107]
	v_mfma_f32_16x16x32_bf16 v[92:95], v[164:167], v[188:191], v[92:95]
	v_mfma_f32_16x16x32_bf16 v[88:91], v[172:175], v[188:191], v[88:91]
	v_mfma_f32_16x16x32_bf16 v[76:79], v[164:167], v[196:199], v[76:79]
	v_mfma_f32_16x16x32_bf16 v[72:75], v[172:175], v[196:199], v[72:75]
	v_mfma_f32_16x16x32_bf16 v[68:71], v[164:167], v[204:207], v[68:71]
	v_mfma_f32_16x16x32_bf16 v[64:67], v[172:175], v[204:207], v[64:67]
	v_mfma_f32_16x16x32_bf16 v[108:111], v[168:171], v[184:187], v[108:111]
	v_mfma_f32_16x16x32_bf16 v[104:107], v[176:179], v[184:187], v[104:107]
	v_mfma_f32_16x16x32_bf16 v[92:95], v[168:171], v[192:195], v[92:95]
	v_mfma_f32_16x16x32_bf16 v[88:91], v[176:179], v[192:195], v[88:91]
	s_setprio 2
	s_barrier
	v_mfma_f32_16x16x32_bf16 v[76:79], v[168:171], v[200:203], v[76:79]
	v_mfma_f32_16x16x32_bf16 v[72:75], v[176:179], v[200:203], v[72:75]
	v_mfma_f32_16x16x32_bf16 v[68:71], v[168:171], v[208:211], v[68:71]
	v_mfma_f32_16x16x32_bf16 v[64:67], v[176:179], v[208:211], v[64:67]
	s_setprio 0
	s_mov_b32 m0, s69
	v_lshl_add_u64 v[212:213], s[36:37], 0, v[134:135]
	ds_read_b128 v[180:183], v147 offset:16384
	ds_read_b128 v[184:187], v147 offset:17408
	ds_read_b128 v[188:191], v147 offset:18432
	ds_read_b128 v[192:195], v147 offset:19456
	ds_read_b128 v[196:199], v147 offset:20480
	ds_read_b128 v[200:203], v147 offset:21504
	ds_read_b128 v[204:207], v147 offset:22528
	ds_read_b128 v[208:211], v147 offset:23552
	global_load_lds_dwordx4 v[212:213], off
	v_lshl_add_u64 v[214:215], s[36:37], 0, v[130:131]
	s_mov_b32 m0, s66
	v_lshl_add_u64 v[216:217], s[38:39], 0, v[134:135]
	global_load_lds_dwordx4 v[214:215], off
	s_mov_b32 m0, s68
	v_lshl_add_u64 v[218:219], s[34:35], 0, v[132:133]
	global_load_lds_dwordx4 v[216:217], off
	v_lshl_add_u64 v[216:217], s[38:39], 0, v[130:131]
	s_mov_b32 m0, s67
	s_nop 0
	global_load_lds_dwordx4 v[216:217], off
	v_lshl_add_u64 v[216:217], s[34:35], 0, v[136:137]
	s_mov_b32 m0, s17
	s_nop 0
	global_load_lds_dwordx4 v[216:217], off
	s_mov_b32 m0, s47
	s_nop 0
	global_load_lds_dwordx4 v[218:219], off
	s_waitcnt vmcnt(8)
	s_waitcnt lgkmcnt(0)
	s_barrier
; #define PG8_STAGE(bufoff, gbase, voff) do { _Pragma("unroll") for (int _i = 0; _i < 2; ++_i) \
;         __builtin_amdgcn_global_load_lds((const unsigned*)((const char*)(gbase) + (voff)[_i]), (PG8_LAS unsigned*)(lds + (bufoff) + ldsw + _i * 8192), 16, 0, 0); } while (0)
; #define PG8_LDA(dst, b, h) do { _Pragma("unroll") for (int m = 0; m < 4; ++m) _Pragma("unroll") for (int k = 0; k < 2; ++k) dst[m][k] = *(const PG8_LAS bf16x8*)(lds + PG8_SA(b, h) + aoff + m * 2048 + k * 1024); } while (0)
; #define PG8_LDB(dst, b, h) do { _Pragma("unroll") for (int n = 0; n < 2; ++n) _Pragma("unroll") for (int k = 0; k < 2; ++k) dst[n][k] = *(const PG8_LAS bf16x8*)(lds + PG8_SB(b, h) + boff + n * 2048 + k * 1024); } while (0)
; #define PG8_MMA(ai, bj, At, Bt) do { __builtin_amdgcn_s_setprio(1); _Pragma("unroll") for (int m = 0; m < 4; ++m) _Pragma("unroll") for (int n = 0; n < 2; ++n) _Pragma("unroll") for (int k = 0; k < 2; ++k) \
;         acc[ai][bj][m][n] = __builtin_amdgcn_mfma_f32_16x16x32_bf16(Bt[n][k], At[m][k], acc[ai][bj][m][n], 0, 0, 0); __builtin_amdgcn_s_setprio(0); } while (0)
; #define PG8_WAIT_V(n) asm volatile("s_waitcnt vmcnt(" #n ")" ::: "memory")
; #define PG8_WAIT_L(n) asm volatile("s_waitcnt lgkmcnt(" #n ")" ::: "memory")
; #define PG8_BAR __builtin_amdgcn_s_barrier()
; #define PG8_SCHED __builtin_amdgcn_sched_barrier(0)
; template <class Epi, class Sched, bool ALIGN_EPI = false, bool SP2 = false>
; __device__ __forceinline__ void gemm_phase(PG8_LAS unsigned char* lds, const Gemm g, const Sched& S, const Epi& E) {
;     ...
;             PG8_WAIT_V(8); PG8_WAIT_L(0); PG8_BAR; PG8_MMA(1, 0, At, B0); PG8_MMA(1, 1, At, B1); PG8_BAR; PG8_SCHED;
;             PG8_LDB(B0, 1, 0); PG8_LDB(B1, 1, 1); PG8_SCHED; PG8_LDA(At, 1, 0); PG8_STAGE(PG8_SA(0, 1), a2 + hstep, voffA);
;             PG8_WAIT_V(8); PG8_WAIT_L(0); PG8_BAR; PG8_MMA(0, 0, At, B0); PG8_MMA(0, 1, At, B1); PG8_BAR; PG8_SCHED;
	s_setprio 1
	s_waitcnt lgkmcnt(0)
	v_mfma_f32_16x16x32_bf16 v[60:63], v[148:151], v[180:183], v[60:63]
	v_mfma_f32_16x16x32_bf16 v[56:59], v[156:159], v[180:183], v[56:59]
	v_mfma_f32_16x16x32_bf16 v[52:55], v[148:151], v[188:191], v[52:55]
	v_mfma_f32_16x16x32_bf16 v[48:51], v[156:159], v[188:191], v[48:51]
	v_mfma_f32_16x16x32_bf16 v[36:39], v[148:151], v[196:199], v[36:39]
	v_mfma_f32_16x16x32_bf16 v[32:35], v[156:159], v[196:199], v[32:35]
	v_mfma_f32_16x16x32_bf16 v[20:23], v[148:151], v[204:207], v[20:23]
	v_mfma_f32_16x16x32_bf16 v[16:19], v[156:159], v[204:207], v[16:19]
	v_mfma_f32_16x16x32_bf16 v[60:63], v[152:155], v[184:187], v[60:63]
	v_mfma_f32_16x16x32_bf16 v[56:59], v[160:163], v[184:187], v[56:59]
	v_mfma_f32_16x16x32_bf16 v[52:55], v[152:155], v[192:195], v[52:55]
	v_mfma_f32_16x16x32_bf16 v[48:51], v[160:163], v[192:195], v[48:51]
	v_mfma_f32_16x16x32_bf16 v[36:39], v[152:155], v[200:203], v[36:39]
	v_mfma_f32_16x16x32_bf16 v[32:35], v[160:163], v[200:203], v[32:35]
	v_mfma_f32_16x16x32_bf16 v[20:23], v[152:155], v[208:211], v[20:23]
	v_mfma_f32_16x16x32_bf16 v[16:19], v[160:163], v[208:211], v[16:19]
	s_setprio 0
	s_setprio 1
	v_mfma_f32_16x16x32_bf16 v[44:47], v[164:167], v[180:183], v[44:47]
	v_mfma_f32_16x16x32_bf16 v[40:43], v[172:175], v[180:183], v[40:43]
	v_mfma_f32_16x16x32_bf16 v[28:31], v[164:167], v[188:191], v[28:31]
	v_mfma_f32_16x16x32_bf16 v[24:27], v[172:175], v[188:191], v[24:27]
	v_mfma_f32_16x16x32_bf16 v[12:15], v[164:167], v[196:199], v[12:15]
	v_mfma_f32_16x16x32_bf16 v[8:11], v[172:175], v[196:199], v[8:11]
	v_mfma_f32_16x16x32_bf16 v[4:7], v[164:167], v[204:207], v[4:7]
	v_mfma_f32_16x16x32_bf16 v[0:3], v[172:175], v[204:207], v[0:3]
	v_mfma_f32_16x16x32_bf16 v[44:47], v[168:171], v[184:187], v[44:47]
	v_mfma_f32_16x16x32_bf16 v[40:43], v[176:179], v[184:187], v[40:43]
	v_mfma_f32_16x16x32_bf16 v[28:31], v[168:171], v[192:195], v[28:31]
	v_mfma_f32_16x16x32_bf16 v[24:27], v[176:179], v[192:195], v[24:27]
	s_setprio 2
	s_barrier
	v_mfma_f32_16x16x32_bf16 v[12:15], v[168:171], v[200:203], v[12:15]
	v_mfma_f32_16x16x32_bf16 v[8:11], v[176:179], v[200:203], v[8:11]
	v_mfma_f32_16x16x32_bf16 v[4:7], v[168:171], v[208:211], v[4:7]
	v_mfma_f32_16x16x32_bf16 v[0:3], v[176:179], v[208:211], v[0:3]
	s_setprio 0
	v_add_u32_e32 v160, s65, v143
	v_add_u32_e32 v176, s64, v143
	ds_read_b128 v[148:151], v160
	ds_read_b128 v[152:155], v160 offset:1024
	ds_read_b128 v[156:159], v160 offset:2048
	ds_read_b128 v[160:163], v160 offset:3072
	ds_read_b128 v[164:167], v176
	ds_read_b128 v[168:171], v176 offset:1024
	ds_read_b128 v[172:175], v176 offset:2048
	ds_read_b128 v[176:179], v176 offset:3072
	s_mov_b32 m0, s48
	v_lshl_add_u64 v[220:221], s[30:31], 0, v[136:137]
	ds_read_b128 v[180:183], v147 offset:32768
	ds_read_b128 v[184:187], v147 offset:33792
	ds_read_b128 v[188:191], v147 offset:34816
	ds_read_b128 v[192:195], v147 offset:35840
	ds_read_b128 v[196:199], v147 offset:36864
	ds_read_b128 v[200:203], v147 offset:37888
	ds_read_b128 v[204:207], v147 offset:38912
	ds_read_b128 v[208:211], v147 offset:39936
	global_load_lds_dwordx4 v[220:221], off
	v_lshl_add_u64 v[220:221], s[30:31], 0, v[132:133]
	s_mov_b32 m0, s49
	s_nop 0
	global_load_lds_dwordx4 v[220:221], off
	s_waitcnt vmcnt(8)
	s_waitcnt lgkmcnt(0)
	s_barrier
	s_setprio 1
	s_waitcnt lgkmcnt(0)
	v_mfma_f32_16x16x32_bf16 v[124:127], v[148:151], v[180:183], v[124:127]
	v_mfma_f32_16x16x32_bf16 v[120:123], v[156:159], v[180:183], v[120:123]
	v_mfma_f32_16x16x32_bf16 v[116:119], v[148:151], v[188:191], v[116:119]
	v_mfma_f32_16x16x32_bf16 v[112:115], v[156:159], v[188:191], v[112:115]
	v_mfma_f32_16x16x32_bf16 v[100:103], v[148:151], v[196:199], v[100:103]
	v_mfma_f32_16x16x32_bf16 v[96:99], v[156:159], v[196:199], v[96:99]
	v_mfma_f32_16x16x32_bf16 v[84:87], v[148:151], v[204:207], v[84:87]
	v_mfma_f32_16x16x32_bf16 v[80:83], v[156:159], v[204:207], v[80:83]
	v_mfma_f32_16x16x32_bf16 v[124:127], v[152:155], v[184:187], v[124:127]
	v_mfma_f32_16x16x32_bf16 v[120:123], v[160:163], v[184:187], v[120:123]
	v_mfma_f32_16x16x32_bf16 v[116:119], v[152:155], v[192:195], v[116:119]
	v_mfma_f32_16x16x32_bf16 v[112:115], v[160:163], v[192:195], v[112:115]
	v_mfma_f32_16x16x32_bf16 v[100:103], v[152:155], v[200:203], v[100:103]
	v_mfma_f32_16x16x32_bf16 v[96:99], v[160:163], v[200:203], v[96:99]
	v_mfma_f32_16x16x32_bf16 v[84:87], v[152:155], v[208:211], v[84:87]
	v_mfma_f32_16x16x32_bf16 v[80:83], v[160:163], v[208:211], v[80:83]
	s_setprio 0
	s_setprio 1
	v_mfma_f32_16x16x32_bf16 v[108:111], v[164:167], v[180:183], v[108:111]
	v_mfma_f32_16x16x32_bf16 v[104:107], v[172:175], v[180:183], v[104:107]
	v_mfma_f32_16x16x32_bf16 v[92:95], v[164:167], v[188:191], v[92:95]
	v_mfma_f32_16x16x32_bf16 v[88:91], v[172:175], v[188:191], v[88:91]
	v_mfma_f32_16x16x32_bf16 v[76:79], v[164:167], v[196:199], v[76:79]
	v_mfma_f32_16x16x32_bf16 v[72:75], v[172:175], v[196:199], v[72:75]
	v_mfma_f32_16x16x32_bf16 v[68:71], v[164:167], v[204:207], v[68:71]
	v_mfma_f32_16x16x32_bf16 v[64:67], v[172:175], v[204:207], v[64:67]
	v_mfma_f32_16x16x32_bf16 v[108:111], v[168:171], v[184:187], v[108:111]
	v_mfma_f32_16x16x32_bf16 v[104:107], v[176:179], v[184:187], v[104:107]
	v_mfma_f32_16x16x32_bf16 v[92:95], v[168:171], v[192:195], v[92:95]
	v_mfma_f32_16x16x32_bf16 v[88:91], v[176:179], v[192:195], v[88:91]
	s_setprio 2
	s_barrier
; #define PG8_STAGE(bufoff, gbase, voff) do { _Pragma("unroll") for (int _i = 0; _i < 2; ++_i) \
;         __builtin_amdgcn_global_load_lds((const unsigned*)((const char*)(gbase) + (voff)[_i]), (PG8_LAS unsigned*)(lds + (bufoff) + ldsw + _i * 8192), 16, 0, 0); } while (0)
; #define PG8_LDA(dst, b, h) do { _Pragma("unroll") for (int m = 0; m < 4; ++m) _Pragma("unroll") for (int k = 0; k < 2; ++k) dst[m][k] = *(const PG8_LAS bf16x8*)(lds + PG8_SA(b, h) + aoff + m * 2048 + k * 1024); } while (0)
; #define PG8_MMA(ai, bj, At, Bt) do { __builtin_amdgcn_s_setprio(1); _Pragma("unroll") for (int m = 0; m < 4; ++m) _Pragma("unroll") for (int n = 0; n < 2; ++n) _Pragma("unroll") for (int k = 0; k < 2; ++k) \
;         acc[ai][bj][m][n] = __builtin_amdgcn_mfma_f32_16x16x32_bf16(Bt[n][k], At[m][k], acc[ai][bj][m][n], 0, 0, 0); __builtin_amdgcn_s_setprio(0); } while (0)
; #define PG8_WAIT_V(n) asm volatile("s_waitcnt vmcnt(" #n ")" ::: "memory")
; #define PG8_WAIT_L(n) asm volatile("s_waitcnt lgkmcnt(" #n ")" ::: "memory")
; #define PG8_BAR __builtin_amdgcn_s_barrier()
; #define PG8_SCHED __builtin_amdgcn_sched_barrier(0)
; template <class Epi, class Sched, bool ALIGN_EPI = false, bool SP2 = false>
; __device__ __forceinline__ void gemm_phase(PG8_LAS unsigned char* lds, const Gemm g, const Sched& S, const Epi& E) {
;     ...
;             PG8_WAIT_V(8); PG8_WAIT_L(0); PG8_BAR; PG8_MMA(0, 0, At, B0); PG8_MMA(0, 1, At, B1); PG8_BAR; PG8_SCHED;
;             PG8_LDA(At, 1, 1); PG8_STAGE(PG8_SB(1, 0), b3, voffB); PG8_STAGE(PG8_SB(1, 1), b3 + hstep, voffB); PG8_STAGE(PG8_SA(1, 0), a3, voffA);
;             PG8_WAIT_V(8); PG8_WAIT_L(0); PG8_BAR; PG8_MMA(1, 0, At, B0); PG8_MMA(1, 1, At, B1); PG8_BAR; PG8_SCHED;
	v_mfma_f32_16x16x32_bf16 v[76:79], v[168:171], v[200:203], v[76:79]
	v_mfma_f32_16x16x32_bf16 v[72:75], v[176:179], v[200:203], v[72:75]
	v_mfma_f32_16x16x32_bf16 v[68:71], v[168:171], v[208:211], v[68:71]
	v_mfma_f32_16x16x32_bf16 v[64:67], v[176:179], v[208:211], v[64:67]
	s_setprio 0
	s_mov_b32 m0, s63
	v_lshl_add_u64 v[212:213], v[212:213], 0, s[4:5]
	ds_read_b128 v[180:183], v147 offset:49152
	ds_read_b128 v[184:187], v147 offset:50176
	ds_read_b128 v[188:191], v147 offset:51200
	ds_read_b128 v[192:195], v147 offset:52224
	ds_read_b128 v[196:199], v147 offset:53248
	ds_read_b128 v[200:203], v147 offset:54272
	ds_read_b128 v[204:207], v147 offset:55296
	ds_read_b128 v[208:211], v147 offset:56320
	global_load_lds_dwordx4 v[212:213], off
	v_lshl_add_u64 v[212:213], v[214:215], 0, s[4:5]
	s_mov_b32 m0, s61
	s_nop 0
	global_load_lds_dwordx4 v[212:213], off
	v_lshl_add_u64 v[212:213], s[28:29], 0, v[134:135]
	s_mov_b32 m0, s62
	s_nop 0
	global_load_lds_dwordx4 v[212:213], off
	v_lshl_add_u64 v[212:213], s[28:29], 0, v[130:131]
	s_mov_b32 m0, s60
	s_nop 0
	global_load_lds_dwordx4 v[212:213], off
	v_lshl_add_u64 v[212:213], v[216:217], 0, s[4:5]
	s_mov_b32 m0, s52
	s_nop 0
	global_load_lds_dwordx4 v[212:213], off
	v_lshl_add_u64 v[212:213], v[218:219], 0, s[4:5]
	s_mov_b32 m0, s53
	s_nop 0
	global_load_lds_dwordx4 v[212:213], off
	s_waitcnt vmcnt(8)
	s_waitcnt lgkmcnt(0)
	s_barrier
	s_setprio 1
	s_waitcnt lgkmcnt(0)
	v_mfma_f32_16x16x32_bf16 v[60:63], v[148:151], v[180:183], v[60:63]
	v_mfma_f32_16x16x32_bf16 v[56:59], v[156:159], v[180:183], v[56:59]
	v_mfma_f32_16x16x32_bf16 v[52:55], v[148:151], v[188:191], v[52:55]
	v_mfma_f32_16x16x32_bf16 v[48:51], v[156:159], v[188:191], v[48:51]
	v_mfma_f32_16x16x32_bf16 v[36:39], v[148:151], v[196:199], v[36:39]
	v_mfma_f32_16x16x32_bf16 v[32:35], v[156:159], v[196:199], v[32:35]
	v_mfma_f32_16x16x32_bf16 v[20:23], v[148:151], v[204:207], v[20:23]
	v_mfma_f32_16x16x32_bf16 v[16:19], v[156:159], v[204:207], v[16:19]
	v_mfma_f32_16x16x32_bf16 v[60:63], v[152:155], v[184:187], v[60:63]
	v_mfma_f32_16x16x32_bf16 v[56:59], v[160:163], v[184:187], v[56:59]
	v_mfma_f32_16x16x32_bf16 v[52:55], v[152:155], v[192:195], v[52:55]
	v_mfma_f32_16x16x32_bf16 v[48:51], v[160:163], v[192:195], v[48:51]
	v_mfma_f32_16x16x32_bf16 v[36:39], v[152:155], v[200:203], v[36:39]
	v_mfma_f32_16x16x32_bf16 v[32:35], v[160:163], v[200:203], v[32:35]
	v_mfma_f32_16x16x32_bf16 v[20:23], v[152:155], v[208:211], v[20:23]
	v_mfma_f32_16x16x32_bf16 v[16:19], v[160:163], v[208:211], v[16:19]
	s_setprio 0
	s_setprio 1
	v_mfma_f32_16x16x32_bf16 v[44:47], v[164:167], v[180:183], v[44:47]
	v_mfma_f32_16x16x32_bf16 v[40:43], v[172:175], v[180:183], v[40:43]
	v_mfma_f32_16x16x32_bf16 v[28:31], v[164:167], v[188:191], v[28:31]
	v_mfma_f32_16x16x32_bf16 v[24:27], v[172:175], v[188:191], v[24:27]
	v_mfma_f32_16x16x32_bf16 v[12:15], v[164:167], v[196:199], v[12:15]
	v_mfma_f32_16x16x32_bf16 v[8:11], v[172:175], v[196:199], v[8:11]
	v_mfma_f32_16x16x32_bf16 v[4:7], v[164:167], v[204:207], v[4:7]
	v_mfma_f32_16x16x32_bf16 v[0:3], v[172:175], v[204:207], v[0:3]
	v_mfma_f32_16x16x32_bf16 v[44:47], v[168:171], v[184:187], v[44:47]
	v_mfma_f32_16x16x32_bf16 v[40:43], v[176:179], v[184:187], v[40:43]
	v_mfma_f32_16x16x32_bf16 v[28:31], v[168:171], v[192:195], v[28:31]
	v_mfma_f32_16x16x32_bf16 v[24:27], v[176:179], v[192:195], v[24:27]
	s_setprio 2
	s_barrier
	v_mfma_f32_16x16x32_bf16 v[12:15], v[168:171], v[200:203], v[12:15]
	v_mfma_f32_16x16x32_bf16 v[8:11], v[176:179], v[200:203], v[8:11]
	v_mfma_f32_16x16x32_bf16 v[4:7], v[168:171], v[208:211], v[4:7]
	v_mfma_f32_16x16x32_bf16 v[0:3], v[176:179], v[208:211], v[0:3]
	s_setprio 0
	s_movk_i32 s30, 0x100
	s_andn2_b64 vcc, exec, s[26:27]
	s_mov_b64 s[28:29], -1
	s_mov_b64 s[26:27], 0
	s_cbranch_vccz .LBB0_835
	s_and_b64 vcc, exec, s[10:11]
	s_cbranch_vccz .LBB0_838
	s_barrier

;     __host__ __device__ bool next(int i, Unit& u) const { return (i + I0 < I1) && StaticOrder::next(i + I0, u); }
; #define PG8_STAGE(bufoff, gbase, voff) do { _Pragma("unroll") for (int _i = 0; _i < 2; ++_i) \
;         __builtin_amdgcn_global_load_lds((const unsigned*)((const char*)(gbase) + (voff)[_i]), (PG8_LAS unsigned*)(lds + (bufoff) + ldsw + _i * 8192), 16, 0, 0); } while (0)
; #define PG8_LDA(dst, b, h) do { _Pragma("unroll") for (int m = 0; m < 4; ++m) _Pragma("unroll") for (int k = 0; k < 2; ++k) dst[m][k] = *(const PG8_LAS bf16x8*)(lds + PG8_SA(b, h) + aoff + m * 2048 + k * 1024); } while (0)
; #define PG8_LDB(dst, b, h) do { _Pragma("unroll") for (int n = 0; n < 2; ++n) _Pragma("unroll") for (int k = 0; k < 2; ++k) dst[n][k] = *(const PG8_LAS bf16x8*)(lds + PG8_SB(b, h) + boff + n * 2048 + k * 1024); } while (0)
; #define PG8_WAIT_V(n) asm volatile("s_waitcnt vmcnt(" #n ")" ::: "memory")
; #define PG8_WAIT_L(n) asm volatile("s_waitcnt lgkmcnt(" #n ")" ::: "memory")
; #define PG8_BAR __builtin_amdgcn_s_barrier()
; #define PG8_SCHED __builtin_amdgcn_sched_barrier(0)
; template <class Epi, class Sched, bool ALIGN_EPI = false, bool SP2 = false>
; __device__ __forceinline__ void gemm_phase(PG8_LAS unsigned char* lds, const Gemm g, const Sched& S, const Epi& E) {
;     ...
;         const bool has_next = S.next(ui + 1, nxt);
;         const char* nA = has_next ? (const char*)g.A + (size_t)nxt.pm * tstep : cA; const char* nB = has_next ? (const char*)g.Bt + (size_t)nxt.pn * tstep : cB;
;         for (int t = 0; t < nt; t += 2) {
;             const bool last = (t == nt - 2);
;             const char* a1 = cA + (size_t)(t + 1) * kstep;
;             const char* a2 = last ? nA : cA + (size_t)(t + 2) * kstep; const char* b2 = last ? nB : cB + (size_t)(t + 2) * kstep;
;             const char* a3 = a2 + kstep; const char* b3 = b2 + kstep;
;             if (last && has_next) S.a_ready(nxt);
;             if constexpr (SP2) {
;             PG8_LDB(B0, 0, 0); PG8_LDB(B1, 0, 1); PG8_SCHED; PG8_LDA(At, 0, 0); PG8_STAGE(PG8_SA(1, 1), a1 + hstep, voffA);
;             PG8_WAIT_V(8); PG8_WAIT_L(0); PG8_BAR; PG8_MMA(0, 0, At, B0); PG8_MMA(0, 1, At, B1); PG8_BAR; PG8_SCHED;
;             PG8_LDA(At, 0, 1); PG8_STAGE(PG8_SB(0, 0), b2, voffB); PG8_STAGE(PG8_SB(0, 1), b2 + hstep, voffB); PG8_STAGE(PG8_SA(0, 0), a2, voffA);
.LBB0_966:
	ds_read_b128 v[146:149], v153
	ds_read_b128 v[156:159], v153 offset:1024
	ds_read_b128 v[160:163], v153 offset:2048
	ds_read_b128 v[164:167], v153 offset:3072
	ds_read_b128 v[168:171], v154
	ds_read_b128 v[172:175], v154 offset:1024
	ds_read_b128 v[176:179], v154 offset:2048
	ds_read_b128 v[180:183], v154 offset:3072
	s_add_u32 s24, s22, 0xfff80080
	s_addc_u32 s25, s23, -1
	s_cmp_eq_u32 s52, 28
	s_cselect_b32 s27, s15, s25
	s_cselect_b32 s26, s45, s24
	s_cselect_b32 s25, s13, s51
	s_cselect_b32 s24, s46, s47
	v_lshl_add_u64 v[216:217], s[22:23], 0, v[138:139]
	s_add_i32 m0, s21, 0xc000
	ds_read_b128 v[184:187], v155
	ds_read_b128 v[188:191], v155 offset:1024
	ds_read_b128 v[192:195], v155 offset:2048
	ds_read_b128 v[196:199], v155 offset:3072
	ds_read_b128 v[200:203], v155 offset:4096
	ds_read_b128 v[204:207], v155 offset:5120
	ds_read_b128 v[208:211], v155 offset:6144
	ds_read_b128 v[212:215], v155 offset:7168
	global_load_lds_dwordx4 v[216:217], off
	v_lshl_add_u64 v[216:217], s[22:23], 0, v[140:141]
	s_add_i32 m0, s21, 0xe000
	s_nop 0
	global_load_lds_dwordx4 v[216:217], off
	s_waitcnt vmcnt(8)
	s_waitcnt lgkmcnt(0)
	s_barrier
	s_setprio 1
	s_waitcnt lgkmcnt(0)
	v_mfma_f32_16x16x32_bf16 v[124:127], v[146:149], v[184:187], v[124:127]
	v_mfma_f32_16x16x32_bf16 v[116:119], v[160:163], v[184:187], v[116:119]
	v_mfma_f32_16x16x32_bf16 v[108:111], v[146:149], v[192:195], v[108:111]
	v_mfma_f32_16x16x32_bf16 v[100:103], v[160:163], v[192:195], v[100:103]
	v_mfma_f32_16x16x32_bf16 v[92:95], v[146:149], v[200:203], v[92:95]
	v_mfma_f32_16x16x32_bf16 v[84:87], v[160:163], v[200:203], v[84:87]
	v_mfma_f32_16x16x32_bf16 v[76:79], v[146:149], v[208:211], v[76:79]
	v_mfma_f32_16x16x32_bf16 v[68:71], v[160:163], v[208:211], v[68:71]
	v_mfma_f32_16x16x32_bf16 v[124:127], v[156:159], v[188:191], v[124:127]
	v_mfma_f32_16x16x32_bf16 v[116:119], v[164:167], v[188:191], v[116:119]
	v_mfma_f32_16x16x32_bf16 v[108:111], v[156:159], v[196:199], v[108:111]
	v_mfma_f32_16x16x32_bf16 v[100:103], v[164:167], v[196:199], v[100:103]
	v_mfma_f32_16x16x32_bf16 v[92:95], v[156:159], v[204:207], v[92:95]
	v_mfma_f32_16x16x32_bf16 v[84:87], v[164:167], v[204:207], v[84:87]
	v_mfma_f32_16x16x32_bf16 v[76:79], v[156:159], v[212:215], v[76:79]
	v_mfma_f32_16x16x32_bf16 v[68:71], v[164:167], v[212:215], v[68:71]
	s_setprio 0
	s_setprio 1
	v_mfma_f32_16x16x32_bf16 v[120:123], v[168:171], v[184:187], v[120:123]
	v_mfma_f32_16x16x32_bf16 v[112:115], v[176:179], v[184:187], v[112:115]
	v_mfma_f32_16x16x32_bf16 v[104:107], v[168:171], v[192:195], v[104:107]
	v_mfma_f32_16x16x32_bf16 v[96:99], v[176:179], v[192:195], v[96:99]
	v_mfma_f32_16x16x32_bf16 v[88:91], v[168:171], v[200:203], v[88:91]
	v_mfma_f32_16x16x32_bf16 v[80:83], v[176:179], v[200:203], v[80:83]
	v_mfma_f32_16x16x32_bf16 v[72:75], v[168:171], v[208:211], v[72:75]
	v_mfma_f32_16x16x32_bf16 v[64:67], v[176:179], v[208:211], v[64:67]
	v_mfma_f32_16x16x32_bf16 v[120:123], v[172:175], v[188:191], v[120:123]
	v_mfma_f32_16x16x32_bf16 v[112:115], v[180:183], v[188:191], v[112:115]
	v_mfma_f32_16x16x32_bf16 v[104:107], v[172:175], v[196:199], v[104:107]
	v_mfma_f32_16x16x32_bf16 v[96:99], v[180:183], v[196:199], v[96:99]
	s_setprio 2
	s_barrier
	v_mfma_f32_16x16x32_bf16 v[88:91], v[172:175], v[204:207], v[88:91]
	v_mfma_f32_16x16x32_bf16 v[80:83], v[180:183], v[204:207], v[80:83]
	v_mfma_f32_16x16x32_bf16 v[72:75], v[172:175], v[212:215], v[72:75]
	v_mfma_f32_16x16x32_bf16 v[64:67], v[180:183], v[212:215], v[64:67]
	s_setprio 0
	s_add_i32 s53, s41, s28
	v_lshl_add_u64 v[216:217], s[24:25], 0, v[134:135]
	s_mov_b32 m0, s53
	ds_read_b128 v[184:187], v155 offset:16384
	ds_read_b128 v[188:191], v155 offset:17408
	ds_read_b128 v[192:195], v155 offset:18432
	ds_read_b128 v[196:199], v155 offset:19456
	ds_read_b128 v[200:203], v155 offset:20480
	ds_read_b128 v[204:207], v155 offset:21504
	ds_read_b128 v[208:211], v155 offset:22528
	ds_read_b128 v[212:215], v155 offset:23552
	global_load_lds_dwordx4 v[216:217], off
	s_add_i32 m0, s53, 0x2000
	s_add_u32 s54, s24, 0x80000
	v_lshl_add_u64 v[218:219], s[24:25], 0, v[130:131]
	s_addc_u32 s55, s25, 0
	s_add_i32 s53, s42, s28
	global_load_lds_dwordx4 v[218:219], off
	v_lshl_add_u64 v[220:221], s[54:55], 0, v[134:135]
	s_mov_b32 m0, s53
	v_lshl_add_u64 v[222:223], s[26:27], 0, v[132:133]
	global_load_lds_dwordx4 v[220:221], off
	v_lshl_add_u64 v[220:221], s[54:55], 0, v[130:131]
	s_add_i32 m0, s53, 0x2000
	s_nop 0
	global_load_lds_dwordx4 v[220:221], off
	v_lshl_add_u64 v[220:221], s[26:27], 0, v[136:137]
	s_mov_b32 m0, s21
	s_nop 0
	global_load_lds_dwordx4 v[220:221], off
	s_mov_b32 m0, s31
	s_nop 0
	global_load_lds_dwordx4 v[222:223], off
	s_waitcnt vmcnt(8)
	s_waitcnt lgkmcnt(0)
	s_barrier
; #define PG8_STAGE(bufoff, gbase, voff) do { _Pragma("unroll") for (int _i = 0; _i < 2; ++_i) \
;         __builtin_amdgcn_global_load_lds((const unsigned*)((const char*)(gbase) + (voff)[_i]), (PG8_LAS unsigned*)(lds + (bufoff) + ldsw + _i * 8192), 16, 0, 0); } while (0)
; #define PG8_LDA(dst, b, h) do { _Pragma("unroll") for (int m = 0; m < 4; ++m) _Pragma("unroll") for (int k = 0; k < 2; ++k) dst[m][k] = *(const PG8_LAS bf16x8*)(lds + PG8_SA(b, h) + aoff + m * 2048 + k * 1024); } while (0)
; #define PG8_LDB(dst, b, h) do { _Pragma("unroll") for (int n = 0; n < 2; ++n) _Pragma("unroll") for (int k = 0; k < 2; ++k) dst[n][k] = *(const PG8_LAS bf16x8*)(lds + PG8_SB(b, h) + boff + n * 2048 + k * 1024); } while (0)
; #define PG8_MMA(ai, bj, At, Bt) do { __builtin_amdgcn_s_setprio(1); _Pragma("unroll") for (int m = 0; m < 4; ++m) _Pragma("unroll") for (int n = 0; n < 2; ++n) _Pragma("unroll") for (int k = 0; k < 2; ++k) \
;         acc[ai][bj][m][n] = __builtin_amdgcn_mfma_f32_16x16x32_bf16(Bt[n][k], At[m][k], acc[ai][bj][m][n], 0, 0, 0); __builtin_amdgcn_s_setprio(0); } while (0)
; #define PG8_WAIT_V(n) asm volatile("s_waitcnt vmcnt(" #n ")" ::: "memory")
; #define PG8_WAIT_L(n) asm volatile("s_waitcnt lgkmcnt(" #n ")" ::: "memory")
; #define PG8_BAR __builtin_amdgcn_s_barrier()
; #define PG8_SCHED __builtin_amdgcn_sched_barrier(0)
; template <class Epi, class Sched, bool ALIGN_EPI = false, bool SP2 = false>
; __device__ __forceinline__ void gemm_phase(PG8_LAS unsigned char* lds, const Gemm g, const Sched& S, const Epi& E) {
;     ...
;             PG8_WAIT_V(8); PG8_WAIT_L(0); PG8_BAR; PG8_MMA(1, 0, At, B0); PG8_MMA(1, 1, At, B1); PG8_BAR; PG8_SCHED;
;             PG8_LDB(B0, 1, 0); PG8_LDB(B1, 1, 1); PG8_SCHED; PG8_LDA(At, 1, 0); PG8_STAGE(PG8_SA(0, 1), a2 + hstep, voffA);
;             PG8_WAIT_V(8); PG8_WAIT_L(0); PG8_BAR; PG8_MMA(0, 0, At, B0); PG8_MMA(0, 1, At, B1); PG8_BAR; PG8_SCHED;
	s_setprio 1
	s_waitcnt lgkmcnt(0)
	v_mfma_f32_16x16x32_bf16 v[60:63], v[146:149], v[184:187], v[60:63]
	v_mfma_f32_16x16x32_bf16 v[52:55], v[160:163], v[184:187], v[52:55]
	v_mfma_f32_16x16x32_bf16 v[44:47], v[146:149], v[192:195], v[44:47]
	v_mfma_f32_16x16x32_bf16 v[36:39], v[160:163], v[192:195], v[36:39]
	v_mfma_f32_16x16x32_bf16 v[28:31], v[146:149], v[200:203], v[28:31]
	v_mfma_f32_16x16x32_bf16 v[20:23], v[160:163], v[200:203], v[20:23]
	v_mfma_f32_16x16x32_bf16 v[12:15], v[146:149], v[208:211], v[12:15]
	v_mfma_f32_16x16x32_bf16 v[4:7], v[160:163], v[208:211], v[4:7]
	v_mfma_f32_16x16x32_bf16 v[60:63], v[156:159], v[188:191], v[60:63]
	v_mfma_f32_16x16x32_bf16 v[52:55], v[164:167], v[188:191], v[52:55]
	v_mfma_f32_16x16x32_bf16 v[44:47], v[156:159], v[196:199], v[44:47]
	v_mfma_f32_16x16x32_bf16 v[36:39], v[164:167], v[196:199], v[36:39]
	v_mfma_f32_16x16x32_bf16 v[28:31], v[156:159], v[204:207], v[28:31]
	v_mfma_f32_16x16x32_bf16 v[20:23], v[164:167], v[204:207], v[20:23]
	v_mfma_f32_16x16x32_bf16 v[12:15], v[156:159], v[212:215], v[12:15]
	v_mfma_f32_16x16x32_bf16 v[4:7], v[164:167], v[212:215], v[4:7]
	s_setprio 0
	s_setprio 1
	v_mfma_f32_16x16x32_bf16 v[56:59], v[168:171], v[184:187], v[56:59]
	v_mfma_f32_16x16x32_bf16 v[48:51], v[176:179], v[184:187], v[48:51]
	v_mfma_f32_16x16x32_bf16 v[40:43], v[168:171], v[192:195], v[40:43]
	v_mfma_f32_16x16x32_bf16 v[32:35], v[176:179], v[192:195], v[32:35]
	v_mfma_f32_16x16x32_bf16 v[24:27], v[168:171], v[200:203], v[24:27]
	v_mfma_f32_16x16x32_bf16 v[16:19], v[176:179], v[200:203], v[16:19]
	v_mfma_f32_16x16x32_bf16 v[8:11], v[168:171], v[208:211], v[8:11]
	v_mfma_f32_16x16x32_bf16 v[0:3], v[176:179], v[208:211], v[0:3]
	v_mfma_f32_16x16x32_bf16 v[56:59], v[172:175], v[188:191], v[56:59]
	v_mfma_f32_16x16x32_bf16 v[48:51], v[180:183], v[188:191], v[48:51]
	v_mfma_f32_16x16x32_bf16 v[40:43], v[172:175], v[196:199], v[40:43]
	v_mfma_f32_16x16x32_bf16 v[32:35], v[180:183], v[196:199], v[32:35]
	s_setprio 2
	s_barrier
	v_mfma_f32_16x16x32_bf16 v[24:27], v[172:175], v[204:207], v[24:27]
	v_mfma_f32_16x16x32_bf16 v[16:19], v[180:183], v[204:207], v[16:19]
	v_mfma_f32_16x16x32_bf16 v[8:11], v[172:175], v[212:215], v[8:11]
	v_mfma_f32_16x16x32_bf16 v[0:3], v[180:183], v[212:215], v[0:3]
	s_setprio 0
	s_add_i32 s53, 0, 0x18000
	s_add_i32 s54, 0, 0x1c000
	v_add_u32_e32 v164, s53, v151
	v_add_u32_e32 v180, s54, v151
	ds_read_b128 v[146:149], v164
	ds_read_b128 v[156:159], v164 offset:1024
	ds_read_b128 v[160:163], v164 offset:2048
	ds_read_b128 v[164:167], v164 offset:3072
	ds_read_b128 v[168:171], v180
	ds_read_b128 v[172:175], v180 offset:1024
	ds_read_b128 v[176:179], v180 offset:2048
	ds_read_b128 v[180:183], v180 offset:3072
	s_add_u32 s26, s26, 0x80000
	s_addc_u32 s27, s27, 0
	s_mov_b32 m0, s34
	v_lshl_add_u64 v[224:225], s[26:27], 0, v[136:137]
	ds_read_b128 v[184:187], v155 offset:32768
	ds_read_b128 v[188:191], v155 offset:33792
	ds_read_b128 v[192:195], v155 offset:34816
	ds_read_b128 v[196:199], v155 offset:35840
	ds_read_b128 v[200:203], v155 offset:36864
	ds_read_b128 v[204:207], v155 offset:37888
	ds_read_b128 v[208:211], v155 offset:38912
	ds_read_b128 v[212:215], v155 offset:39936
	global_load_lds_dwordx4 v[224:225], off
	v_lshl_add_u64 v[224:225], s[26:27], 0, v[132:133]
	s_mov_b32 m0, s35
	s_nop 0
	global_load_lds_dwordx4 v[224:225], off
	s_waitcnt vmcnt(8)
	s_waitcnt lgkmcnt(0)
	s_barrier
	s_setprio 1
	s_waitcnt lgkmcnt(0)
	v_mfma_f32_16x16x32_bf16 v[124:127], v[146:149], v[184:187], v[124:127]
	v_mfma_f32_16x16x32_bf16 v[116:119], v[160:163], v[184:187], v[116:119]
	v_mfma_f32_16x16x32_bf16 v[108:111], v[146:149], v[192:195], v[108:111]
	v_mfma_f32_16x16x32_bf16 v[100:103], v[160:163], v[192:195], v[100:103]
	v_mfma_f32_16x16x32_bf16 v[92:95], v[146:149], v[200:203], v[92:95]
	v_mfma_f32_16x16x32_bf16 v[84:87], v[160:163], v[200:203], v[84:87]
	v_mfma_f32_16x16x32_bf16 v[76:79], v[146:149], v[208:211], v[76:79]
	v_mfma_f32_16x16x32_bf16 v[68:71], v[160:163], v[208:211], v[68:71]
	v_mfma_f32_16x16x32_bf16 v[124:127], v[156:159], v[188:191], v[124:127]
	v_mfma_f32_16x16x32_bf16 v[116:119], v[164:167], v[188:191], v[116:119]
	v_mfma_f32_16x16x32_bf16 v[108:111], v[156:159], v[196:199], v[108:111]
	v_mfma_f32_16x16x32_bf16 v[100:103], v[164:167], v[196:199], v[100:103]
	v_mfma_f32_16x16x32_bf16 v[92:95], v[156:159], v[204:207], v[92:95]
	v_mfma_f32_16x16x32_bf16 v[84:87], v[164:167], v[204:207], v[84:87]
	v_mfma_f32_16x16x32_bf16 v[76:79], v[156:159], v[212:215], v[76:79]
	v_mfma_f32_16x16x32_bf16 v[68:71], v[164:167], v[212:215], v[68:71]
	s_setprio 0
	s_setprio 1
	v_mfma_f32_16x16x32_bf16 v[120:123], v[168:171], v[184:187], v[120:123]
	v_mfma_f32_16x16x32_bf16 v[112:115], v[176:179], v[184:187], v[112:115]
	v_mfma_f32_16x16x32_bf16 v[104:107], v[168:171], v[192:195], v[104:107]
	v_mfma_f32_16x16x32_bf16 v[96:99], v[176:179], v[192:195], v[96:99]
	v_mfma_f32_16x16x32_bf16 v[88:91], v[168:171], v[200:203], v[88:91]
	v_mfma_f32_16x16x32_bf16 v[80:83], v[176:179], v[200:203], v[80:83]
	v_mfma_f32_16x16x32_bf16 v[72:75], v[168:171], v[208:211], v[72:75]
	v_mfma_f32_16x16x32_bf16 v[64:67], v[176:179], v[208:211], v[64:67]
	v_mfma_f32_16x16x32_bf16 v[120:123], v[172:175], v[188:191], v[120:123]
	v_mfma_f32_16x16x32_bf16 v[112:115], v[180:183], v[188:191], v[112:115]
	v_mfma_f32_16x16x32_bf16 v[104:107], v[172:175], v[196:199], v[104:107]
	v_mfma_f32_16x16x32_bf16 v[96:99], v[180:183], v[196:199], v[96:99]
	s_setprio 2
	s_barrier
; #define PG8_STAGE(bufoff, gbase, voff) do { _Pragma("unroll") for (int _i = 0; _i < 2; ++_i) \
;         __builtin_amdgcn_global_load_lds((const unsigned*)((const char*)(gbase) + (voff)[_i]), (PG8_LAS unsigned*)(lds + (bufoff) + ldsw + _i * 8192), 16, 0, 0); } while (0)
; #define PG8_LDA(dst, b, h) do { _Pragma("unroll") for (int m = 0; m < 4; ++m) _Pragma("unroll") for (int k = 0; k < 2; ++k) dst[m][k] = *(const PG8_LAS bf16x8*)(lds + PG8_SA(b, h) + aoff + m * 2048 + k * 1024); } while (0)
; #define PG8_MMA(ai, bj, At, Bt) do { __builtin_amdgcn_s_setprio(1); _Pragma("unroll") for (int m = 0; m < 4; ++m) _Pragma("unroll") for (int n = 0; n < 2; ++n) _Pragma("unroll") for (int k = 0; k < 2; ++k) \
;         acc[ai][bj][m][n] = __builtin_amdgcn_mfma_f32_16x16x32_bf16(Bt[n][k], At[m][k], acc[ai][bj][m][n], 0, 0, 0); __builtin_amdgcn_s_setprio(0); } while (0)
; #define PG8_WAIT_V(n) asm volatile("s_waitcnt vmcnt(" #n ")" ::: "memory")
; #define PG8_WAIT_L(n) asm volatile("s_waitcnt lgkmcnt(" #n ")" ::: "memory")
; #define PG8_BAR __builtin_amdgcn_s_barrier()
; #define PG8_SCHED __builtin_amdgcn_sched_barrier(0)
; template <class Epi, class Sched, bool ALIGN_EPI = false, bool SP2 = false>
; __device__ __forceinline__ void gemm_phase(PG8_LAS unsigned char* lds, const Gemm g, const Sched& S, const Epi& E) {
;     ...
;             PG8_WAIT_V(8); PG8_WAIT_L(0); PG8_BAR; PG8_MMA(0, 0, At, B0); PG8_MMA(0, 1, At, B1); PG8_BAR; PG8_SCHED;
;             PG8_LDA(At, 1, 1); PG8_STAGE(PG8_SB(1, 0), b3, voffB); PG8_STAGE(PG8_SB(1, 1), b3 + hstep, voffB); PG8_STAGE(PG8_SA(1, 0), a3, voffA);
;             PG8_WAIT_V(8); PG8_WAIT_L(0); PG8_BAR; PG8_MMA(1, 0, At, B0); PG8_MMA(1, 1, At, B1); PG8_BAR; PG8_SCHED;
	v_mfma_f32_16x16x32_bf16 v[88:91], v[172:175], v[204:207], v[88:91]
	v_mfma_f32_16x16x32_bf16 v[80:83], v[180:183], v[204:207], v[80:83]
	v_mfma_f32_16x16x32_bf16 v[72:75], v[172:175], v[212:215], v[72:75]
	v_mfma_f32_16x16x32_bf16 v[64:67], v[180:183], v[212:215], v[64:67]
	s_setprio 0
	s_add_i32 s26, s53, s28
	v_lshl_add_u64 v[216:217], v[216:217], 0, s[4:5]
	s_mov_b32 m0, s26
	ds_read_b128 v[184:187], v155 offset:49152
	ds_read_b128 v[188:191], v155 offset:50176
	ds_read_b128 v[192:195], v155 offset:51200
	ds_read_b128 v[196:199], v155 offset:52224
	ds_read_b128 v[200:203], v155 offset:53248
	ds_read_b128 v[204:207], v155 offset:54272
	ds_read_b128 v[208:211], v155 offset:55296
	ds_read_b128 v[212:215], v155 offset:56320
	global_load_lds_dwordx4 v[216:217], off
	s_add_i32 m0, s26, 0x2000
	s_add_u32 s24, s24, 0x80080
	v_lshl_add_u64 v[216:217], v[218:219], 0, s[4:5]
	s_addc_u32 s25, s25, 0
	s_add_i32 s26, s54, s28
	global_load_lds_dwordx4 v[216:217], off
	v_lshl_add_u64 v[216:217], s[24:25], 0, v[134:135]
	s_mov_b32 m0, s26
	s_nop 0
	global_load_lds_dwordx4 v[216:217], off
	v_lshl_add_u64 v[216:217], s[24:25], 0, v[130:131]
	s_add_i32 m0, s26, 0x2000
	s_nop 0
	global_load_lds_dwordx4 v[216:217], off
	v_lshl_add_u64 v[216:217], v[220:221], 0, s[4:5]
	s_mov_b32 m0, s37
	s_nop 0
	global_load_lds_dwordx4 v[216:217], off
	v_lshl_add_u64 v[216:217], v[222:223], 0, s[4:5]
	s_mov_b32 m0, s38
	s_nop 0
	global_load_lds_dwordx4 v[216:217], off
	s_waitcnt vmcnt(8)
	s_waitcnt lgkmcnt(0)
	s_barrier
	s_setprio 1
	s_waitcnt lgkmcnt(0)
	v_mfma_f32_16x16x32_bf16 v[60:63], v[146:149], v[184:187], v[60:63]
	v_mfma_f32_16x16x32_bf16 v[52:55], v[160:163], v[184:187], v[52:55]
	v_mfma_f32_16x16x32_bf16 v[44:47], v[146:149], v[192:195], v[44:47]
	v_mfma_f32_16x16x32_bf16 v[36:39], v[160:163], v[192:195], v[36:39]
	v_mfma_f32_16x16x32_bf16 v[28:31], v[146:149], v[200:203], v[28:31]
	v_mfma_f32_16x16x32_bf16 v[20:23], v[160:163], v[200:203], v[20:23]
	v_mfma_f32_16x16x32_bf16 v[12:15], v[146:149], v[208:211], v[12:15]
	v_mfma_f32_16x16x32_bf16 v[4:7], v[160:163], v[208:211], v[4:7]
	v_mfma_f32_16x16x32_bf16 v[60:63], v[156:159], v[188:191], v[60:63]
	v_mfma_f32_16x16x32_bf16 v[52:55], v[164:167], v[188:191], v[52:55]
	v_mfma_f32_16x16x32_bf16 v[44:47], v[156:159], v[196:199], v[44:47]
	v_mfma_f32_16x16x32_bf16 v[36:39], v[164:167], v[196:199], v[36:39]
	v_mfma_f32_16x16x32_bf16 v[28:31], v[156:159], v[204:207], v[28:31]
	v_mfma_f32_16x16x32_bf16 v[20:23], v[164:167], v[204:207], v[20:23]
	v_mfma_f32_16x16x32_bf16 v[12:15], v[156:159], v[212:215], v[12:15]
	v_mfma_f32_16x16x32_bf16 v[4:7], v[164:167], v[212:215], v[4:7]
	s_setprio 0
	s_setprio 1
	v_mfma_f32_16x16x32_bf16 v[56:59], v[168:171], v[184:187], v[56:59]
	v_mfma_f32_16x16x32_bf16 v[48:51], v[176:179], v[184:187], v[48:51]
	v_mfma_f32_16x16x32_bf16 v[40:43], v[168:171], v[192:195], v[40:43]
	v_mfma_f32_16x16x32_bf16 v[32:35], v[176:179], v[192:195], v[32:35]
	v_mfma_f32_16x16x32_bf16 v[24:27], v[168:171], v[200:203], v[24:27]
	v_mfma_f32_16x16x32_bf16 v[16:19], v[176:179], v[200:203], v[16:19]
	v_mfma_f32_16x16x32_bf16 v[8:11], v[168:171], v[208:211], v[8:11]
	v_mfma_f32_16x16x32_bf16 v[0:3], v[176:179], v[208:211], v[0:3]
	v_mfma_f32_16x16x32_bf16 v[56:59], v[172:175], v[188:191], v[56:59]
	v_mfma_f32_16x16x32_bf16 v[48:51], v[180:183], v[188:191], v[48:51]
	v_mfma_f32_16x16x32_bf16 v[40:43], v[172:175], v[196:199], v[40:43]
	v_mfma_f32_16x16x32_bf16 v[32:35], v[180:183], v[196:199], v[32:35]
	s_setprio 2
	s_barrier
	v_mfma_f32_16x16x32_bf16 v[24:27], v[172:175], v[204:207], v[24:27]
	v_mfma_f32_16x16x32_bf16 v[16:19], v[180:183], v[204:207], v[16:19]
	v_mfma_f32_16x16x32_bf16 v[8:11], v[172:175], v[212:215], v[8:11]
	v_mfma_f32_16x16x32_bf16 v[0:3], v[180:183], v[212:215], v[0:3]
	s_setprio 0
	s_add_i32 s52, s52, 2
	s_add_u32 s22, s22, 0x100
	s_addc_u32 s23, s23, 0
	s_add_u32 s47, s47, 0x100
	s_addc_u32 s51, s51, 0
	s_cmp_gt_u32 s52, 29
	s_cbranch_scc0 .LBB0_966
	s_and_b64 vcc, exec, s[10:11]
	s_cbranch_vccz .LBB0_969
	s_barrier

;     __host__ __device__ bool next(int i, Unit& u) const { return (i + I0 < I1) && StaticOrder::next(i + I0, u); }
; #define PG8_STAGE(bufoff, gbase, voff) do { _Pragma("unroll") for (int _i = 0; _i < 2; ++_i) \
;         __builtin_amdgcn_global_load_lds((const unsigned*)((const char*)(gbase) + (voff)[_i]), (PG8_LAS unsigned*)(lds + (bufoff) + ldsw + _i * 8192), 16, 0, 0); } while (0)
; #define PG8_LDA(dst, b, h) do { _Pragma("unroll") for (int m = 0; m < 4; ++m) _Pragma("unroll") for (int k = 0; k < 2; ++k) dst[m][k] = *(const PG8_LAS bf16x8*)(lds + PG8_SA(b, h) + aoff + m * 2048 + k * 1024); } while (0)
; #define PG8_LDB(dst, b, h) do { _Pragma("unroll") for (int n = 0; n < 2; ++n) _Pragma("unroll") for (int k = 0; k < 2; ++k) dst[n][k] = *(const PG8_LAS bf16x8*)(lds + PG8_SB(b, h) + boff + n * 2048 + k * 1024); } while (0)
; #define PG8_WAIT_V(n) asm volatile("s_waitcnt vmcnt(" #n ")" ::: "memory")
; #define PG8_WAIT_L(n) asm volatile("s_waitcnt lgkmcnt(" #n ")" ::: "memory")
; #define PG8_BAR __builtin_amdgcn_s_barrier()
; #define PG8_SCHED __builtin_amdgcn_sched_barrier(0)
; template <class Epi, class Sched, bool ALIGN_EPI = false, bool SP2 = false>
; __device__ __forceinline__ void gemm_phase(PG8_LAS unsigned char* lds, const Gemm g, const Sched& S, const Epi& E) {
;     ...
;         const bool has_next = S.next(ui + 1, nxt);
;         const char* nA = has_next ? (const char*)g.A + (size_t)nxt.pm * tstep : cA; const char* nB = has_next ? (const char*)g.Bt + (size_t)nxt.pn * tstep : cB;
;         for (int t = 0; t < nt; t += 2) {
;             const bool last = (t == nt - 2);
;             const char* a1 = cA + (size_t)(t + 1) * kstep;
;             const char* a2 = last ? nA : cA + (size_t)(t + 2) * kstep; const char* b2 = last ? nB : cB + (size_t)(t + 2) * kstep;
;             const char* a3 = a2 + kstep; const char* b3 = b2 + kstep;
;             if (last && has_next) S.a_ready(nxt);
;             if constexpr (SP2) {
;             PG8_LDB(B0, 0, 0); PG8_LDB(B1, 0, 1); PG8_SCHED; PG8_LDA(At, 0, 0); PG8_STAGE(PG8_SA(1, 1), a1 + hstep, voffA);
;             PG8_WAIT_V(8); PG8_WAIT_L(0); PG8_BAR; PG8_MMA(0, 0, At, B0); PG8_MMA(0, 1, At, B1); PG8_BAR; PG8_SCHED;
;             PG8_LDA(At, 0, 1); PG8_STAGE(PG8_SB(0, 0), b2, voffB); PG8_STAGE(PG8_SB(0, 1), b2 + hstep, voffB); PG8_STAGE(PG8_SA(0, 0), a2, voffA);
.LBB0_1056:
	ds_read_b128 v[158:161], v155
	ds_read_b128 v[162:165], v155 offset:1024
	ds_read_b128 v[166:169], v155 offset:2048
	ds_read_b128 v[170:173], v155 offset:3072
	ds_read_b128 v[174:177], v156
	ds_read_b128 v[178:181], v156 offset:1024
	ds_read_b128 v[182:185], v156 offset:2048
	ds_read_b128 v[186:189], v156 offset:3072
	s_add_u32 s26, s24, 0xffea0080
	s_addc_u32 s27, s25, -1
	s_cmpk_eq_i32 s59, 0x54
	s_cselect_b32 s29, s21, s27
	s_cselect_b32 s28, s20, s26
	s_cselect_b32 s27, s23, s58
	s_cselect_b32 s26, s22, s57
	v_lshl_add_u64 v[222:223], s[24:25], 0, v[138:139]
	s_add_i32 m0, s35, 0xc000
	ds_read_b128 v[190:193], v157
	ds_read_b128 v[194:197], v157 offset:1024
	ds_read_b128 v[198:201], v157 offset:2048
	ds_read_b128 v[202:205], v157 offset:3072
	ds_read_b128 v[206:209], v157 offset:4096
	ds_read_b128 v[210:213], v157 offset:5120
	ds_read_b128 v[214:217], v157 offset:6144
	ds_read_b128 v[218:221], v157 offset:7168
	global_load_lds_dwordx4 v[222:223], off
	v_lshl_add_u64 v[222:223], s[24:25], 0, v[140:141]
	s_add_i32 m0, s35, 0xe000
	s_nop 0
	global_load_lds_dwordx4 v[222:223], off
	s_waitcnt vmcnt(8)
	s_waitcnt lgkmcnt(0)
	s_barrier
	s_setprio 1
	s_waitcnt lgkmcnt(0)
	v_mfma_f32_16x16x32_bf16 v[124:127], v[158:161], v[190:193], v[124:127]
	v_mfma_f32_16x16x32_bf16 v[120:123], v[166:169], v[190:193], v[120:123]
	v_mfma_f32_16x16x32_bf16 v[116:119], v[158:161], v[198:201], v[116:119]
	v_mfma_f32_16x16x32_bf16 v[112:115], v[166:169], v[198:201], v[112:115]
	v_mfma_f32_16x16x32_bf16 v[100:103], v[158:161], v[206:209], v[100:103]
	v_mfma_f32_16x16x32_bf16 v[96:99], v[166:169], v[206:209], v[96:99]
	v_mfma_f32_16x16x32_bf16 v[84:87], v[158:161], v[214:217], v[84:87]
	v_mfma_f32_16x16x32_bf16 v[80:83], v[166:169], v[214:217], v[80:83]
	v_mfma_f32_16x16x32_bf16 v[124:127], v[162:165], v[194:197], v[124:127]
	v_mfma_f32_16x16x32_bf16 v[120:123], v[170:173], v[194:197], v[120:123]
	v_mfma_f32_16x16x32_bf16 v[116:119], v[162:165], v[202:205], v[116:119]
	v_mfma_f32_16x16x32_bf16 v[112:115], v[170:173], v[202:205], v[112:115]
	v_mfma_f32_16x16x32_bf16 v[100:103], v[162:165], v[210:213], v[100:103]
	v_mfma_f32_16x16x32_bf16 v[96:99], v[170:173], v[210:213], v[96:99]
	v_mfma_f32_16x16x32_bf16 v[84:87], v[162:165], v[218:221], v[84:87]
	v_mfma_f32_16x16x32_bf16 v[80:83], v[170:173], v[218:221], v[80:83]
	s_setprio 0
	s_setprio 1
	v_mfma_f32_16x16x32_bf16 v[108:111], v[174:177], v[190:193], v[108:111]
	v_mfma_f32_16x16x32_bf16 v[104:107], v[182:185], v[190:193], v[104:107]
	v_mfma_f32_16x16x32_bf16 v[92:95], v[174:177], v[198:201], v[92:95]
	v_mfma_f32_16x16x32_bf16 v[88:91], v[182:185], v[198:201], v[88:91]
	v_mfma_f32_16x16x32_bf16 v[76:79], v[174:177], v[206:209], v[76:79]
	v_mfma_f32_16x16x32_bf16 v[72:75], v[182:185], v[206:209], v[72:75]
	v_mfma_f32_16x16x32_bf16 v[68:71], v[174:177], v[214:217], v[68:71]
	v_mfma_f32_16x16x32_bf16 v[64:67], v[182:185], v[214:217], v[64:67]
	v_mfma_f32_16x16x32_bf16 v[108:111], v[178:181], v[194:197], v[108:111]
	v_mfma_f32_16x16x32_bf16 v[104:107], v[186:189], v[194:197], v[104:107]
	v_mfma_f32_16x16x32_bf16 v[92:95], v[178:181], v[202:205], v[92:95]
	v_mfma_f32_16x16x32_bf16 v[88:91], v[186:189], v[202:205], v[88:91]
	s_setprio 2
	s_barrier
	v_mfma_f32_16x16x32_bf16 v[76:79], v[178:181], v[210:213], v[76:79]
	v_mfma_f32_16x16x32_bf16 v[72:75], v[186:189], v[210:213], v[72:75]
	v_mfma_f32_16x16x32_bf16 v[68:71], v[178:181], v[218:221], v[68:71]
	v_mfma_f32_16x16x32_bf16 v[64:67], v[186:189], v[218:221], v[64:67]
	s_setprio 0
	s_add_i32 s60, s44, s30
	v_lshl_add_u64 v[222:223], s[26:27], 0, v[132:133]
	s_mov_b32 m0, s60
	ds_read_b128 v[190:193], v157 offset:16384
	ds_read_b128 v[194:197], v157 offset:17408
	ds_read_b128 v[198:201], v157 offset:18432
	ds_read_b128 v[202:205], v157 offset:19456
	ds_read_b128 v[206:209], v157 offset:20480
	ds_read_b128 v[210:213], v157 offset:21504
	ds_read_b128 v[214:217], v157 offset:22528
	ds_read_b128 v[218:221], v157 offset:23552
	global_load_lds_dwordx4 v[222:223], off
	s_add_i32 m0, s60, 0x2000
	s_add_u32 s60, s26, 0x160000
	v_lshl_add_u64 v[224:225], s[26:27], 0, v[136:137]
	s_addc_u32 s61, s27, 0
	s_add_i32 s62, s45, s30
	global_load_lds_dwordx4 v[224:225], off
	v_lshl_add_u64 v[226:227], s[60:61], 0, v[132:133]
	s_mov_b32 m0, s62
	v_lshl_add_u64 v[228:229], s[28:29], 0, v[134:135]
	global_load_lds_dwordx4 v[226:227], off
	v_lshl_add_u64 v[226:227], s[60:61], 0, v[136:137]
	s_add_i32 m0, s62, 0x2000
	s_nop 0
	global_load_lds_dwordx4 v[226:227], off
	v_lshl_add_u64 v[226:227], s[28:29], 0, v[130:131]
	s_mov_b32 m0, s35
	s_nop 0
	global_load_lds_dwordx4 v[226:227], off
	s_mov_b32 m0, s36
	s_nop 0
	global_load_lds_dwordx4 v[228:229], off
	s_waitcnt vmcnt(8)
	s_waitcnt lgkmcnt(0)
	s_barrier
; #define PG8_STAGE(bufoff, gbase, voff) do { _Pragma("unroll") for (int _i = 0; _i < 2; ++_i) \
;         __builtin_amdgcn_global_load_lds((const unsigned*)((const char*)(gbase) + (voff)[_i]), (PG8_LAS unsigned*)(lds + (bufoff) + ldsw + _i * 8192), 16, 0, 0); } while (0)
; #define PG8_LDA(dst, b, h) do { _Pragma("unroll") for (int m = 0; m < 4; ++m) _Pragma("unroll") for (int k = 0; k < 2; ++k) dst[m][k] = *(const PG8_LAS bf16x8*)(lds + PG8_SA(b, h) + aoff + m * 2048 + k * 1024); } while (0)
; #define PG8_LDB(dst, b, h) do { _Pragma("unroll") for (int n = 0; n < 2; ++n) _Pragma("unroll") for (int k = 0; k < 2; ++k) dst[n][k] = *(const PG8_LAS bf16x8*)(lds + PG8_SB(b, h) + boff + n * 2048 + k * 1024); } while (0)
; #define PG8_MMA(ai, bj, At, Bt) do { __builtin_amdgcn_s_setprio(1); _Pragma("unroll") for (int m = 0; m < 4; ++m) _Pragma("unroll") for (int n = 0; n < 2; ++n) _Pragma("unroll") for (int k = 0; k < 2; ++k) \
;         acc[ai][bj][m][n] = __builtin_amdgcn_mfma_f32_16x16x32_bf16(Bt[n][k], At[m][k], acc[ai][bj][m][n], 0, 0, 0); __builtin_amdgcn_s_setprio(0); } while (0)
; #define PG8_WAIT_V(n) asm volatile("s_waitcnt vmcnt(" #n ")" ::: "memory")
; #define PG8_WAIT_L(n) asm volatile("s_waitcnt lgkmcnt(" #n ")" ::: "memory")
; #define PG8_BAR __builtin_amdgcn_s_barrier()
; #define PG8_SCHED __builtin_amdgcn_sched_barrier(0)
; template <class Epi, class Sched, bool ALIGN_EPI = false, bool SP2 = false>
; __device__ __forceinline__ void gemm_phase(PG8_LAS unsigned char* lds, const Gemm g, const Sched& S, const Epi& E) {
;     ...
;             PG8_WAIT_V(8); PG8_WAIT_L(0); PG8_BAR; PG8_MMA(1, 0, At, B0); PG8_MMA(1, 1, At, B1); PG8_BAR; PG8_SCHED;
;             PG8_LDB(B0, 1, 0); PG8_LDB(B1, 1, 1); PG8_SCHED; PG8_LDA(At, 1, 0); PG8_STAGE(PG8_SA(0, 1), a2 + hstep, voffA);
;             PG8_WAIT_V(8); PG8_WAIT_L(0); PG8_BAR; PG8_MMA(0, 0, At, B0); PG8_MMA(0, 1, At, B1); PG8_BAR; PG8_SCHED;
	s_setprio 1
	s_waitcnt lgkmcnt(0)
	v_mfma_f32_16x16x32_bf16 v[60:63], v[158:161], v[190:193], v[60:63]
	v_mfma_f32_16x16x32_bf16 v[56:59], v[166:169], v[190:193], v[56:59]
	v_mfma_f32_16x16x32_bf16 v[52:55], v[158:161], v[198:201], v[52:55]
	v_mfma_f32_16x16x32_bf16 v[48:51], v[166:169], v[198:201], v[48:51]
	v_mfma_f32_16x16x32_bf16 v[36:39], v[158:161], v[206:209], v[36:39]
	v_mfma_f32_16x16x32_bf16 v[32:35], v[166:169], v[206:209], v[32:35]
	v_mfma_f32_16x16x32_bf16 v[20:23], v[158:161], v[214:217], v[20:23]
	v_mfma_f32_16x16x32_bf16 v[16:19], v[166:169], v[214:217], v[16:19]
	v_mfma_f32_16x16x32_bf16 v[60:63], v[162:165], v[194:197], v[60:63]
	v_mfma_f32_16x16x32_bf16 v[56:59], v[170:173], v[194:197], v[56:59]
	v_mfma_f32_16x16x32_bf16 v[52:55], v[162:165], v[202:205], v[52:55]
	v_mfma_f32_16x16x32_bf16 v[48:51], v[170:173], v[202:205], v[48:51]
	v_mfma_f32_16x16x32_bf16 v[36:39], v[162:165], v[210:213], v[36:39]
	v_mfma_f32_16x16x32_bf16 v[32:35], v[170:173], v[210:213], v[32:35]
	v_mfma_f32_16x16x32_bf16 v[20:23], v[162:165], v[218:221], v[20:23]
	v_mfma_f32_16x16x32_bf16 v[16:19], v[170:173], v[218:221], v[16:19]
	s_setprio 0
	s_setprio 1
	v_mfma_f32_16x16x32_bf16 v[44:47], v[174:177], v[190:193], v[44:47]
	v_mfma_f32_16x16x32_bf16 v[40:43], v[182:185], v[190:193], v[40:43]
	v_mfma_f32_16x16x32_bf16 v[28:31], v[174:177], v[198:201], v[28:31]
	v_mfma_f32_16x16x32_bf16 v[24:27], v[182:185], v[198:201], v[24:27]
	v_mfma_f32_16x16x32_bf16 v[12:15], v[174:177], v[206:209], v[12:15]
	v_mfma_f32_16x16x32_bf16 v[8:11], v[182:185], v[206:209], v[8:11]
	v_mfma_f32_16x16x32_bf16 v[4:7], v[174:177], v[214:217], v[4:7]
	v_mfma_f32_16x16x32_bf16 v[0:3], v[182:185], v[214:217], v[0:3]
	v_mfma_f32_16x16x32_bf16 v[44:47], v[178:181], v[194:197], v[44:47]
	v_mfma_f32_16x16x32_bf16 v[40:43], v[186:189], v[194:197], v[40:43]
	v_mfma_f32_16x16x32_bf16 v[28:31], v[178:181], v[202:205], v[28:31]
	v_mfma_f32_16x16x32_bf16 v[24:27], v[186:189], v[202:205], v[24:27]
	s_setprio 2
	s_barrier
	v_mfma_f32_16x16x32_bf16 v[12:15], v[178:181], v[210:213], v[12:15]
	v_mfma_f32_16x16x32_bf16 v[8:11], v[186:189], v[210:213], v[8:11]
	v_mfma_f32_16x16x32_bf16 v[4:7], v[178:181], v[218:221], v[4:7]
	v_mfma_f32_16x16x32_bf16 v[0:3], v[186:189], v[218:221], v[0:3]
	s_setprio 0
	s_add_i32 s60, 0, 0x18000
	s_add_i32 s61, 0, 0x1c000
	v_add_u32_e32 v170, s60, v153
	v_add_u32_e32 v186, s61, v153
	ds_read_b128 v[158:161], v170
	ds_read_b128 v[162:165], v170 offset:1024
	ds_read_b128 v[166:169], v170 offset:2048
	ds_read_b128 v[170:173], v170 offset:3072
	ds_read_b128 v[174:177], v186
	ds_read_b128 v[178:181], v186 offset:1024
	ds_read_b128 v[182:185], v186 offset:2048
	ds_read_b128 v[186:189], v186 offset:3072
	s_add_u32 s28, s28, 0x160000
	s_addc_u32 s29, s29, 0
	s_mov_b32 m0, s37
	v_lshl_add_u64 v[230:231], s[28:29], 0, v[130:131]
	ds_read_b128 v[190:193], v157 offset:32768
	ds_read_b128 v[194:197], v157 offset:33792
	ds_read_b128 v[198:201], v157 offset:34816
	ds_read_b128 v[202:205], v157 offset:35840
	ds_read_b128 v[206:209], v157 offset:36864
	ds_read_b128 v[210:213], v157 offset:37888
	ds_read_b128 v[214:217], v157 offset:38912
	ds_read_b128 v[218:221], v157 offset:39936
	global_load_lds_dwordx4 v[230:231], off
	v_lshl_add_u64 v[230:231], s[28:29], 0, v[134:135]
	s_mov_b32 m0, s38
	s_nop 0
	global_load_lds_dwordx4 v[230:231], off
	s_waitcnt vmcnt(8)
	s_waitcnt lgkmcnt(0)
	s_barrier
	s_setprio 1
	s_waitcnt lgkmcnt(0)
	v_mfma_f32_16x16x32_bf16 v[124:127], v[158:161], v[190:193], v[124:127]
	v_mfma_f32_16x16x32_bf16 v[120:123], v[166:169], v[190:193], v[120:123]
	v_mfma_f32_16x16x32_bf16 v[116:119], v[158:161], v[198:201], v[116:119]
	v_mfma_f32_16x16x32_bf16 v[112:115], v[166:169], v[198:201], v[112:115]
	v_mfma_f32_16x16x32_bf16 v[100:103], v[158:161], v[206:209], v[100:103]
	v_mfma_f32_16x16x32_bf16 v[96:99], v[166:169], v[206:209], v[96:99]
	v_mfma_f32_16x16x32_bf16 v[84:87], v[158:161], v[214:217], v[84:87]
	v_mfma_f32_16x16x32_bf16 v[80:83], v[166:169], v[214:217], v[80:83]
	v_mfma_f32_16x16x32_bf16 v[124:127], v[162:165], v[194:197], v[124:127]
	v_mfma_f32_16x16x32_bf16 v[120:123], v[170:173], v[194:197], v[120:123]
	v_mfma_f32_16x16x32_bf16 v[116:119], v[162:165], v[202:205], v[116:119]
	v_mfma_f32_16x16x32_bf16 v[112:115], v[170:173], v[202:205], v[112:115]
	v_mfma_f32_16x16x32_bf16 v[100:103], v[162:165], v[210:213], v[100:103]
	v_mfma_f32_16x16x32_bf16 v[96:99], v[170:173], v[210:213], v[96:99]
	v_mfma_f32_16x16x32_bf16 v[84:87], v[162:165], v[218:221], v[84:87]
	v_mfma_f32_16x16x32_bf16 v[80:83], v[170:173], v[218:221], v[80:83]
	s_setprio 0
	s_setprio 1
	v_mfma_f32_16x16x32_bf16 v[108:111], v[174:177], v[190:193], v[108:111]
	v_mfma_f32_16x16x32_bf16 v[104:107], v[182:185], v[190:193], v[104:107]
	v_mfma_f32_16x16x32_bf16 v[92:95], v[174:177], v[198:201], v[92:95]
	v_mfma_f32_16x16x32_bf16 v[88:91], v[182:185], v[198:201], v[88:91]
	v_mfma_f32_16x16x32_bf16 v[76:79], v[174:177], v[206:209], v[76:79]
	v_mfma_f32_16x16x32_bf16 v[72:75], v[182:185], v[206:209], v[72:75]
	v_mfma_f32_16x16x32_bf16 v[68:71], v[174:177], v[214:217], v[68:71]
	v_mfma_f32_16x16x32_bf16 v[64:67], v[182:185], v[214:217], v[64:67]
	v_mfma_f32_16x16x32_bf16 v[108:111], v[178:181], v[194:197], v[108:111]
	v_mfma_f32_16x16x32_bf16 v[104:107], v[186:189], v[194:197], v[104:107]
	v_mfma_f32_16x16x32_bf16 v[92:95], v[178:181], v[202:205], v[92:95]
	v_mfma_f32_16x16x32_bf16 v[88:91], v[186:189], v[202:205], v[88:91]
	s_setprio 2
	s_barrier
; #define PG8_STAGE(bufoff, gbase, voff) do { _Pragma("unroll") for (int _i = 0; _i < 2; ++_i) \
;         __builtin_amdgcn_global_load_lds((const unsigned*)((const char*)(gbase) + (voff)[_i]), (PG8_LAS unsigned*)(lds + (bufoff) + ldsw + _i * 8192), 16, 0, 0); } while (0)
; #define PG8_LDA(dst, b, h) do { _Pragma("unroll") for (int m = 0; m < 4; ++m) _Pragma("unroll") for (int k = 0; k < 2; ++k) dst[m][k] = *(const PG8_LAS bf16x8*)(lds + PG8_SA(b, h) + aoff + m * 2048 + k * 1024); } while (0)
; #define PG8_MMA(ai, bj, At, Bt) do { __builtin_amdgcn_s_setprio(1); _Pragma("unroll") for (int m = 0; m < 4; ++m) _Pragma("unroll") for (int n = 0; n < 2; ++n) _Pragma("unroll") for (int k = 0; k < 2; ++k) \
;         acc[ai][bj][m][n] = __builtin_amdgcn_mfma_f32_16x16x32_bf16(Bt[n][k], At[m][k], acc[ai][bj][m][n], 0, 0, 0); __builtin_amdgcn_s_setprio(0); } while (0)
; #define PG8_WAIT_V(n) asm volatile("s_waitcnt vmcnt(" #n ")" ::: "memory")
; #define PG8_WAIT_L(n) asm volatile("s_waitcnt lgkmcnt(" #n ")" ::: "memory")
; #define PG8_BAR __builtin_amdgcn_s_barrier()
; #define PG8_SCHED __builtin_amdgcn_sched_barrier(0)
; template <class Epi, class Sched, bool ALIGN_EPI = false, bool SP2 = false>
; __device__ __forceinline__ void gemm_phase(PG8_LAS unsigned char* lds, const Gemm g, const Sched& S, const Epi& E) {
;     ...
;             PG8_WAIT_V(8); PG8_WAIT_L(0); PG8_BAR; PG8_MMA(0, 0, At, B0); PG8_MMA(0, 1, At, B1); PG8_BAR; PG8_SCHED;
;             PG8_LDA(At, 1, 1); PG8_STAGE(PG8_SB(1, 0), b3, voffB); PG8_STAGE(PG8_SB(1, 1), b3 + hstep, voffB); PG8_STAGE(PG8_SA(1, 0), a3, voffA);
;             PG8_WAIT_V(8); PG8_WAIT_L(0); PG8_BAR; PG8_MMA(1, 0, At, B0); PG8_MMA(1, 1, At, B1); PG8_BAR; PG8_SCHED;
	v_mfma_f32_16x16x32_bf16 v[76:79], v[178:181], v[210:213], v[76:79]
	v_mfma_f32_16x16x32_bf16 v[72:75], v[186:189], v[210:213], v[72:75]
	v_mfma_f32_16x16x32_bf16 v[68:71], v[178:181], v[218:221], v[68:71]
	v_mfma_f32_16x16x32_bf16 v[64:67], v[186:189], v[218:221], v[64:67]
	s_setprio 0
	s_add_i32 s28, s60, s30
	v_lshl_add_u64 v[222:223], v[222:223], 0, s[4:5]
	s_mov_b32 m0, s28
	ds_read_b128 v[190:193], v157 offset:49152
	ds_read_b128 v[194:197], v157 offset:50176
	ds_read_b128 v[198:201], v157 offset:51200
	ds_read_b128 v[202:205], v157 offset:52224
	ds_read_b128 v[206:209], v157 offset:53248
	ds_read_b128 v[210:213], v157 offset:54272
	ds_read_b128 v[214:217], v157 offset:55296
	ds_read_b128 v[218:221], v157 offset:56320
	global_load_lds_dwordx4 v[222:223], off
	s_add_i32 m0, s28, 0x2000
	s_add_u32 s26, s26, 0x160080
	v_lshl_add_u64 v[222:223], v[224:225], 0, s[4:5]
	s_addc_u32 s27, s27, 0
	s_add_i32 s28, s61, s30
	global_load_lds_dwordx4 v[222:223], off
	v_lshl_add_u64 v[222:223], s[26:27], 0, v[132:133]
	s_mov_b32 m0, s28
	s_nop 0
	global_load_lds_dwordx4 v[222:223], off
	v_lshl_add_u64 v[222:223], s[26:27], 0, v[136:137]
	s_add_i32 m0, s28, 0x2000
	s_nop 0
	global_load_lds_dwordx4 v[222:223], off
	v_lshl_add_u64 v[222:223], v[226:227], 0, s[4:5]
	s_mov_b32 m0, s40
	s_nop 0
	global_load_lds_dwordx4 v[222:223], off
	v_lshl_add_u64 v[222:223], v[228:229], 0, s[4:5]
	s_mov_b32 m0, s41
	s_nop 0
	global_load_lds_dwordx4 v[222:223], off
	s_waitcnt vmcnt(8)
	s_waitcnt lgkmcnt(0)
	s_barrier
	s_setprio 1
	s_waitcnt lgkmcnt(0)
	v_mfma_f32_16x16x32_bf16 v[60:63], v[158:161], v[190:193], v[60:63]
	v_mfma_f32_16x16x32_bf16 v[56:59], v[166:169], v[190:193], v[56:59]
	v_mfma_f32_16x16x32_bf16 v[52:55], v[158:161], v[198:201], v[52:55]
	v_mfma_f32_16x16x32_bf16 v[48:51], v[166:169], v[198:201], v[48:51]
	v_mfma_f32_16x16x32_bf16 v[36:39], v[158:161], v[206:209], v[36:39]
	v_mfma_f32_16x16x32_bf16 v[32:35], v[166:169], v[206:209], v[32:35]
	v_mfma_f32_16x16x32_bf16 v[20:23], v[158:161], v[214:217], v[20:23]
	v_mfma_f32_16x16x32_bf16 v[16:19], v[166:169], v[214:217], v[16:19]
	v_mfma_f32_16x16x32_bf16 v[60:63], v[162:165], v[194:197], v[60:63]
	v_mfma_f32_16x16x32_bf16 v[56:59], v[170:173], v[194:197], v[56:59]
	v_mfma_f32_16x16x32_bf16 v[52:55], v[162:165], v[202:205], v[52:55]
	v_mfma_f32_16x16x32_bf16 v[48:51], v[170:173], v[202:205], v[48:51]
	v_mfma_f32_16x16x32_bf16 v[36:39], v[162:165], v[210:213], v[36:39]
	v_mfma_f32_16x16x32_bf16 v[32:35], v[170:173], v[210:213], v[32:35]
	v_mfma_f32_16x16x32_bf16 v[20:23], v[162:165], v[218:221], v[20:23]
	v_mfma_f32_16x16x32_bf16 v[16:19], v[170:173], v[218:221], v[16:19]
	s_setprio 0
	s_setprio 1
	v_mfma_f32_16x16x32_bf16 v[44:47], v[174:177], v[190:193], v[44:47]
	v_mfma_f32_16x16x32_bf16 v[40:43], v[182:185], v[190:193], v[40:43]
	v_mfma_f32_16x16x32_bf16 v[28:31], v[174:177], v[198:201], v[28:31]
	v_mfma_f32_16x16x32_bf16 v[24:27], v[182:185], v[198:201], v[24:27]
	v_mfma_f32_16x16x32_bf16 v[12:15], v[174:177], v[206:209], v[12:15]
	v_mfma_f32_16x16x32_bf16 v[8:11], v[182:185], v[206:209], v[8:11]
	v_mfma_f32_16x16x32_bf16 v[4:7], v[174:177], v[214:217], v[4:7]
	v_mfma_f32_16x16x32_bf16 v[0:3], v[182:185], v[214:217], v[0:3]
	v_mfma_f32_16x16x32_bf16 v[44:47], v[178:181], v[194:197], v[44:47]
	v_mfma_f32_16x16x32_bf16 v[40:43], v[186:189], v[194:197], v[40:43]
	v_mfma_f32_16x16x32_bf16 v[28:31], v[178:181], v[202:205], v[28:31]
	v_mfma_f32_16x16x32_bf16 v[24:27], v[186:189], v[202:205], v[24:27]
	s_setprio 2
	s_barrier
	v_mfma_f32_16x16x32_bf16 v[12:15], v[178:181], v[210:213], v[12:15]
	v_mfma_f32_16x16x32_bf16 v[8:11], v[186:189], v[210:213], v[8:11]
	v_mfma_f32_16x16x32_bf16 v[4:7], v[178:181], v[218:221], v[4:7]
	v_mfma_f32_16x16x32_bf16 v[0:3], v[186:189], v[218:221], v[0:3]
	s_setprio 0
	s_add_i32 s59, s59, 2
	s_add_u32 s24, s24, 0x100
	s_addc_u32 s25, s25, 0
	s_add_u32 s57, s57, 0x100
	s_addc_u32 s58, s58, 0
	s_cmpk_gt_u32 s59, 0x55
	s_cbranch_scc0 .LBB0_1056
	s_and_b64 vcc, exec, s[10:11]
	s_cbranch_vccz .LBB0_1059
	s_barrier

; #define PG8_STAGE(bufoff, gbase, voff) do { _Pragma("unroll") for (int _i = 0; _i < 2; ++_i) \
;         __builtin_amdgcn_global_load_lds((const unsigned*)((const char*)(gbase) + (voff)[_i]), (PG8_LAS unsigned*)(lds + (bufoff) + ldsw + _i * 8192), 16, 0, 0); } while (0)
; #define PG8_LDA(dst, b, h) do { _Pragma("unroll") for (int m = 0; m < 4; ++m) _Pragma("unroll") for (int k = 0; k < 2; ++k) dst[m][k] = *(const PG8_LAS bf16x8*)(lds + PG8_SA(b, h) + aoff + m * 2048 + k * 1024); } while (0)
; #define PG8_LDB(dst, b, h) do { _Pragma("unroll") for (int n = 0; n < 2; ++n) _Pragma("unroll") for (int k = 0; k < 2; ++k) dst[n][k] = *(const PG8_LAS bf16x8*)(lds + PG8_SB(b, h) + boff + n * 2048 + k * 1024); } while (0)
; #define PG8_MMA(ai, bj, At, Bt) do { __builtin_amdgcn_s_setprio(1); _Pragma("unroll") for (int m = 0; m < 4; ++m) _Pragma("unroll") for (int n = 0; n < 2; ++n) _Pragma("unroll") for (int k = 0; k < 2; ++k) \
;         acc[ai][bj][m][n] = __builtin_amdgcn_mfma_f32_16x16x32_bf16(Bt[n][k], At[m][k], acc[ai][bj][m][n], 0, 0, 0); __builtin_amdgcn_s_setprio(0); } while (0)
; #define PG8_WAIT_V(n) asm volatile("s_waitcnt vmcnt(" #n ")" ::: "memory")
; #define PG8_WAIT_L(n) asm volatile("s_waitcnt lgkmcnt(" #n ")" ::: "memory")
; #define PG8_BAR __builtin_amdgcn_s_barrier()
; #define PG8_SCHED __builtin_amdgcn_sched_barrier(0)
; template <class Epi, class Sched, bool ALIGN_EPI = false, bool SP2 = false>
; __device__ __forceinline__ void gemm_phase(PG8_LAS unsigned char* lds, const Gemm g, const Sched& S, const Epi& E) {
;     ...
;             PG8_LDB(B0, 0, 0); PG8_LDB(B1, 0, 1); PG8_SCHED; PG8_LDA(At, 0, 0); PG8_STAGE(PG8_SA(1, 1), a1 + hstep, voffA);
;             PG8_WAIT_V(8); PG8_WAIT_L(0); PG8_BAR; PG8_MMA(0, 0, At, B0); PG8_MMA(0, 1, At, B1); PG8_BAR; PG8_SCHED;
;             PG8_LDA(At, 0, 1); PG8_STAGE(PG8_SB(0, 0), b2, voffB); PG8_STAGE(PG8_SB(0, 1), b2 + hstep, voffB); PG8_STAGE(PG8_SA(0, 0), a2, voffA);
;             PG8_WAIT_V(8); PG8_WAIT_L(0); PG8_BAR; PG8_MMA(1, 0, At, B0); PG8_MMA(1, 1, At, B1); PG8_BAR; PG8_SCHED;
.LBB0_1068:
	ds_read_b128 v[150:153], v139
	ds_read_b128 v[154:157], v139 offset:1024
	ds_read_b128 v[158:161], v139 offset:2048
	ds_read_b128 v[162:165], v139 offset:3072
	ds_read_b128 v[166:169], v145
	ds_read_b128 v[170:173], v145 offset:1024
	ds_read_b128 v[174:177], v145 offset:2048
	ds_read_b128 v[178:181], v145 offset:3072
	s_add_u32 s14, s10, s12
	s_addc_u32 s15, s11, s13
	s_add_u32 s14, s14, 0x13500100
	s_addc_u32 s15, s15, 0
	s_add_u32 s40, s26, s12
	s_addc_u32 s41, s27, s13
	s_cmpk_eq_i32 s12, 0x1500
	s_cselect_b32 s17, s5, s15
	s_cselect_b32 s16, s4, s14
	s_cselect_b32 s15, s3, s41
	s_cselect_b32 s14, s2, s40
	s_mov_b32 m0, s29
	v_lshl_add_u64 v[214:215], v[140:141], 0, s[12:13]
	ds_read_b128 v[182:185], v146
	ds_read_b128 v[186:189], v146 offset:1024
	ds_read_b128 v[190:193], v146 offset:2048
	ds_read_b128 v[194:197], v146 offset:3072
	ds_read_b128 v[198:201], v146 offset:4096
	ds_read_b128 v[202:205], v146 offset:5120
	ds_read_b128 v[206:209], v146 offset:6144
	ds_read_b128 v[210:213], v146 offset:7168
	global_load_lds_dwordx4 v[214:215], off
	v_lshl_add_u64 v[214:215], v[142:143], 0, s[12:13]
	s_mov_b32 m0, s30
	s_nop 0
	global_load_lds_dwordx4 v[214:215], off
	s_waitcnt vmcnt(8)
	s_waitcnt lgkmcnt(0)
	s_barrier
	s_setprio 1
	s_waitcnt lgkmcnt(0)
	v_mfma_f32_16x16x32_bf16 v[124:127], v[150:153], v[182:185], v[124:127]
	v_mfma_f32_16x16x32_bf16 v[120:123], v[158:161], v[182:185], v[120:123]
	v_mfma_f32_16x16x32_bf16 v[116:119], v[150:153], v[190:193], v[116:119]
	v_mfma_f32_16x16x32_bf16 v[112:115], v[158:161], v[190:193], v[112:115]
	v_mfma_f32_16x16x32_bf16 v[108:111], v[150:153], v[198:201], v[108:111]
	v_mfma_f32_16x16x32_bf16 v[104:107], v[158:161], v[198:201], v[104:107]
	v_mfma_f32_16x16x32_bf16 v[96:99], v[150:153], v[206:209], v[96:99]
	v_mfma_f32_16x16x32_bf16 v[88:91], v[158:161], v[206:209], v[88:91]
	v_mfma_f32_16x16x32_bf16 v[124:127], v[154:157], v[186:189], v[124:127]
	v_mfma_f32_16x16x32_bf16 v[120:123], v[162:165], v[186:189], v[120:123]
	v_mfma_f32_16x16x32_bf16 v[116:119], v[154:157], v[194:197], v[116:119]
	v_mfma_f32_16x16x32_bf16 v[112:115], v[162:165], v[194:197], v[112:115]
	v_mfma_f32_16x16x32_bf16 v[108:111], v[154:157], v[202:205], v[108:111]
	v_mfma_f32_16x16x32_bf16 v[104:107], v[162:165], v[202:205], v[104:107]
	v_mfma_f32_16x16x32_bf16 v[96:99], v[154:157], v[210:213], v[96:99]
	v_mfma_f32_16x16x32_bf16 v[88:91], v[162:165], v[210:213], v[88:91]
	s_setprio 0
	s_setprio 1
	v_mfma_f32_16x16x32_bf16 v[100:103], v[166:169], v[182:185], v[100:103]
	v_mfma_f32_16x16x32_bf16 v[92:95], v[174:177], v[182:185], v[92:95]
	v_mfma_f32_16x16x32_bf16 v[84:87], v[166:169], v[190:193], v[84:87]
	v_mfma_f32_16x16x32_bf16 v[80:83], v[174:177], v[190:193], v[80:83]
	v_mfma_f32_16x16x32_bf16 v[76:79], v[166:169], v[198:201], v[76:79]
	v_mfma_f32_16x16x32_bf16 v[72:75], v[174:177], v[198:201], v[72:75]
	v_mfma_f32_16x16x32_bf16 v[68:71], v[166:169], v[206:209], v[68:71]
	v_mfma_f32_16x16x32_bf16 v[64:67], v[174:177], v[206:209], v[64:67]
	v_mfma_f32_16x16x32_bf16 v[100:103], v[170:173], v[186:189], v[100:103]
	v_mfma_f32_16x16x32_bf16 v[92:95], v[178:181], v[186:189], v[92:95]
	v_mfma_f32_16x16x32_bf16 v[84:87], v[170:173], v[194:197], v[84:87]
	v_mfma_f32_16x16x32_bf16 v[80:83], v[178:181], v[194:197], v[80:83]
	s_setprio 2
	s_barrier
	v_mfma_f32_16x16x32_bf16 v[76:79], v[170:173], v[202:205], v[76:79]
	v_mfma_f32_16x16x32_bf16 v[72:75], v[178:181], v[202:205], v[72:75]
	v_mfma_f32_16x16x32_bf16 v[68:71], v[170:173], v[210:213], v[68:71]
	v_mfma_f32_16x16x32_bf16 v[64:67], v[178:181], v[210:213], v[64:67]
	s_setprio 0
	s_mov_b32 m0, s31
	v_lshl_add_u64 v[214:215], s[14:15], 0, v[132:133]
	s_add_u32 s40, s14, 0x160000
	ds_read_b128 v[182:185], v146 offset:16384
	ds_read_b128 v[186:189], v146 offset:17408
	ds_read_b128 v[190:193], v146 offset:18432
	ds_read_b128 v[194:197], v146 offset:19456
	ds_read_b128 v[198:201], v146 offset:20480
	ds_read_b128 v[202:205], v146 offset:21504
	ds_read_b128 v[206:209], v146 offset:22528
	ds_read_b128 v[210:213], v146 offset:23552
	global_load_lds_dwordx4 v[214:215], off
	v_lshl_add_u64 v[216:217], s[14:15], 0, v[136:137]
	s_mov_b32 m0, s33
	s_addc_u32 s41, s15, 0
	global_load_lds_dwordx4 v[216:217], off
	v_lshl_add_u64 v[218:219], s[40:41], 0, v[132:133]
	s_mov_b32 m0, s34
	v_lshl_add_u64 v[220:221], s[16:17], 0, v[134:135]
	global_load_lds_dwordx4 v[218:219], off
	v_lshl_add_u64 v[218:219], s[40:41], 0, v[136:137]
	s_mov_b32 m0, s35
	s_nop 0
	global_load_lds_dwordx4 v[218:219], off
	v_lshl_add_u64 v[218:219], s[16:17], 0, v[130:131]
	s_mov_b32 m0, s19
	s_nop 0
	global_load_lds_dwordx4 v[218:219], off
	s_mov_b32 m0, s20
	s_nop 0
	global_load_lds_dwordx4 v[220:221], off
	s_waitcnt vmcnt(8)
	s_waitcnt lgkmcnt(0)
	s_barrier
; #define PG8_STAGE(bufoff, gbase, voff) do { _Pragma("unroll") for (int _i = 0; _i < 2; ++_i) \
;         __builtin_amdgcn_global_load_lds((const unsigned*)((const char*)(gbase) + (voff)[_i]), (PG8_LAS unsigned*)(lds + (bufoff) + ldsw + _i * 8192), 16, 0, 0); } while (0)
; #define PG8_LDA(dst, b, h) do { _Pragma("unroll") for (int m = 0; m < 4; ++m) _Pragma("unroll") for (int k = 0; k < 2; ++k) dst[m][k] = *(const PG8_LAS bf16x8*)(lds + PG8_SA(b, h) + aoff + m * 2048 + k * 1024); } while (0)
; #define PG8_LDB(dst, b, h) do { _Pragma("unroll") for (int n = 0; n < 2; ++n) _Pragma("unroll") for (int k = 0; k < 2; ++k) dst[n][k] = *(const PG8_LAS bf16x8*)(lds + PG8_SB(b, h) + boff + n * 2048 + k * 1024); } while (0)
; #define PG8_MMA(ai, bj, At, Bt) do { __builtin_amdgcn_s_setprio(1); _Pragma("unroll") for (int m = 0; m < 4; ++m) _Pragma("unroll") for (int n = 0; n < 2; ++n) _Pragma("unroll") for (int k = 0; k < 2; ++k) \
;         acc[ai][bj][m][n] = __builtin_amdgcn_mfma_f32_16x16x32_bf16(Bt[n][k], At[m][k], acc[ai][bj][m][n], 0, 0, 0); __builtin_amdgcn_s_setprio(0); } while (0)
; #define PG8_WAIT_V(n) asm volatile("s_waitcnt vmcnt(" #n ")" ::: "memory")
; #define PG8_WAIT_L(n) asm volatile("s_waitcnt lgkmcnt(" #n ")" ::: "memory")
; #define PG8_BAR __builtin_amdgcn_s_barrier()
; #define PG8_SCHED __builtin_amdgcn_sched_barrier(0)
; template <class Epi, class Sched, bool ALIGN_EPI = false, bool SP2 = false>
; __device__ __forceinline__ void gemm_phase(PG8_LAS unsigned char* lds, const Gemm g, const Sched& S, const Epi& E) {
;     ...
;             PG8_WAIT_V(8); PG8_WAIT_L(0); PG8_BAR; PG8_MMA(1, 0, At, B0); PG8_MMA(1, 1, At, B1); PG8_BAR; PG8_SCHED;
;             PG8_LDB(B0, 1, 0); PG8_LDB(B1, 1, 1); PG8_SCHED; PG8_LDA(At, 1, 0); PG8_STAGE(PG8_SA(0, 1), a2 + hstep, voffA);
;             PG8_WAIT_V(8); PG8_WAIT_L(0); PG8_BAR; PG8_MMA(0, 0, At, B0); PG8_MMA(0, 1, At, B1); PG8_BAR; PG8_SCHED;
	s_setprio 1
	s_waitcnt lgkmcnt(0)
	v_mfma_f32_16x16x32_bf16 v[60:63], v[150:153], v[182:185], v[60:63]
	v_mfma_f32_16x16x32_bf16 v[56:59], v[158:161], v[182:185], v[56:59]
	v_mfma_f32_16x16x32_bf16 v[52:55], v[150:153], v[190:193], v[52:55]
	v_mfma_f32_16x16x32_bf16 v[48:51], v[158:161], v[190:193], v[48:51]
	v_mfma_f32_16x16x32_bf16 v[44:47], v[150:153], v[198:201], v[44:47]
	v_mfma_f32_16x16x32_bf16 v[40:43], v[158:161], v[198:201], v[40:43]
	v_mfma_f32_16x16x32_bf16 v[32:35], v[150:153], v[206:209], v[32:35]
	v_mfma_f32_16x16x32_bf16 v[24:27], v[158:161], v[206:209], v[24:27]
	v_mfma_f32_16x16x32_bf16 v[60:63], v[154:157], v[186:189], v[60:63]
	v_mfma_f32_16x16x32_bf16 v[56:59], v[162:165], v[186:189], v[56:59]
	v_mfma_f32_16x16x32_bf16 v[52:55], v[154:157], v[194:197], v[52:55]
	v_mfma_f32_16x16x32_bf16 v[48:51], v[162:165], v[194:197], v[48:51]
	v_mfma_f32_16x16x32_bf16 v[44:47], v[154:157], v[202:205], v[44:47]
	v_mfma_f32_16x16x32_bf16 v[40:43], v[162:165], v[202:205], v[40:43]
	v_mfma_f32_16x16x32_bf16 v[32:35], v[154:157], v[210:213], v[32:35]
	v_mfma_f32_16x16x32_bf16 v[24:27], v[162:165], v[210:213], v[24:27]
	s_setprio 0
	s_setprio 1
	v_mfma_f32_16x16x32_bf16 v[36:39], v[166:169], v[182:185], v[36:39]
	v_mfma_f32_16x16x32_bf16 v[28:31], v[174:177], v[182:185], v[28:31]
	v_mfma_f32_16x16x32_bf16 v[20:23], v[166:169], v[190:193], v[20:23]
	v_mfma_f32_16x16x32_bf16 v[16:19], v[174:177], v[190:193], v[16:19]
	v_mfma_f32_16x16x32_bf16 v[12:15], v[166:169], v[198:201], v[12:15]
	v_mfma_f32_16x16x32_bf16 v[8:11], v[174:177], v[198:201], v[8:11]
	v_mfma_f32_16x16x32_bf16 v[4:7], v[166:169], v[206:209], v[4:7]
	v_mfma_f32_16x16x32_bf16 v[0:3], v[174:177], v[206:209], v[0:3]
	v_mfma_f32_16x16x32_bf16 v[36:39], v[170:173], v[186:189], v[36:39]
	v_mfma_f32_16x16x32_bf16 v[28:31], v[178:181], v[186:189], v[28:31]
	v_mfma_f32_16x16x32_bf16 v[20:23], v[170:173], v[194:197], v[20:23]
	v_mfma_f32_16x16x32_bf16 v[16:19], v[178:181], v[194:197], v[16:19]
	s_setprio 2
	s_barrier
	v_mfma_f32_16x16x32_bf16 v[12:15], v[170:173], v[202:205], v[12:15]
	v_mfma_f32_16x16x32_bf16 v[8:11], v[178:181], v[202:205], v[8:11]
	v_mfma_f32_16x16x32_bf16 v[4:7], v[170:173], v[210:213], v[4:7]
	v_mfma_f32_16x16x32_bf16 v[0:3], v[178:181], v[210:213], v[0:3]
	s_setprio 0
	ds_read_b128 v[150:153], v147
	ds_read_b128 v[154:157], v147 offset:1024
	ds_read_b128 v[158:161], v147 offset:2048
	ds_read_b128 v[162:165], v147 offset:3072
	ds_read_b128 v[166:169], v148
	ds_read_b128 v[170:173], v148 offset:1024
	ds_read_b128 v[174:177], v148 offset:2048
	ds_read_b128 v[178:181], v148 offset:3072
	s_add_u32 s16, s16, 0x160000
	s_addc_u32 s17, s17, 0
	s_mov_b32 m0, s21
	v_lshl_add_u64 v[222:223], s[16:17], 0, v[130:131]
	ds_read_b128 v[182:185], v146 offset:32768
	ds_read_b128 v[186:189], v146 offset:33792
	ds_read_b128 v[190:193], v146 offset:34816
	ds_read_b128 v[194:197], v146 offset:35840
	ds_read_b128 v[198:201], v146 offset:36864
	ds_read_b128 v[202:205], v146 offset:37888
	ds_read_b128 v[206:209], v146 offset:38912
	ds_read_b128 v[210:213], v146 offset:39936
	global_load_lds_dwordx4 v[222:223], off
	v_lshl_add_u64 v[222:223], s[16:17], 0, v[134:135]
	s_mov_b32 m0, s22
	s_nop 0
	global_load_lds_dwordx4 v[222:223], off
	s_waitcnt vmcnt(8)
	s_waitcnt lgkmcnt(0)
	s_barrier
	s_setprio 1
	s_waitcnt lgkmcnt(0)
	v_mfma_f32_16x16x32_bf16 v[124:127], v[150:153], v[182:185], v[124:127]
	v_mfma_f32_16x16x32_bf16 v[120:123], v[158:161], v[182:185], v[120:123]
	v_mfma_f32_16x16x32_bf16 v[116:119], v[150:153], v[190:193], v[116:119]
	v_mfma_f32_16x16x32_bf16 v[112:115], v[158:161], v[190:193], v[112:115]
	v_mfma_f32_16x16x32_bf16 v[108:111], v[150:153], v[198:201], v[108:111]
	v_mfma_f32_16x16x32_bf16 v[104:107], v[158:161], v[198:201], v[104:107]
	v_mfma_f32_16x16x32_bf16 v[96:99], v[150:153], v[206:209], v[96:99]
	v_mfma_f32_16x16x32_bf16 v[88:91], v[158:161], v[206:209], v[88:91]
	v_mfma_f32_16x16x32_bf16 v[124:127], v[154:157], v[186:189], v[124:127]
	v_mfma_f32_16x16x32_bf16 v[120:123], v[162:165], v[186:189], v[120:123]
	v_mfma_f32_16x16x32_bf16 v[116:119], v[154:157], v[194:197], v[116:119]
	v_mfma_f32_16x16x32_bf16 v[112:115], v[162:165], v[194:197], v[112:115]
	v_mfma_f32_16x16x32_bf16 v[108:111], v[154:157], v[202:205], v[108:111]
	v_mfma_f32_16x16x32_bf16 v[104:107], v[162:165], v[202:205], v[104:107]
	v_mfma_f32_16x16x32_bf16 v[96:99], v[154:157], v[210:213], v[96:99]
	v_mfma_f32_16x16x32_bf16 v[88:91], v[162:165], v[210:213], v[88:91]
	s_setprio 0
	s_setprio 1
	v_mfma_f32_16x16x32_bf16 v[100:103], v[166:169], v[182:185], v[100:103]
	v_mfma_f32_16x16x32_bf16 v[92:95], v[174:177], v[182:185], v[92:95]
	v_mfma_f32_16x16x32_bf16 v[84:87], v[166:169], v[190:193], v[84:87]
	v_mfma_f32_16x16x32_bf16 v[80:83], v[174:177], v[190:193], v[80:83]
	v_mfma_f32_16x16x32_bf16 v[76:79], v[166:169], v[198:201], v[76:79]
	v_mfma_f32_16x16x32_bf16 v[72:75], v[174:177], v[198:201], v[72:75]
	v_mfma_f32_16x16x32_bf16 v[68:71], v[166:169], v[206:209], v[68:71]
	v_mfma_f32_16x16x32_bf16 v[64:67], v[174:177], v[206:209], v[64:67]
	v_mfma_f32_16x16x32_bf16 v[100:103], v[170:173], v[186:189], v[100:103]
	v_mfma_f32_16x16x32_bf16 v[92:95], v[178:181], v[186:189], v[92:95]
	v_mfma_f32_16x16x32_bf16 v[84:87], v[170:173], v[194:197], v[84:87]
	v_mfma_f32_16x16x32_bf16 v[80:83], v[178:181], v[194:197], v[80:83]
	s_setprio 2
	s_barrier
; #define PG8_STAGE(bufoff, gbase, voff) do { _Pragma("unroll") for (int _i = 0; _i < 2; ++_i) \
;         __builtin_amdgcn_global_load_lds((const unsigned*)((const char*)(gbase) + (voff)[_i]), (PG8_LAS unsigned*)(lds + (bufoff) + ldsw + _i * 8192), 16, 0, 0); } while (0)
; #define PG8_LDA(dst, b, h) do { _Pragma("unroll") for (int m = 0; m < 4; ++m) _Pragma("unroll") for (int k = 0; k < 2; ++k) dst[m][k] = *(const PG8_LAS bf16x8*)(lds + PG8_SA(b, h) + aoff + m * 2048 + k * 1024); } while (0)
; #define PG8_MMA(ai, bj, At, Bt) do { __builtin_amdgcn_s_setprio(1); _Pragma("unroll") for (int m = 0; m < 4; ++m) _Pragma("unroll") for (int n = 0; n < 2; ++n) _Pragma("unroll") for (int k = 0; k < 2; ++k) \
;         acc[ai][bj][m][n] = __builtin_amdgcn_mfma_f32_16x16x32_bf16(Bt[n][k], At[m][k], acc[ai][bj][m][n], 0, 0, 0); __builtin_amdgcn_s_setprio(0); } while (0)
; #define PG8_WAIT_V(n) asm volatile("s_waitcnt vmcnt(" #n ")" ::: "memory")
; #define PG8_WAIT_L(n) asm volatile("s_waitcnt lgkmcnt(" #n ")" ::: "memory")
; #define PG8_BAR __builtin_amdgcn_s_barrier()
; #define PG8_SCHED __builtin_amdgcn_sched_barrier(0)
; template <class Epi, class Sched, bool ALIGN_EPI = false, bool SP2 = false>
; __device__ __forceinline__ void gemm_phase(PG8_LAS unsigned char* lds, const Gemm g, const Sched& S, const Epi& E) {
;     ...
;             PG8_WAIT_V(8); PG8_WAIT_L(0); PG8_BAR; PG8_MMA(0, 0, At, B0); PG8_MMA(0, 1, At, B1); PG8_BAR; PG8_SCHED;
;             PG8_LDA(At, 1, 1); PG8_STAGE(PG8_SB(1, 0), b3, voffB); PG8_STAGE(PG8_SB(1, 1), b3 + hstep, voffB); PG8_STAGE(PG8_SA(1, 0), a3, voffA);
;             PG8_WAIT_V(8); PG8_WAIT_L(0); PG8_BAR; PG8_MMA(1, 0, At, B0); PG8_MMA(1, 1, At, B1); PG8_BAR; PG8_SCHED;
	v_mfma_f32_16x16x32_bf16 v[76:79], v[170:173], v[202:205], v[76:79]
	v_mfma_f32_16x16x32_bf16 v[72:75], v[178:181], v[202:205], v[72:75]
	v_mfma_f32_16x16x32_bf16 v[68:71], v[170:173], v[210:213], v[68:71]
	v_mfma_f32_16x16x32_bf16 v[64:67], v[178:181], v[210:213], v[64:67]
	s_setprio 0
	s_mov_b32 m0, s36
	v_lshl_add_u64 v[214:215], v[214:215], 0, s[6:7]
	s_add_u32 s14, s14, 0x160080
	ds_read_b128 v[182:185], v146 offset:49152
	ds_read_b128 v[186:189], v146 offset:50176
	ds_read_b128 v[190:193], v146 offset:51200
	ds_read_b128 v[194:197], v146 offset:52224
	ds_read_b128 v[198:201], v146 offset:53248
	ds_read_b128 v[202:205], v146 offset:54272
	ds_read_b128 v[206:209], v146 offset:55296
	ds_read_b128 v[210:213], v146 offset:56320
	global_load_lds_dwordx4 v[214:215], off
	v_lshl_add_u64 v[214:215], v[216:217], 0, s[6:7]
	s_mov_b32 m0, s37
	s_addc_u32 s15, s15, 0
	global_load_lds_dwordx4 v[214:215], off
	v_lshl_add_u64 v[214:215], s[14:15], 0, v[132:133]
	s_mov_b32 m0, s38
	s_nop 0
	global_load_lds_dwordx4 v[214:215], off
	v_lshl_add_u64 v[214:215], s[14:15], 0, v[136:137]
	s_mov_b32 m0, s39
	s_nop 0
	global_load_lds_dwordx4 v[214:215], off
	v_lshl_add_u64 v[214:215], v[218:219], 0, s[6:7]
	s_mov_b32 m0, s24
	s_nop 0
	global_load_lds_dwordx4 v[214:215], off
	v_lshl_add_u64 v[214:215], v[220:221], 0, s[6:7]
	s_mov_b32 m0, s25
	s_nop 0
	global_load_lds_dwordx4 v[214:215], off
	s_waitcnt vmcnt(8)
	s_waitcnt lgkmcnt(0)
	s_barrier
	s_setprio 1
	s_waitcnt lgkmcnt(0)
	v_mfma_f32_16x16x32_bf16 v[60:63], v[150:153], v[182:185], v[60:63]
	v_mfma_f32_16x16x32_bf16 v[56:59], v[158:161], v[182:185], v[56:59]
	v_mfma_f32_16x16x32_bf16 v[52:55], v[150:153], v[190:193], v[52:55]
	v_mfma_f32_16x16x32_bf16 v[48:51], v[158:161], v[190:193], v[48:51]
	v_mfma_f32_16x16x32_bf16 v[44:47], v[150:153], v[198:201], v[44:47]
	v_mfma_f32_16x16x32_bf16 v[40:43], v[158:161], v[198:201], v[40:43]
	v_mfma_f32_16x16x32_bf16 v[32:35], v[150:153], v[206:209], v[32:35]
	v_mfma_f32_16x16x32_bf16 v[24:27], v[158:161], v[206:209], v[24:27]
	v_mfma_f32_16x16x32_bf16 v[60:63], v[154:157], v[186:189], v[60:63]
	v_mfma_f32_16x16x32_bf16 v[56:59], v[162:165], v[186:189], v[56:59]
	v_mfma_f32_16x16x32_bf16 v[52:55], v[154:157], v[194:197], v[52:55]
	v_mfma_f32_16x16x32_bf16 v[48:51], v[162:165], v[194:197], v[48:51]
	v_mfma_f32_16x16x32_bf16 v[44:47], v[154:157], v[202:205], v[44:47]
	v_mfma_f32_16x16x32_bf16 v[40:43], v[162:165], v[202:205], v[40:43]
	v_mfma_f32_16x16x32_bf16 v[32:35], v[154:157], v[210:213], v[32:35]
	v_mfma_f32_16x16x32_bf16 v[24:27], v[162:165], v[210:213], v[24:27]
	s_setprio 0
	s_setprio 1
	v_mfma_f32_16x16x32_bf16 v[36:39], v[166:169], v[182:185], v[36:39]
	v_mfma_f32_16x16x32_bf16 v[28:31], v[174:177], v[182:185], v[28:31]
	v_mfma_f32_16x16x32_bf16 v[20:23], v[166:169], v[190:193], v[20:23]
	v_mfma_f32_16x16x32_bf16 v[16:19], v[174:177], v[190:193], v[16:19]
	v_mfma_f32_16x16x32_bf16 v[12:15], v[166:169], v[198:201], v[12:15]
	v_mfma_f32_16x16x32_bf16 v[8:11], v[174:177], v[198:201], v[8:11]
	v_mfma_f32_16x16x32_bf16 v[4:7], v[166:169], v[206:209], v[4:7]
	v_mfma_f32_16x16x32_bf16 v[0:3], v[174:177], v[206:209], v[0:3]
	v_mfma_f32_16x16x32_bf16 v[36:39], v[170:173], v[186:189], v[36:39]
	v_mfma_f32_16x16x32_bf16 v[28:31], v[178:181], v[186:189], v[28:31]
	v_mfma_f32_16x16x32_bf16 v[20:23], v[170:173], v[194:197], v[20:23]
	v_mfma_f32_16x16x32_bf16 v[16:19], v[178:181], v[194:197], v[16:19]
	s_setprio 2
	s_barrier
	v_mfma_f32_16x16x32_bf16 v[12:15], v[170:173], v[202:205], v[12:15]
	v_mfma_f32_16x16x32_bf16 v[8:11], v[178:181], v[202:205], v[8:11]
	v_mfma_f32_16x16x32_bf16 v[4:7], v[170:173], v[210:213], v[4:7]
	v_mfma_f32_16x16x32_bf16 v[0:3], v[178:181], v[210:213], v[0:3]
	s_setprio 0
	s_add_i32 s28, s28, 2
	s_add_u32 s12, s12, 0x100
	s_addc_u32 s13, s13, 0
	s_cmp_gt_u32 s28, 41
	s_cbranch_scc0 .LBB0_1068
	s_cmpk_lt_u32 s18, 0x100
	s_cbranch_scc0 .LBB0_1071
	s_barrier

; #define PG8_STAGE(bufoff, gbase, voff) do { _Pragma("unroll") for (int _i = 0; _i < 2; ++_i) \
;         __builtin_amdgcn_global_load_lds((const unsigned*)((const char*)(gbase) + (voff)[_i]), (PG8_LAS unsigned*)(lds + (bufoff) + ldsw + _i * 8192), 16, 0, 0); } while (0)
; #define PG8_LDA(dst, b, h) do { _Pragma("unroll") for (int m = 0; m < 4; ++m) _Pragma("unroll") for (int k = 0; k < 2; ++k) dst[m][k] = *(const PG8_LAS bf16x8*)(lds + PG8_SA(b, h) + aoff + m * 2048 + k * 1024); } while (0)
; #define PG8_LDB(dst, b, h) do { _Pragma("unroll") for (int n = 0; n < 2; ++n) _Pragma("unroll") for (int k = 0; k < 2; ++k) dst[n][k] = *(const PG8_LAS bf16x8*)(lds + PG8_SB(b, h) + boff + n * 2048 + k * 1024); } while (0)
; #define PG8_MMA(ai, bj, At, Bt) do { __builtin_amdgcn_s_setprio(1); _Pragma("unroll") for (int m = 0; m < 4; ++m) _Pragma("unroll") for (int n = 0; n < 2; ++n) _Pragma("unroll") for (int k = 0; k < 2; ++k) \
;         acc[ai][bj][m][n] = __builtin_amdgcn_mfma_f32_16x16x32_bf16(Bt[n][k], At[m][k], acc[ai][bj][m][n], 0, 0, 0); __builtin_amdgcn_s_setprio(0); } while (0)
; #define PG8_WAIT_V(n) asm volatile("s_waitcnt vmcnt(" #n ")" ::: "memory")
; #define PG8_WAIT_L(n) asm volatile("s_waitcnt lgkmcnt(" #n ")" ::: "memory")
; #define PG8_BAR __builtin_amdgcn_s_barrier()
; #define PG8_SCHED __builtin_amdgcn_sched_barrier(0)
; template <class Epi, class Sched, bool ALIGN_EPI = false, bool SP2 = false>
; __device__ __forceinline__ void gemm_phase(PG8_LAS unsigned char* lds, const Gemm g, const Sched& S, const Epi& E) {
;     ...
;             PG8_LDB(B0, 0, 0); PG8_LDB(B1, 0, 1); PG8_SCHED; PG8_LDA(At, 0, 0); PG8_STAGE(PG8_SA(1, 1), a1 + hstep, voffA);
;             PG8_WAIT_V(8); PG8_WAIT_L(0); PG8_BAR; PG8_MMA(0, 0, At, B0); PG8_MMA(0, 1, At, B1); PG8_BAR; PG8_SCHED;
;             PG8_LDA(At, 0, 1); PG8_STAGE(PG8_SB(0, 0), b2, voffB); PG8_STAGE(PG8_SB(0, 1), b2 + hstep, voffB); PG8_STAGE(PG8_SA(0, 0), a2, voffA);
;             PG8_WAIT_V(8); PG8_WAIT_L(0); PG8_BAR; PG8_MMA(1, 0, At, B0); PG8_MMA(1, 1, At, B1); PG8_BAR; PG8_SCHED;
.LBB0_1260:
	ds_read_b128 v[146:149], v129
	ds_read_b128 v[158:161], v129 offset:1024
	ds_read_b128 v[162:165], v129 offset:2048
	ds_read_b128 v[166:169], v129 offset:3072
	ds_read_b128 v[170:173], v155
	ds_read_b128 v[174:177], v155 offset:1024
	ds_read_b128 v[178:181], v155 offset:2048
	ds_read_b128 v[182:185], v155 offset:3072
	s_add_u32 s34, s30, 0xfff80080
	s_addc_u32 s35, s31, -1
	s_cmp_eq_u32 s57, 28
	s_cselect_b32 s37, s23, s35
	s_cselect_b32 s36, s53, s34
	s_cselect_b32 s35, s21, s56
	s_cselect_b32 s34, s54, s55
	v_lshl_add_u64 v[150:151], s[30:31], 0, v[138:139]
	s_add_i32 m0, s29, 0xc000
	ds_read_b128 v[186:189], v156
	ds_read_b128 v[190:193], v156 offset:1024
	ds_read_b128 v[194:197], v156 offset:2048
	ds_read_b128 v[198:201], v156 offset:3072
	ds_read_b128 v[202:205], v156 offset:4096
	ds_read_b128 v[206:209], v156 offset:5120
	ds_read_b128 v[210:213], v156 offset:6144
	ds_read_b128 v[214:217], v156 offset:7168
	global_load_lds_dwordx4 v[150:151], off
	v_lshl_add_u64 v[150:151], s[30:31], 0, v[140:141]
	s_add_i32 m0, s29, 0xe000
	s_nop 0
	global_load_lds_dwordx4 v[150:151], off
	s_waitcnt vmcnt(8)
	s_waitcnt lgkmcnt(0)
	s_barrier
	s_setprio 1
	s_waitcnt lgkmcnt(0)
	v_mfma_f32_16x16x32_bf16 v[124:127], v[146:149], v[186:189], v[124:127]
	v_mfma_f32_16x16x32_bf16 v[120:123], v[162:165], v[186:189], v[120:123]
	v_mfma_f32_16x16x32_bf16 v[108:111], v[146:149], v[194:197], v[108:111]
	v_mfma_f32_16x16x32_bf16 v[104:107], v[162:165], v[194:197], v[104:107]
	v_mfma_f32_16x16x32_bf16 v[92:95], v[146:149], v[202:205], v[92:95]
	v_mfma_f32_16x16x32_bf16 v[88:91], v[162:165], v[202:205], v[88:91]
	v_mfma_f32_16x16x32_bf16 v[76:79], v[146:149], v[210:213], v[76:79]
	v_mfma_f32_16x16x32_bf16 v[72:75], v[162:165], v[210:213], v[72:75]
	v_mfma_f32_16x16x32_bf16 v[124:127], v[158:161], v[190:193], v[124:127]
	v_mfma_f32_16x16x32_bf16 v[120:123], v[166:169], v[190:193], v[120:123]
	v_mfma_f32_16x16x32_bf16 v[108:111], v[158:161], v[198:201], v[108:111]
	v_mfma_f32_16x16x32_bf16 v[104:107], v[166:169], v[198:201], v[104:107]
	v_mfma_f32_16x16x32_bf16 v[92:95], v[158:161], v[206:209], v[92:95]
	v_mfma_f32_16x16x32_bf16 v[88:91], v[166:169], v[206:209], v[88:91]
	v_mfma_f32_16x16x32_bf16 v[76:79], v[158:161], v[214:217], v[76:79]
	v_mfma_f32_16x16x32_bf16 v[72:75], v[166:169], v[214:217], v[72:75]
	s_setprio 0
	s_setprio 1
	v_mfma_f32_16x16x32_bf16 v[116:119], v[170:173], v[186:189], v[116:119]
	v_mfma_f32_16x16x32_bf16 v[112:115], v[178:181], v[186:189], v[112:115]
	v_mfma_f32_16x16x32_bf16 v[100:103], v[170:173], v[194:197], v[100:103]
	v_mfma_f32_16x16x32_bf16 v[96:99], v[178:181], v[194:197], v[96:99]
	v_mfma_f32_16x16x32_bf16 v[84:87], v[170:173], v[202:205], v[84:87]
	v_mfma_f32_16x16x32_bf16 v[80:83], v[178:181], v[202:205], v[80:83]
	v_mfma_f32_16x16x32_bf16 v[68:71], v[170:173], v[210:213], v[68:71]
	v_mfma_f32_16x16x32_bf16 v[64:67], v[178:181], v[210:213], v[64:67]
	v_mfma_f32_16x16x32_bf16 v[116:119], v[174:177], v[190:193], v[116:119]
	v_mfma_f32_16x16x32_bf16 v[112:115], v[182:185], v[190:193], v[112:115]
	v_mfma_f32_16x16x32_bf16 v[100:103], v[174:177], v[198:201], v[100:103]
	v_mfma_f32_16x16x32_bf16 v[96:99], v[182:185], v[198:201], v[96:99]
	s_setprio 2
	s_barrier
	v_mfma_f32_16x16x32_bf16 v[84:87], v[174:177], v[206:209], v[84:87]
	v_mfma_f32_16x16x32_bf16 v[80:83], v[182:185], v[206:209], v[80:83]
	v_mfma_f32_16x16x32_bf16 v[68:71], v[174:177], v[214:217], v[68:71]
	v_mfma_f32_16x16x32_bf16 v[64:67], v[182:185], v[214:217], v[64:67]
	s_setprio 0
	s_add_i32 s58, s50, s33
	v_lshl_add_u64 v[150:151], s[34:35], 0, v[134:135]
	s_mov_b32 m0, s58
	ds_read_b128 v[186:189], v156 offset:16384
	ds_read_b128 v[190:193], v156 offset:17408
	ds_read_b128 v[194:197], v156 offset:18432
	ds_read_b128 v[198:201], v156 offset:19456
	ds_read_b128 v[202:205], v156 offset:20480
	ds_read_b128 v[206:209], v156 offset:21504
	ds_read_b128 v[210:213], v156 offset:22528
	ds_read_b128 v[214:217], v156 offset:23552
	global_load_lds_dwordx4 v[150:151], off
	s_add_i32 m0, s58, 0x2000
	s_add_u32 s58, s34, 0x80000
	v_lshl_add_u64 v[218:219], s[34:35], 0, v[130:131]
	s_addc_u32 s59, s35, 0
	s_add_i32 s60, s51, s33
	global_load_lds_dwordx4 v[218:219], off
	v_lshl_add_u64 v[220:221], s[58:59], 0, v[134:135]
	s_mov_b32 m0, s60
	v_lshl_add_u64 v[222:223], s[36:37], 0, v[132:133]
	global_load_lds_dwordx4 v[220:221], off
	v_lshl_add_u64 v[220:221], s[58:59], 0, v[130:131]
	s_add_i32 m0, s60, 0x2000
	s_nop 0
	global_load_lds_dwordx4 v[220:221], off
	v_lshl_add_u64 v[220:221], s[36:37], 0, v[136:137]
	s_mov_b32 m0, s29
	s_nop 0
	global_load_lds_dwordx4 v[220:221], off
	s_mov_b32 m0, s40
	s_nop 0
	global_load_lds_dwordx4 v[222:223], off
	s_waitcnt vmcnt(8)
	s_waitcnt lgkmcnt(0)
	s_barrier
; #define PG8_STAGE(bufoff, gbase, voff) do { _Pragma("unroll") for (int _i = 0; _i < 2; ++_i) \
;         __builtin_amdgcn_global_load_lds((const unsigned*)((const char*)(gbase) + (voff)[_i]), (PG8_LAS unsigned*)(lds + (bufoff) + ldsw + _i * 8192), 16, 0, 0); } while (0)
; #define PG8_LDA(dst, b, h) do { _Pragma("unroll") for (int m = 0; m < 4; ++m) _Pragma("unroll") for (int k = 0; k < 2; ++k) dst[m][k] = *(const PG8_LAS bf16x8*)(lds + PG8_SA(b, h) + aoff + m * 2048 + k * 1024); } while (0)
; #define PG8_LDB(dst, b, h) do { _Pragma("unroll") for (int n = 0; n < 2; ++n) _Pragma("unroll") for (int k = 0; k < 2; ++k) dst[n][k] = *(const PG8_LAS bf16x8*)(lds + PG8_SB(b, h) + boff + n * 2048 + k * 1024); } while (0)
; #define PG8_MMA(ai, bj, At, Bt) do { __builtin_amdgcn_s_setprio(1); _Pragma("unroll") for (int m = 0; m < 4; ++m) _Pragma("unroll") for (int n = 0; n < 2; ++n) _Pragma("unroll") for (int k = 0; k < 2; ++k) \
;         acc[ai][bj][m][n] = __builtin_amdgcn_mfma_f32_16x16x32_bf16(Bt[n][k], At[m][k], acc[ai][bj][m][n], 0, 0, 0); __builtin_amdgcn_s_setprio(0); } while (0)
; #define PG8_WAIT_V(n) asm volatile("s_waitcnt vmcnt(" #n ")" ::: "memory")
; #define PG8_WAIT_L(n) asm volatile("s_waitcnt lgkmcnt(" #n ")" ::: "memory")
; #define PG8_BAR __builtin_amdgcn_s_barrier()
; #define PG8_SCHED __builtin_amdgcn_sched_barrier(0)
; template <class Epi, class Sched, bool ALIGN_EPI = false, bool SP2 = false>
; __device__ __forceinline__ void gemm_phase(PG8_LAS unsigned char* lds, const Gemm g, const Sched& S, const Epi& E) {
;     ...
;             PG8_WAIT_V(8); PG8_WAIT_L(0); PG8_BAR; PG8_MMA(1, 0, At, B0); PG8_MMA(1, 1, At, B1); PG8_BAR; PG8_SCHED;
;             PG8_LDB(B0, 1, 0); PG8_LDB(B1, 1, 1); PG8_SCHED; PG8_LDA(At, 1, 0); PG8_STAGE(PG8_SA(0, 1), a2 + hstep, voffA);
;             PG8_WAIT_V(8); PG8_WAIT_L(0); PG8_BAR; PG8_MMA(0, 0, At, B0); PG8_MMA(0, 1, At, B1); PG8_BAR; PG8_SCHED;
	s_setprio 1
	s_waitcnt lgkmcnt(0)
	v_mfma_f32_16x16x32_bf16 v[60:63], v[146:149], v[186:189], v[60:63]
	v_mfma_f32_16x16x32_bf16 v[56:59], v[162:165], v[186:189], v[56:59]
	v_mfma_f32_16x16x32_bf16 v[44:47], v[146:149], v[194:197], v[44:47]
	v_mfma_f32_16x16x32_bf16 v[40:43], v[162:165], v[194:197], v[40:43]
	v_mfma_f32_16x16x32_bf16 v[28:31], v[146:149], v[202:205], v[28:31]
	v_mfma_f32_16x16x32_bf16 v[24:27], v[162:165], v[202:205], v[24:27]
	v_mfma_f32_16x16x32_bf16 v[12:15], v[146:149], v[210:213], v[12:15]
	v_mfma_f32_16x16x32_bf16 v[8:11], v[162:165], v[210:213], v[8:11]
	v_mfma_f32_16x16x32_bf16 v[60:63], v[158:161], v[190:193], v[60:63]
	v_mfma_f32_16x16x32_bf16 v[56:59], v[166:169], v[190:193], v[56:59]
	v_mfma_f32_16x16x32_bf16 v[44:47], v[158:161], v[198:201], v[44:47]
	v_mfma_f32_16x16x32_bf16 v[40:43], v[166:169], v[198:201], v[40:43]
	v_mfma_f32_16x16x32_bf16 v[28:31], v[158:161], v[206:209], v[28:31]
	v_mfma_f32_16x16x32_bf16 v[24:27], v[166:169], v[206:209], v[24:27]
	v_mfma_f32_16x16x32_bf16 v[12:15], v[158:161], v[214:217], v[12:15]
	v_mfma_f32_16x16x32_bf16 v[8:11], v[166:169], v[214:217], v[8:11]
	s_setprio 0
	s_setprio 1
	v_mfma_f32_16x16x32_bf16 v[52:55], v[170:173], v[186:189], v[52:55]
	v_mfma_f32_16x16x32_bf16 v[48:51], v[178:181], v[186:189], v[48:51]
	v_mfma_f32_16x16x32_bf16 v[36:39], v[170:173], v[194:197], v[36:39]
	v_mfma_f32_16x16x32_bf16 v[32:35], v[178:181], v[194:197], v[32:35]
	v_mfma_f32_16x16x32_bf16 v[20:23], v[170:173], v[202:205], v[20:23]
	v_mfma_f32_16x16x32_bf16 v[16:19], v[178:181], v[202:205], v[16:19]
	v_mfma_f32_16x16x32_bf16 v[4:7], v[170:173], v[210:213], v[4:7]
	v_mfma_f32_16x16x32_bf16 v[0:3], v[178:181], v[210:213], v[0:3]
	v_mfma_f32_16x16x32_bf16 v[52:55], v[174:177], v[190:193], v[52:55]
	v_mfma_f32_16x16x32_bf16 v[48:51], v[182:185], v[190:193], v[48:51]
	v_mfma_f32_16x16x32_bf16 v[36:39], v[174:177], v[198:201], v[36:39]
	v_mfma_f32_16x16x32_bf16 v[32:35], v[182:185], v[198:201], v[32:35]
	s_setprio 2
	s_barrier
	v_mfma_f32_16x16x32_bf16 v[20:23], v[174:177], v[206:209], v[20:23]
	v_mfma_f32_16x16x32_bf16 v[16:19], v[182:185], v[206:209], v[16:19]
	v_mfma_f32_16x16x32_bf16 v[4:7], v[174:177], v[214:217], v[4:7]
	v_mfma_f32_16x16x32_bf16 v[0:3], v[182:185], v[214:217], v[0:3]
	s_setprio 0
	s_add_i32 s58, 0, 0x18000
	v_add_u32_e32 v157, s58, v153
	s_add_i32 s59, 0, 0x1c000
	ds_read_b128 v[146:149], v157
	ds_read_b128 v[158:161], v157 offset:1024
	ds_read_b128 v[162:165], v157 offset:2048
	ds_read_b128 v[166:169], v157 offset:3072
	v_add_u32_e32 v157, s59, v153
	ds_read_b128 v[170:173], v157
	ds_read_b128 v[174:177], v157 offset:1024
	ds_read_b128 v[178:181], v157 offset:2048
	ds_read_b128 v[182:185], v157 offset:3072
	s_add_u32 s36, s36, 0x80000
	s_addc_u32 s37, s37, 0
	s_mov_b32 m0, s41
	v_lshl_add_u64 v[224:225], s[36:37], 0, v[136:137]
	ds_read_b128 v[186:189], v156 offset:32768
	ds_read_b128 v[190:193], v156 offset:33792
	ds_read_b128 v[194:197], v156 offset:34816
	ds_read_b128 v[198:201], v156 offset:35840
	ds_read_b128 v[202:205], v156 offset:36864
	ds_read_b128 v[206:209], v156 offset:37888
	ds_read_b128 v[210:213], v156 offset:38912
	ds_read_b128 v[214:217], v156 offset:39936
	global_load_lds_dwordx4 v[224:225], off
	v_lshl_add_u64 v[224:225], s[36:37], 0, v[132:133]
	s_mov_b32 m0, s42
	s_nop 0
	global_load_lds_dwordx4 v[224:225], off
	s_waitcnt vmcnt(8)
	s_waitcnt lgkmcnt(0)
	s_barrier
	s_setprio 1
	s_waitcnt lgkmcnt(0)
	v_mfma_f32_16x16x32_bf16 v[124:127], v[146:149], v[186:189], v[124:127]
	v_mfma_f32_16x16x32_bf16 v[120:123], v[162:165], v[186:189], v[120:123]
	v_mfma_f32_16x16x32_bf16 v[108:111], v[146:149], v[194:197], v[108:111]
	v_mfma_f32_16x16x32_bf16 v[104:107], v[162:165], v[194:197], v[104:107]
	v_mfma_f32_16x16x32_bf16 v[92:95], v[146:149], v[202:205], v[92:95]
	v_mfma_f32_16x16x32_bf16 v[88:91], v[162:165], v[202:205], v[88:91]
	v_mfma_f32_16x16x32_bf16 v[76:79], v[146:149], v[210:213], v[76:79]
	v_mfma_f32_16x16x32_bf16 v[72:75], v[162:165], v[210:213], v[72:75]
	v_mfma_f32_16x16x32_bf16 v[124:127], v[158:161], v[190:193], v[124:127]
	v_mfma_f32_16x16x32_bf16 v[120:123], v[166:169], v[190:193], v[120:123]
	v_mfma_f32_16x16x32_bf16 v[108:111], v[158:161], v[198:201], v[108:111]
	v_mfma_f32_16x16x32_bf16 v[104:107], v[166:169], v[198:201], v[104:107]
	v_mfma_f32_16x16x32_bf16 v[92:95], v[158:161], v[206:209], v[92:95]
	v_mfma_f32_16x16x32_bf16 v[88:91], v[166:169], v[206:209], v[88:91]
	v_mfma_f32_16x16x32_bf16 v[76:79], v[158:161], v[214:217], v[76:79]
	v_mfma_f32_16x16x32_bf16 v[72:75], v[166:169], v[214:217], v[72:75]
	s_setprio 0
	s_setprio 1
	v_mfma_f32_16x16x32_bf16 v[116:119], v[170:173], v[186:189], v[116:119]
	v_mfma_f32_16x16x32_bf16 v[112:115], v[178:181], v[186:189], v[112:115]
	v_mfma_f32_16x16x32_bf16 v[100:103], v[170:173], v[194:197], v[100:103]
	v_mfma_f32_16x16x32_bf16 v[96:99], v[178:181], v[194:197], v[96:99]
	v_mfma_f32_16x16x32_bf16 v[84:87], v[170:173], v[202:205], v[84:87]
	v_mfma_f32_16x16x32_bf16 v[80:83], v[178:181], v[202:205], v[80:83]
	v_mfma_f32_16x16x32_bf16 v[68:71], v[170:173], v[210:213], v[68:71]
	v_mfma_f32_16x16x32_bf16 v[64:67], v[178:181], v[210:213], v[64:67]
	v_mfma_f32_16x16x32_bf16 v[116:119], v[174:177], v[190:193], v[116:119]
	v_mfma_f32_16x16x32_bf16 v[112:115], v[182:185], v[190:193], v[112:115]
	v_mfma_f32_16x16x32_bf16 v[100:103], v[174:177], v[198:201], v[100:103]
	v_mfma_f32_16x16x32_bf16 v[96:99], v[182:185], v[198:201], v[96:99]
	s_setprio 2
	s_barrier
; #define PG8_STAGE(bufoff, gbase, voff) do { _Pragma("unroll") for (int _i = 0; _i < 2; ++_i) \
;         __builtin_amdgcn_global_load_lds((const unsigned*)((const char*)(gbase) + (voff)[_i]), (PG8_LAS unsigned*)(lds + (bufoff) + ldsw + _i * 8192), 16, 0, 0); } while (0)
; #define PG8_LDA(dst, b, h) do { _Pragma("unroll") for (int m = 0; m < 4; ++m) _Pragma("unroll") for (int k = 0; k < 2; ++k) dst[m][k] = *(const PG8_LAS bf16x8*)(lds + PG8_SA(b, h) + aoff + m * 2048 + k * 1024); } while (0)
; #define PG8_MMA(ai, bj, At, Bt) do { __builtin_amdgcn_s_setprio(1); _Pragma("unroll") for (int m = 0; m < 4; ++m) _Pragma("unroll") for (int n = 0; n < 2; ++n) _Pragma("unroll") for (int k = 0; k < 2; ++k) \
;         acc[ai][bj][m][n] = __builtin_amdgcn_mfma_f32_16x16x32_bf16(Bt[n][k], At[m][k], acc[ai][bj][m][n], 0, 0, 0); __builtin_amdgcn_s_setprio(0); } while (0)
; #define PG8_WAIT_V(n) asm volatile("s_waitcnt vmcnt(" #n ")" ::: "memory")
; #define PG8_WAIT_L(n) asm volatile("s_waitcnt lgkmcnt(" #n ")" ::: "memory")
; #define PG8_BAR __builtin_amdgcn_s_barrier()
; #define PG8_SCHED __builtin_amdgcn_sched_barrier(0)
; template <class Epi, class Sched, bool ALIGN_EPI = false, bool SP2 = false>
; __device__ __forceinline__ void gemm_phase(PG8_LAS unsigned char* lds, const Gemm g, const Sched& S, const Epi& E) {
;     ...
;             PG8_WAIT_V(8); PG8_WAIT_L(0); PG8_BAR; PG8_MMA(0, 0, At, B0); PG8_MMA(0, 1, At, B1); PG8_BAR; PG8_SCHED;
;             PG8_LDA(At, 1, 1); PG8_STAGE(PG8_SB(1, 0), b3, voffB); PG8_STAGE(PG8_SB(1, 1), b3 + hstep, voffB); PG8_STAGE(PG8_SA(1, 0), a3, voffA);
;             PG8_WAIT_V(8); PG8_WAIT_L(0); PG8_BAR; PG8_MMA(1, 0, At, B0); PG8_MMA(1, 1, At, B1); PG8_BAR; PG8_SCHED;
	v_mfma_f32_16x16x32_bf16 v[84:87], v[174:177], v[206:209], v[84:87]
	v_mfma_f32_16x16x32_bf16 v[80:83], v[182:185], v[206:209], v[80:83]
	v_mfma_f32_16x16x32_bf16 v[68:71], v[174:177], v[214:217], v[68:71]
	v_mfma_f32_16x16x32_bf16 v[64:67], v[182:185], v[214:217], v[64:67]
	s_setprio 0
	s_add_i32 s36, s58, s33
	v_lshl_add_u64 v[150:151], v[150:151], 0, s[10:11]
	s_mov_b32 m0, s36
	ds_read_b128 v[186:189], v156 offset:49152
	ds_read_b128 v[190:193], v156 offset:50176
	ds_read_b128 v[194:197], v156 offset:51200
	ds_read_b128 v[198:201], v156 offset:52224
	ds_read_b128 v[202:205], v156 offset:53248
	ds_read_b128 v[206:209], v156 offset:54272
	ds_read_b128 v[210:213], v156 offset:55296
	ds_read_b128 v[214:217], v156 offset:56320
	global_load_lds_dwordx4 v[150:151], off
	s_add_i32 m0, s36, 0x2000
	s_add_u32 s34, s34, 0x80080
	v_lshl_add_u64 v[150:151], v[218:219], 0, s[10:11]
	s_addc_u32 s35, s35, 0
	s_add_i32 s36, s59, s33
	global_load_lds_dwordx4 v[150:151], off
	v_lshl_add_u64 v[150:151], s[34:35], 0, v[134:135]
	s_mov_b32 m0, s36
	s_nop 0
	global_load_lds_dwordx4 v[150:151], off
	v_lshl_add_u64 v[150:151], s[34:35], 0, v[130:131]
	s_add_i32 m0, s36, 0x2000
	s_nop 0
	global_load_lds_dwordx4 v[150:151], off
	v_lshl_add_u64 v[150:151], v[220:221], 0, s[10:11]
	s_mov_b32 m0, s44
	s_nop 0
	global_load_lds_dwordx4 v[150:151], off
	v_lshl_add_u64 v[150:151], v[222:223], 0, s[10:11]
	s_mov_b32 m0, s45
	s_nop 0
	global_load_lds_dwordx4 v[150:151], off
	s_waitcnt vmcnt(8)
	s_waitcnt lgkmcnt(0)
	s_barrier
	s_setprio 1
	s_waitcnt lgkmcnt(0)
	v_mfma_f32_16x16x32_bf16 v[60:63], v[146:149], v[186:189], v[60:63]
	v_mfma_f32_16x16x32_bf16 v[56:59], v[162:165], v[186:189], v[56:59]
	v_mfma_f32_16x16x32_bf16 v[44:47], v[146:149], v[194:197], v[44:47]
	v_mfma_f32_16x16x32_bf16 v[40:43], v[162:165], v[194:197], v[40:43]
	v_mfma_f32_16x16x32_bf16 v[28:31], v[146:149], v[202:205], v[28:31]
	v_mfma_f32_16x16x32_bf16 v[24:27], v[162:165], v[202:205], v[24:27]
	v_mfma_f32_16x16x32_bf16 v[12:15], v[146:149], v[210:213], v[12:15]
	v_mfma_f32_16x16x32_bf16 v[8:11], v[162:165], v[210:213], v[8:11]
	v_mfma_f32_16x16x32_bf16 v[60:63], v[158:161], v[190:193], v[60:63]
	v_mfma_f32_16x16x32_bf16 v[56:59], v[166:169], v[190:193], v[56:59]
	v_mfma_f32_16x16x32_bf16 v[44:47], v[158:161], v[198:201], v[44:47]
	v_mfma_f32_16x16x32_bf16 v[40:43], v[166:169], v[198:201], v[40:43]
	v_mfma_f32_16x16x32_bf16 v[28:31], v[158:161], v[206:209], v[28:31]
	v_mfma_f32_16x16x32_bf16 v[24:27], v[166:169], v[206:209], v[24:27]
	v_mfma_f32_16x16x32_bf16 v[12:15], v[158:161], v[214:217], v[12:15]
	v_mfma_f32_16x16x32_bf16 v[8:11], v[166:169], v[214:217], v[8:11]
	s_setprio 0
	s_setprio 1
	v_mfma_f32_16x16x32_bf16 v[52:55], v[170:173], v[186:189], v[52:55]
	v_mfma_f32_16x16x32_bf16 v[48:51], v[178:181], v[186:189], v[48:51]
	v_mfma_f32_16x16x32_bf16 v[36:39], v[170:173], v[194:197], v[36:39]
	v_mfma_f32_16x16x32_bf16 v[32:35], v[178:181], v[194:197], v[32:35]
	v_mfma_f32_16x16x32_bf16 v[20:23], v[170:173], v[202:205], v[20:23]
	v_mfma_f32_16x16x32_bf16 v[16:19], v[178:181], v[202:205], v[16:19]
	v_mfma_f32_16x16x32_bf16 v[4:7], v[170:173], v[210:213], v[4:7]
	v_mfma_f32_16x16x32_bf16 v[0:3], v[178:181], v[210:213], v[0:3]
	v_mfma_f32_16x16x32_bf16 v[52:55], v[174:177], v[190:193], v[52:55]
	v_mfma_f32_16x16x32_bf16 v[48:51], v[182:185], v[190:193], v[48:51]
	v_mfma_f32_16x16x32_bf16 v[36:39], v[174:177], v[198:201], v[36:39]
	v_mfma_f32_16x16x32_bf16 v[32:35], v[182:185], v[198:201], v[32:35]
	s_setprio 2
	s_barrier
	v_mfma_f32_16x16x32_bf16 v[20:23], v[174:177], v[206:209], v[20:23]
	v_mfma_f32_16x16x32_bf16 v[16:19], v[182:185], v[206:209], v[16:19]
	v_mfma_f32_16x16x32_bf16 v[4:7], v[174:177], v[214:217], v[4:7]
	v_mfma_f32_16x16x32_bf16 v[0:3], v[182:185], v[214:217], v[0:3]
	s_setprio 0
	s_add_i32 s57, s57, 2
	s_add_u32 s30, s30, 0x100
	s_addc_u32 s31, s31, 0
	s_add_u32 s55, s55, 0x100
	s_addc_u32 s56, s56, 0
	s_cmp_gt_u32 s57, 29
	s_cbranch_scc0 .LBB0_1260
	s_and_b64 vcc, exec, s[12:13]
	s_cbranch_vccz .LBB0_1263
	s_barrier
